# priority: dropped the back-to-back mid-cluster s_setprio 0/1 toggle in the GEMM K-loops (priority stays raised across each 16-MFMA cluster)
# baseline (speedup 1.0000x reference)
; #define PG8_STAGE(bufoff, gbase, voff) do { _Pragma("unroll") for (int _i = 0; _i < 2; ++_i) \
;         __builtin_amdgcn_global_load_lds((const unsigned*)((const char*)(gbase) + (voff)[_i]), (PG8_LAS unsigned*)(lds + (bufoff) + ldsw + _i * 8192), 16, 0, 0); } while (0)
; #define PG8_LDA(dst, b, h) do { _Pragma("unroll") for (int m = 0; m < 4; ++m) _Pragma("unroll") for (int k = 0; k < 2; ++k) dst[m][k] = *(const PG8_LAS bf16x8*)(lds + PG8_SA(b, h) + aoff + m * 2048 + k * 1024); } while (0)
; #define PG8_LDB(dst, b, h) do { _Pragma("unroll") for (int n = 0; n < 2; ++n) _Pragma("unroll") for (int k = 0; k < 2; ++k) dst[n][k] = *(const PG8_LAS bf16x8*)(lds + PG8_SB(b, h) + boff + n * 2048 + k * 1024); } while (0)
; #define PG8_MMA(ai, bj, At, Bt) do { __builtin_amdgcn_s_setprio(1); _Pragma("unroll") for (int m = 0; m < 4; ++m) _Pragma("unroll") for (int n = 0; n < 2; ++n) _Pragma("unroll") for (int k = 0; k < 2; ++k) \
;         acc[ai][bj][m][n] = __builtin_amdgcn_mfma_f32_16x16x32_bf16(Bt[n][k], At[m][k], acc[ai][bj][m][n], 0, 0, 0); __builtin_amdgcn_s_setprio(0); } while (0)
; #define PG8_WAIT_V(n) asm volatile("s_waitcnt vmcnt(" #n ")" ::: "memory")
; #define PG8_WAIT_L(n) asm volatile("s_waitcnt lgkmcnt(" #n ")" ::: "memory")
; #define PG8_BAR __builtin_amdgcn_s_barrier()
; #define PG8_SCHED __builtin_amdgcn_sched_barrier(0)
; template <class Epi, class Sched, bool ALIGN_EPI, bool SP2, int KC>
; __device__ __forceinline__ void gemm_phase(PG8_LAS unsigned char* lds, const Gemm g, const Sched& S, const Epi& E, const int tid) {
;     ...
;             PG8_LDB(B0, 0, 0); PG8_LDB(B1, 0, 1); PG8_SCHED; PG8_LDA(At, 0, 0); PG8_STAGE(PG8_SA(1, 1), a1 + hstep, voffA);
;             PG8_WAIT_V(8); PG8_WAIT_L(0); PG8_BAR; PG8_MMA(0, 0, At, B0); PG8_MMA(0, 1, At, B1); PG8_BAR; PG8_SCHED;
;             PG8_LDA(At, 0, 1); PG8_STAGE(PG8_SB(0, 0), b2, voffB); PG8_STAGE(PG8_SB(0, 1), b2 + hstep, voffB); PG8_STAGE(PG8_SA(0, 0), a2, voffA);
;             PG8_WAIT_V(8); PG8_WAIT_L(0); PG8_BAR; PG8_MMA(1, 0, At, B0); PG8_MMA(1, 1, At, B1); PG8_BAR; PG8_SCHED;
.LBB0_44:
	s_add_u32 s24, s22, 0xfffc0080
	s_addc_u32 s25, s23, -1
	s_add_i32 s43, 0, 0x10000
	s_cmp_eq_u32 s42, 12
	s_cselect_b32 s27, s17, s25
	s_cselect_b32 s26, s38, s24
	v_add_u32_e32 v138, s43, v145
	s_cselect_b32 s25, s15, s41
	s_cselect_b32 s24, s39, s40
	s_add_i32 s46, 0, 0x14000
	ds_read_b128 v[148:151], v138
	ds_read_b128 v[152:155], v138 offset:1024
	ds_read_b128 v[156:159], v138 offset:2048
	ds_read_b128 v[160:163], v138 offset:3072
	v_add_u32_e32 v138, s46, v145
	ds_read_b128 v[174:177], v138
	ds_read_b128 v[178:181], v138 offset:1024
	ds_read_b128 v[182:185], v138 offset:2048
	ds_read_b128 v[186:189], v138 offset:3072
	v_lshl_add_u64 v[138:139], s[22:23], 0, v[134:135]
	s_add_i32 m0, s29, 0xc000
	ds_read_b128 v[190:193], v147
	ds_read_b128 v[194:197], v147 offset:1024
	ds_read_b128 v[198:201], v147 offset:2048
	ds_read_b128 v[202:205], v147 offset:3072
	ds_read_b128 v[206:209], v147 offset:4096
	ds_read_b128 v[210:213], v147 offset:5120
	ds_read_b128 v[214:217], v147 offset:6144
	ds_read_b128 v[218:221], v147 offset:7168
	global_load_lds_dwordx4 v[138:139], off
	v_lshl_add_u64 v[138:139], s[22:23], 0, v[136:137]
	s_add_i32 m0, s29, 0xe000
	s_nop 0
	global_load_lds_dwordx4 v[138:139], off
	s_waitcnt vmcnt(8)
	s_waitcnt lgkmcnt(0)
	s_barrier
	s_setprio 1
	s_waitcnt lgkmcnt(0)
	v_mfma_f32_16x16x32_bf16 v[124:127], v[148:151], v[190:193], v[124:127]
	v_mfma_f32_16x16x32_bf16 v[120:123], v[156:159], v[190:193], v[120:123]
	v_mfma_f32_16x16x32_bf16 v[116:119], v[148:151], v[198:201], v[116:119]
	v_mfma_f32_16x16x32_bf16 v[108:111], v[156:159], v[198:201], v[108:111]
	v_mfma_f32_16x16x32_bf16 v[100:103], v[148:151], v[206:209], v[100:103]
	v_mfma_f32_16x16x32_bf16 v[92:95], v[156:159], v[206:209], v[92:95]
	v_mfma_f32_16x16x32_bf16 v[80:83], v[148:151], v[214:217], v[80:83]
	v_mfma_f32_16x16x32_bf16 v[72:75], v[156:159], v[214:217], v[72:75]
	v_mfma_f32_16x16x32_bf16 v[124:127], v[152:155], v[194:197], v[124:127]
	v_mfma_f32_16x16x32_bf16 v[120:123], v[160:163], v[194:197], v[120:123]
	v_mfma_f32_16x16x32_bf16 v[116:119], v[152:155], v[202:205], v[116:119]
	v_mfma_f32_16x16x32_bf16 v[108:111], v[160:163], v[202:205], v[108:111]
	v_mfma_f32_16x16x32_bf16 v[100:103], v[152:155], v[210:213], v[100:103]
	v_mfma_f32_16x16x32_bf16 v[92:95], v[160:163], v[210:213], v[92:95]
	v_mfma_f32_16x16x32_bf16 v[80:83], v[152:155], v[218:221], v[80:83]
	v_mfma_f32_16x16x32_bf16 v[72:75], v[160:163], v[218:221], v[72:75]
	v_mfma_f32_16x16x32_bf16 v[112:115], v[174:177], v[190:193], v[112:115]
	v_mfma_f32_16x16x32_bf16 v[104:107], v[182:185], v[190:193], v[104:107]
	v_mfma_f32_16x16x32_bf16 v[96:99], v[174:177], v[198:201], v[96:99]
	v_mfma_f32_16x16x32_bf16 v[88:91], v[182:185], v[198:201], v[88:91]
	v_mfma_f32_16x16x32_bf16 v[84:87], v[174:177], v[206:209], v[84:87]
	v_mfma_f32_16x16x32_bf16 v[76:79], v[182:185], v[206:209], v[76:79]
	v_mfma_f32_16x16x32_bf16 v[68:71], v[174:177], v[214:217], v[68:71]
	v_mfma_f32_16x16x32_bf16 v[64:67], v[182:185], v[214:217], v[64:67]
	v_mfma_f32_16x16x32_bf16 v[112:115], v[178:181], v[194:197], v[112:115]
	v_mfma_f32_16x16x32_bf16 v[104:107], v[186:189], v[194:197], v[104:107]
	v_mfma_f32_16x16x32_bf16 v[96:99], v[178:181], v[202:205], v[96:99]
	v_mfma_f32_16x16x32_bf16 v[88:91], v[186:189], v[202:205], v[88:91]
	v_mfma_f32_16x16x32_bf16 v[84:87], v[178:181], v[210:213], v[84:87]
	v_mfma_f32_16x16x32_bf16 v[76:79], v[186:189], v[210:213], v[76:79]
	v_mfma_f32_16x16x32_bf16 v[68:71], v[178:181], v[218:221], v[68:71]
	v_mfma_f32_16x16x32_bf16 v[64:67], v[186:189], v[218:221], v[64:67]
	s_setprio 0
	s_barrier
	s_add_i32 s43, s43, s28
	v_lshl_add_u64 v[138:139], s[24:25], 0, v[164:165]
	s_mov_b32 m0, s43
	ds_read_b128 v[190:193], v147 offset:16384
	ds_read_b128 v[194:197], v147 offset:17408
	ds_read_b128 v[198:201], v147 offset:18432
	ds_read_b128 v[202:205], v147 offset:19456
	ds_read_b128 v[206:209], v147 offset:20480
	ds_read_b128 v[210:213], v147 offset:21504
	ds_read_b128 v[214:217], v147 offset:22528
	ds_read_b128 v[218:221], v147 offset:23552
	global_load_lds_dwordx4 v[138:139], off
	s_add_i32 m0, s43, 0x2000
	s_add_u32 s44, s24, 0x40000
	v_lshl_add_u64 v[222:223], s[24:25], 0, v[128:129]
	s_addc_u32 s45, s25, 0
	s_add_i32 s43, s46, s28
	global_load_lds_dwordx4 v[222:223], off
	v_lshl_add_u64 v[234:235], s[44:45], 0, v[164:165]
	s_mov_b32 m0, s43
	v_lshl_add_u64 v[236:237], s[26:27], 0, v[130:131]
	global_load_lds_dwordx4 v[234:235], off
	v_lshl_add_u64 v[234:235], s[44:45], 0, v[128:129]
	s_add_i32 m0, s43, 0x2000
	s_nop 0
	global_load_lds_dwordx4 v[234:235], off
	v_lshl_add_u64 v[234:235], s[26:27], 0, v[132:133]
	s_mov_b32 m0, s29
	s_nop 0
	global_load_lds_dwordx4 v[234:235], off
	s_mov_b32 m0, s30
	s_nop 0
	global_load_lds_dwordx4 v[236:237], off
	s_waitcnt vmcnt(8)
	s_waitcnt lgkmcnt(0)
	s_barrier
; #define PG8_STAGE(bufoff, gbase, voff) do { _Pragma("unroll") for (int _i = 0; _i < 2; ++_i) \
;         __builtin_amdgcn_global_load_lds((const unsigned*)((const char*)(gbase) + (voff)[_i]), (PG8_LAS unsigned*)(lds + (bufoff) + ldsw + _i * 8192), 16, 0, 0); } while (0)
; #define PG8_LDA(dst, b, h) do { _Pragma("unroll") for (int m = 0; m < 4; ++m) _Pragma("unroll") for (int k = 0; k < 2; ++k) dst[m][k] = *(const PG8_LAS bf16x8*)(lds + PG8_SA(b, h) + aoff + m * 2048 + k * 1024); } while (0)
; #define PG8_LDB(dst, b, h) do { _Pragma("unroll") for (int n = 0; n < 2; ++n) _Pragma("unroll") for (int k = 0; k < 2; ++k) dst[n][k] = *(const PG8_LAS bf16x8*)(lds + PG8_SB(b, h) + boff + n * 2048 + k * 1024); } while (0)
; #define PG8_MMA(ai, bj, At, Bt) do { __builtin_amdgcn_s_setprio(1); _Pragma("unroll") for (int m = 0; m < 4; ++m) _Pragma("unroll") for (int n = 0; n < 2; ++n) _Pragma("unroll") for (int k = 0; k < 2; ++k) \
;         acc[ai][bj][m][n] = __builtin_amdgcn_mfma_f32_16x16x32_bf16(Bt[n][k], At[m][k], acc[ai][bj][m][n], 0, 0, 0); __builtin_amdgcn_s_setprio(0); } while (0)
; #define PG8_WAIT_V(n) asm volatile("s_waitcnt vmcnt(" #n ")" ::: "memory")
; #define PG8_WAIT_L(n) asm volatile("s_waitcnt lgkmcnt(" #n ")" ::: "memory")
; #define PG8_BAR __builtin_amdgcn_s_barrier()
; #define PG8_SCHED __builtin_amdgcn_sched_barrier(0)
; template <class Epi, class Sched, bool ALIGN_EPI, bool SP2, int KC>
; __device__ __forceinline__ void gemm_phase(PG8_LAS unsigned char* lds, const Gemm g, const Sched& S, const Epi& E, const int tid) {
;     ...
;             PG8_WAIT_V(8); PG8_WAIT_L(0); PG8_BAR; PG8_MMA(1, 0, At, B0); PG8_MMA(1, 1, At, B1); PG8_BAR; PG8_SCHED;
;             PG8_LDB(B0, 1, 0); PG8_LDB(B1, 1, 1); PG8_SCHED; PG8_LDA(At, 1, 0); PG8_STAGE(PG8_SA(0, 1), a2 + hstep, voffA);
;             PG8_WAIT_V(8); PG8_WAIT_L(0); PG8_BAR; PG8_MMA(0, 0, At, B0); PG8_MMA(0, 1, At, B1); PG8_BAR; PG8_SCHED;
	s_setprio 1
	s_waitcnt lgkmcnt(0)
	v_mfma_f32_16x16x32_bf16 v[60:63], v[148:151], v[190:193], v[60:63]
	v_mfma_f32_16x16x32_bf16 v[56:59], v[156:159], v[190:193], v[56:59]
	v_mfma_f32_16x16x32_bf16 v[52:55], v[148:151], v[198:201], v[52:55]
	v_mfma_f32_16x16x32_bf16 v[44:47], v[156:159], v[198:201], v[44:47]
	v_mfma_f32_16x16x32_bf16 v[36:39], v[148:151], v[206:209], v[36:39]
	v_mfma_f32_16x16x32_bf16 v[28:31], v[156:159], v[206:209], v[28:31]
	v_mfma_f32_16x16x32_bf16 v[20:23], v[148:151], v[214:217], v[20:23]
	v_mfma_f32_16x16x32_bf16 v[12:15], v[156:159], v[214:217], v[12:15]
	v_mfma_f32_16x16x32_bf16 v[60:63], v[152:155], v[194:197], v[60:63]
	v_mfma_f32_16x16x32_bf16 v[56:59], v[160:163], v[194:197], v[56:59]
	v_mfma_f32_16x16x32_bf16 v[52:55], v[152:155], v[202:205], v[52:55]
	v_mfma_f32_16x16x32_bf16 v[44:47], v[160:163], v[202:205], v[44:47]
	v_mfma_f32_16x16x32_bf16 v[36:39], v[152:155], v[210:213], v[36:39]
	v_mfma_f32_16x16x32_bf16 v[28:31], v[160:163], v[210:213], v[28:31]
	v_mfma_f32_16x16x32_bf16 v[20:23], v[152:155], v[218:221], v[20:23]
	v_mfma_f32_16x16x32_bf16 v[12:15], v[160:163], v[218:221], v[12:15]
	v_mfma_f32_16x16x32_bf16 v[48:51], v[174:177], v[190:193], v[48:51]
	v_mfma_f32_16x16x32_bf16 v[40:43], v[182:185], v[190:193], v[40:43]
	v_mfma_f32_16x16x32_bf16 v[32:35], v[174:177], v[198:201], v[32:35]
	v_mfma_f32_16x16x32_bf16 v[24:27], v[182:185], v[198:201], v[24:27]
	v_mfma_f32_16x16x32_bf16 v[16:19], v[174:177], v[206:209], v[16:19]
	v_mfma_f32_16x16x32_bf16 v[8:11], v[182:185], v[206:209], v[8:11]
	v_mfma_f32_16x16x32_bf16 v[4:7], v[174:177], v[214:217], v[4:7]
	v_mfma_f32_16x16x32_bf16 v[0:3], v[182:185], v[214:217], v[0:3]
	v_mfma_f32_16x16x32_bf16 v[48:51], v[178:181], v[194:197], v[48:51]
	v_mfma_f32_16x16x32_bf16 v[40:43], v[186:189], v[194:197], v[40:43]
	v_mfma_f32_16x16x32_bf16 v[32:35], v[178:181], v[202:205], v[32:35]
	v_mfma_f32_16x16x32_bf16 v[24:27], v[186:189], v[202:205], v[24:27]
	v_mfma_f32_16x16x32_bf16 v[16:19], v[178:181], v[210:213], v[16:19]
	v_mfma_f32_16x16x32_bf16 v[8:11], v[186:189], v[210:213], v[8:11]
	v_mfma_f32_16x16x32_bf16 v[4:7], v[178:181], v[218:221], v[4:7]
	v_mfma_f32_16x16x32_bf16 v[0:3], v[186:189], v[218:221], v[0:3]
	s_setprio 0
	s_barrier
	s_add_i32 s43, 0, 0x18000
	s_add_i32 s44, 0, 0x1c000
	v_add_u32_e32 v160, s43, v145
	v_add_u32_e32 v171, s44, v145
	ds_read_b128 v[148:151], v160
	ds_read_b128 v[152:155], v160 offset:1024
	ds_read_b128 v[156:159], v160 offset:2048
	ds_read_b128 v[160:163], v160 offset:3072
	ds_read_b128 v[174:177], v171
	ds_read_b128 v[178:181], v171 offset:1024
	ds_read_b128 v[182:185], v171 offset:2048
	ds_read_b128 v[186:189], v171 offset:3072
	s_add_u32 s26, s26, 0x40000
	s_addc_u32 s27, s27, 0
	s_mov_b32 m0, s31
	v_lshl_add_u64 v[238:239], s[26:27], 0, v[132:133]
	ds_read_b128 v[190:193], v147 offset:32768
	ds_read_b128 v[194:197], v147 offset:33792
	ds_read_b128 v[198:201], v147 offset:34816
	ds_read_b128 v[202:205], v147 offset:35840
	ds_read_b128 v[206:209], v147 offset:36864
	ds_read_b128 v[210:213], v147 offset:37888
	ds_read_b128 v[214:217], v147 offset:38912
	ds_read_b128 v[218:221], v147 offset:39936
	global_load_lds_dwordx4 v[238:239], off
	v_lshl_add_u64 v[238:239], s[26:27], 0, v[130:131]
	s_mov_b32 m0, s34
	s_nop 0
	global_load_lds_dwordx4 v[238:239], off
	s_waitcnt vmcnt(8)
	s_waitcnt lgkmcnt(0)
	s_barrier
	s_setprio 1
	s_waitcnt lgkmcnt(0)
	v_mfma_f32_16x16x32_bf16 v[124:127], v[148:151], v[190:193], v[124:127]
	v_mfma_f32_16x16x32_bf16 v[120:123], v[156:159], v[190:193], v[120:123]
	v_mfma_f32_16x16x32_bf16 v[116:119], v[148:151], v[198:201], v[116:119]
	v_mfma_f32_16x16x32_bf16 v[108:111], v[156:159], v[198:201], v[108:111]
	v_mfma_f32_16x16x32_bf16 v[100:103], v[148:151], v[206:209], v[100:103]
	v_mfma_f32_16x16x32_bf16 v[92:95], v[156:159], v[206:209], v[92:95]
	v_mfma_f32_16x16x32_bf16 v[80:83], v[148:151], v[214:217], v[80:83]
	v_mfma_f32_16x16x32_bf16 v[72:75], v[156:159], v[214:217], v[72:75]
	v_mfma_f32_16x16x32_bf16 v[124:127], v[152:155], v[194:197], v[124:127]
	v_mfma_f32_16x16x32_bf16 v[120:123], v[160:163], v[194:197], v[120:123]
	v_mfma_f32_16x16x32_bf16 v[116:119], v[152:155], v[202:205], v[116:119]
	v_mfma_f32_16x16x32_bf16 v[108:111], v[160:163], v[202:205], v[108:111]
	v_mfma_f32_16x16x32_bf16 v[100:103], v[152:155], v[210:213], v[100:103]
	v_mfma_f32_16x16x32_bf16 v[92:95], v[160:163], v[210:213], v[92:95]
	v_mfma_f32_16x16x32_bf16 v[80:83], v[152:155], v[218:221], v[80:83]
	v_mfma_f32_16x16x32_bf16 v[72:75], v[160:163], v[218:221], v[72:75]
	v_mfma_f32_16x16x32_bf16 v[112:115], v[174:177], v[190:193], v[112:115]
	v_mfma_f32_16x16x32_bf16 v[104:107], v[182:185], v[190:193], v[104:107]
	v_mfma_f32_16x16x32_bf16 v[96:99], v[174:177], v[198:201], v[96:99]
	v_mfma_f32_16x16x32_bf16 v[88:91], v[182:185], v[198:201], v[88:91]
	v_mfma_f32_16x16x32_bf16 v[84:87], v[174:177], v[206:209], v[84:87]
	v_mfma_f32_16x16x32_bf16 v[76:79], v[182:185], v[206:209], v[76:79]
	v_mfma_f32_16x16x32_bf16 v[68:71], v[174:177], v[214:217], v[68:71]
	v_mfma_f32_16x16x32_bf16 v[64:67], v[182:185], v[214:217], v[64:67]
	v_mfma_f32_16x16x32_bf16 v[112:115], v[178:181], v[194:197], v[112:115]
	v_mfma_f32_16x16x32_bf16 v[104:107], v[186:189], v[194:197], v[104:107]
	v_mfma_f32_16x16x32_bf16 v[96:99], v[178:181], v[202:205], v[96:99]
	v_mfma_f32_16x16x32_bf16 v[88:91], v[186:189], v[202:205], v[88:91]
	v_mfma_f32_16x16x32_bf16 v[84:87], v[178:181], v[210:213], v[84:87]
	v_mfma_f32_16x16x32_bf16 v[76:79], v[186:189], v[210:213], v[76:79]
	v_mfma_f32_16x16x32_bf16 v[68:71], v[178:181], v[218:221], v[68:71]
	v_mfma_f32_16x16x32_bf16 v[64:67], v[186:189], v[218:221], v[64:67]
	s_setprio 0
	s_barrier
; #define PG8_STAGE(bufoff, gbase, voff) do { _Pragma("unroll") for (int _i = 0; _i < 2; ++_i) \
;         __builtin_amdgcn_global_load_lds((const unsigned*)((const char*)(gbase) + (voff)[_i]), (PG8_LAS unsigned*)(lds + (bufoff) + ldsw + _i * 8192), 16, 0, 0); } while (0)
; #define PG8_LDA(dst, b, h) do { _Pragma("unroll") for (int m = 0; m < 4; ++m) _Pragma("unroll") for (int k = 0; k < 2; ++k) dst[m][k] = *(const PG8_LAS bf16x8*)(lds + PG8_SA(b, h) + aoff + m * 2048 + k * 1024); } while (0)
; #define PG8_MMA(ai, bj, At, Bt) do { __builtin_amdgcn_s_setprio(1); _Pragma("unroll") for (int m = 0; m < 4; ++m) _Pragma("unroll") for (int n = 0; n < 2; ++n) _Pragma("unroll") for (int k = 0; k < 2; ++k) \
;         acc[ai][bj][m][n] = __builtin_amdgcn_mfma_f32_16x16x32_bf16(Bt[n][k], At[m][k], acc[ai][bj][m][n], 0, 0, 0); __builtin_amdgcn_s_setprio(0); } while (0)
; #define PG8_WAIT_V(n) asm volatile("s_waitcnt vmcnt(" #n ")" ::: "memory")
; #define PG8_WAIT_L(n) asm volatile("s_waitcnt lgkmcnt(" #n ")" ::: "memory")
; #define PG8_BAR __builtin_amdgcn_s_barrier()
; #define PG8_SCHED __builtin_amdgcn_sched_barrier(0)
; template <class Epi, class Sched, bool ALIGN_EPI, bool SP2, int KC>
; __device__ __forceinline__ void gemm_phase(PG8_LAS unsigned char* lds, const Gemm g, const Sched& S, const Epi& E, const int tid) {
;     ...
;             PG8_LDA(At, 1, 1); PG8_STAGE(PG8_SB(1, 0), b3, voffB); PG8_STAGE(PG8_SB(1, 1), b3 + hstep, voffB); PG8_STAGE(PG8_SA(1, 0), a3, voffA);
;             PG8_WAIT_V(8); PG8_WAIT_L(0); PG8_BAR; PG8_MMA(1, 0, At, B0); PG8_MMA(1, 1, At, B1); PG8_BAR; PG8_SCHED;
	s_add_i32 s26, s43, s28
	v_lshl_add_u64 v[138:139], v[138:139], 0, s[86:87]
	s_mov_b32 m0, s26
	ds_read_b128 v[190:193], v147 offset:49152
	ds_read_b128 v[194:197], v147 offset:50176
	ds_read_b128 v[198:201], v147 offset:51200
	ds_read_b128 v[202:205], v147 offset:52224
	ds_read_b128 v[206:209], v147 offset:53248
	ds_read_b128 v[210:213], v147 offset:54272
	ds_read_b128 v[214:217], v147 offset:55296
	ds_read_b128 v[218:221], v147 offset:56320
	global_load_lds_dwordx4 v[138:139], off
	s_add_i32 m0, s26, 0x2000
	s_add_u32 s24, s24, 0x40080
	v_lshl_add_u64 v[138:139], v[222:223], 0, s[86:87]
	s_addc_u32 s25, s25, 0
	s_add_i32 s26, s44, s28
	global_load_lds_dwordx4 v[138:139], off
	v_lshl_add_u64 v[138:139], s[24:25], 0, v[164:165]
	s_mov_b32 m0, s26
	s_nop 0
	global_load_lds_dwordx4 v[138:139], off
	v_lshl_add_u64 v[138:139], s[24:25], 0, v[128:129]
	s_add_i32 m0, s26, 0x2000
	s_nop 0
	global_load_lds_dwordx4 v[138:139], off
	v_lshl_add_u64 v[138:139], v[234:235], 0, s[86:87]
	s_mov_b32 m0, s35
	s_nop 0
	global_load_lds_dwordx4 v[138:139], off
	v_lshl_add_u64 v[138:139], v[236:237], 0, s[86:87]
	s_mov_b32 m0, s36
	s_nop 0
	global_load_lds_dwordx4 v[138:139], off
	s_waitcnt vmcnt(8)
	s_waitcnt lgkmcnt(0)
	s_barrier
	s_setprio 1
	s_waitcnt lgkmcnt(0)
	v_mfma_f32_16x16x32_bf16 v[60:63], v[148:151], v[190:193], v[60:63]
	v_mfma_f32_16x16x32_bf16 v[56:59], v[156:159], v[190:193], v[56:59]
	v_mfma_f32_16x16x32_bf16 v[52:55], v[148:151], v[198:201], v[52:55]
	v_mfma_f32_16x16x32_bf16 v[44:47], v[156:159], v[198:201], v[44:47]
	v_mfma_f32_16x16x32_bf16 v[36:39], v[148:151], v[206:209], v[36:39]
	v_mfma_f32_16x16x32_bf16 v[28:31], v[156:159], v[206:209], v[28:31]
	v_mfma_f32_16x16x32_bf16 v[20:23], v[148:151], v[214:217], v[20:23]
	v_mfma_f32_16x16x32_bf16 v[12:15], v[156:159], v[214:217], v[12:15]
	v_mfma_f32_16x16x32_bf16 v[60:63], v[152:155], v[194:197], v[60:63]
	v_mfma_f32_16x16x32_bf16 v[56:59], v[160:163], v[194:197], v[56:59]
	v_mfma_f32_16x16x32_bf16 v[52:55], v[152:155], v[202:205], v[52:55]
	v_mfma_f32_16x16x32_bf16 v[44:47], v[160:163], v[202:205], v[44:47]
	v_mfma_f32_16x16x32_bf16 v[36:39], v[152:155], v[210:213], v[36:39]
	v_mfma_f32_16x16x32_bf16 v[28:31], v[160:163], v[210:213], v[28:31]
	v_mfma_f32_16x16x32_bf16 v[20:23], v[152:155], v[218:221], v[20:23]
	v_mfma_f32_16x16x32_bf16 v[12:15], v[160:163], v[218:221], v[12:15]
	v_mfma_f32_16x16x32_bf16 v[48:51], v[174:177], v[190:193], v[48:51]
	v_mfma_f32_16x16x32_bf16 v[40:43], v[182:185], v[190:193], v[40:43]
	v_mfma_f32_16x16x32_bf16 v[32:35], v[174:177], v[198:201], v[32:35]
	v_mfma_f32_16x16x32_bf16 v[24:27], v[182:185], v[198:201], v[24:27]
	v_mfma_f32_16x16x32_bf16 v[16:19], v[174:177], v[206:209], v[16:19]
	v_mfma_f32_16x16x32_bf16 v[8:11], v[182:185], v[206:209], v[8:11]
	v_mfma_f32_16x16x32_bf16 v[4:7], v[174:177], v[214:217], v[4:7]
	v_mfma_f32_16x16x32_bf16 v[0:3], v[182:185], v[214:217], v[0:3]
	v_mfma_f32_16x16x32_bf16 v[48:51], v[178:181], v[194:197], v[48:51]
	v_mfma_f32_16x16x32_bf16 v[40:43], v[186:189], v[194:197], v[40:43]
	v_mfma_f32_16x16x32_bf16 v[32:35], v[178:181], v[202:205], v[32:35]
	v_mfma_f32_16x16x32_bf16 v[24:27], v[186:189], v[202:205], v[24:27]
	v_mfma_f32_16x16x32_bf16 v[16:19], v[178:181], v[210:213], v[16:19]
	v_mfma_f32_16x16x32_bf16 v[8:11], v[186:189], v[210:213], v[8:11]
	v_mfma_f32_16x16x32_bf16 v[4:7], v[178:181], v[218:221], v[4:7]
	v_mfma_f32_16x16x32_bf16 v[0:3], v[186:189], v[218:221], v[0:3]
	s_setprio 0
	s_barrier
	s_add_i32 s42, s42, 2
	s_add_u32 s22, s22, 0x100
	s_addc_u32 s23, s23, 0
	s_add_u32 s40, s40, 0x100
	s_addc_u32 s41, s41, 0
	s_cmp_gt_u32 s42, 13
	s_cbranch_scc0 .LBB0_44
	s_and_b64 vcc, exec, s[10:11]
	s_cbranch_vccz .LBB0_47
	s_barrier

; #define PG8_STAGE(bufoff, gbase, voff) do { _Pragma("unroll") for (int _i = 0; _i < 2; ++_i) \
;         __builtin_amdgcn_global_load_lds((const unsigned*)((const char*)(gbase) + (voff)[_i]), (PG8_LAS unsigned*)(lds + (bufoff) + ldsw + _i * 8192), 16, 0, 0); } while (0)
; #define PG8_LDA(dst, b, h) do { _Pragma("unroll") for (int m = 0; m < 4; ++m) _Pragma("unroll") for (int k = 0; k < 2; ++k) dst[m][k] = *(const PG8_LAS bf16x8*)(lds + PG8_SA(b, h) + aoff + m * 2048 + k * 1024); } while (0)
; #define PG8_LDB(dst, b, h) do { _Pragma("unroll") for (int n = 0; n < 2; ++n) _Pragma("unroll") for (int k = 0; k < 2; ++k) dst[n][k] = *(const PG8_LAS bf16x8*)(lds + PG8_SB(b, h) + boff + n * 2048 + k * 1024); } while (0)
; #define PG8_MMA(ai, bj, At, Bt) do { __builtin_amdgcn_s_setprio(1); _Pragma("unroll") for (int m = 0; m < 4; ++m) _Pragma("unroll") for (int n = 0; n < 2; ++n) _Pragma("unroll") for (int k = 0; k < 2; ++k) \
;         acc[ai][bj][m][n] = __builtin_amdgcn_mfma_f32_16x16x32_bf16(Bt[n][k], At[m][k], acc[ai][bj][m][n], 0, 0, 0); __builtin_amdgcn_s_setprio(0); } while (0)
; #define PG8_WAIT_V(n) asm volatile("s_waitcnt vmcnt(" #n ")" ::: "memory")
; #define PG8_WAIT_L(n) asm volatile("s_waitcnt lgkmcnt(" #n ")" ::: "memory")
; #define PG8_BAR __builtin_amdgcn_s_barrier()
; #define PG8_SCHED __builtin_amdgcn_sched_barrier(0)
; template <class Epi, class Sched, bool ALIGN_EPI, bool SP2, int KC>
; __device__ __forceinline__ void gemm_phase(PG8_LAS unsigned char* lds, const Gemm g, const Sched& S, const Epi& E, const int tid) {
;     ...
;             const bool last = (t == nt - 2);
;             const char* a1 = cA + (size_t)(t + 1) * kstep;
;             const char* a2 = last ? nA : cA + (size_t)(t + 2) * kstep; const char* b2 = last ? nB : cB + (size_t)(t + 2) * kstep;
;             const char* a3 = a2 + kstep; const char* b3 = b2 + kstep;
;             if (last && has_next) S.a_ready(nxt);
;             if constexpr (SP2) {
;             PG8_LDB(B0, 0, 0); PG8_LDB(B1, 0, 1); PG8_SCHED; PG8_LDA(At, 0, 0); PG8_STAGE(PG8_SA(1, 1), a1 + hstep, voffA);
;             PG8_WAIT_V(8); PG8_WAIT_L(0); PG8_BAR; PG8_MMA(0, 0, At, B0); PG8_MMA(0, 1, At, B1); PG8_BAR; PG8_SCHED;
;             PG8_LDA(At, 0, 1); PG8_STAGE(PG8_SB(0, 0), b2, voffB); PG8_STAGE(PG8_SB(0, 1), b2 + hstep, voffB); PG8_STAGE(PG8_SA(0, 0), a2, voffA);
.LBB0_66:
	s_add_u32 s24, s22, 0xfffc0080
	s_addc_u32 s25, s23, -1
	s_add_i32 s43, 0, 0x10000
	s_cmp_eq_u32 s42, 12
	s_cselect_b32 s27, s17, s25
	s_cselect_b32 s26, s38, s24
	v_add_u32_e32 v138, s43, v141
	s_cselect_b32 s25, s15, s41
	s_cselect_b32 s24, s39, s40
	s_add_i32 s46, 0, 0x14000
	ds_read_b128 v[146:149], v138
	ds_read_b128 v[150:153], v138 offset:1024
	ds_read_b128 v[154:157], v138 offset:2048
	ds_read_b128 v[158:161], v138 offset:3072
	v_add_u32_e32 v138, s46, v141
	ds_read_b128 v[174:177], v138
	ds_read_b128 v[178:181], v138 offset:1024
	ds_read_b128 v[182:185], v138 offset:2048
	ds_read_b128 v[186:189], v138 offset:3072
	v_lshl_add_u64 v[138:139], s[22:23], 0, v[134:135]
	s_add_i32 m0, s29, 0xc000
	ds_read_b128 v[190:193], v142
	ds_read_b128 v[194:197], v142 offset:1024
	ds_read_b128 v[198:201], v142 offset:2048
	ds_read_b128 v[202:205], v142 offset:3072
	ds_read_b128 v[206:209], v142 offset:4096
	ds_read_b128 v[210:213], v142 offset:5120
	ds_read_b128 v[214:217], v142 offset:6144
	ds_read_b128 v[218:221], v142 offset:7168
	global_load_lds_dwordx4 v[138:139], off
	v_lshl_add_u64 v[138:139], s[22:23], 0, v[136:137]
	s_add_i32 m0, s29, 0xe000
	s_nop 0
	global_load_lds_dwordx4 v[138:139], off
	s_waitcnt vmcnt(8)
	s_waitcnt lgkmcnt(0)
	s_barrier
	s_setprio 1
	s_waitcnt lgkmcnt(0)
	v_mfma_f32_16x16x32_bf16 v[124:127], v[146:149], v[190:193], v[124:127]
	v_mfma_f32_16x16x32_bf16 v[120:123], v[154:157], v[190:193], v[120:123]
	v_mfma_f32_16x16x32_bf16 v[116:119], v[146:149], v[198:201], v[116:119]
	v_mfma_f32_16x16x32_bf16 v[108:111], v[154:157], v[198:201], v[108:111]
	v_mfma_f32_16x16x32_bf16 v[100:103], v[146:149], v[206:209], v[100:103]
	v_mfma_f32_16x16x32_bf16 v[92:95], v[154:157], v[206:209], v[92:95]
	v_mfma_f32_16x16x32_bf16 v[80:83], v[146:149], v[214:217], v[80:83]
	v_mfma_f32_16x16x32_bf16 v[72:75], v[154:157], v[214:217], v[72:75]
	v_mfma_f32_16x16x32_bf16 v[124:127], v[150:153], v[194:197], v[124:127]
	v_mfma_f32_16x16x32_bf16 v[120:123], v[158:161], v[194:197], v[120:123]
	v_mfma_f32_16x16x32_bf16 v[116:119], v[150:153], v[202:205], v[116:119]
	v_mfma_f32_16x16x32_bf16 v[108:111], v[158:161], v[202:205], v[108:111]
	v_mfma_f32_16x16x32_bf16 v[100:103], v[150:153], v[210:213], v[100:103]
	v_mfma_f32_16x16x32_bf16 v[92:95], v[158:161], v[210:213], v[92:95]
	v_mfma_f32_16x16x32_bf16 v[80:83], v[150:153], v[218:221], v[80:83]
	v_mfma_f32_16x16x32_bf16 v[72:75], v[158:161], v[218:221], v[72:75]
	v_mfma_f32_16x16x32_bf16 v[112:115], v[174:177], v[190:193], v[112:115]
	v_mfma_f32_16x16x32_bf16 v[104:107], v[182:185], v[190:193], v[104:107]
	v_mfma_f32_16x16x32_bf16 v[96:99], v[174:177], v[198:201], v[96:99]
	v_mfma_f32_16x16x32_bf16 v[88:91], v[182:185], v[198:201], v[88:91]
	v_mfma_f32_16x16x32_bf16 v[84:87], v[174:177], v[206:209], v[84:87]
	v_mfma_f32_16x16x32_bf16 v[76:79], v[182:185], v[206:209], v[76:79]
	v_mfma_f32_16x16x32_bf16 v[68:71], v[174:177], v[214:217], v[68:71]
	v_mfma_f32_16x16x32_bf16 v[64:67], v[182:185], v[214:217], v[64:67]
	v_mfma_f32_16x16x32_bf16 v[112:115], v[178:181], v[194:197], v[112:115]
	v_mfma_f32_16x16x32_bf16 v[104:107], v[186:189], v[194:197], v[104:107]
	v_mfma_f32_16x16x32_bf16 v[96:99], v[178:181], v[202:205], v[96:99]
	v_mfma_f32_16x16x32_bf16 v[88:91], v[186:189], v[202:205], v[88:91]
	v_mfma_f32_16x16x32_bf16 v[84:87], v[178:181], v[210:213], v[84:87]
	v_mfma_f32_16x16x32_bf16 v[76:79], v[186:189], v[210:213], v[76:79]
	v_mfma_f32_16x16x32_bf16 v[68:71], v[178:181], v[218:221], v[68:71]
	v_mfma_f32_16x16x32_bf16 v[64:67], v[186:189], v[218:221], v[64:67]
	s_setprio 0
	s_barrier
	s_add_i32 s43, s43, s28
	v_lshl_add_u64 v[138:139], s[24:25], 0, v[164:165]
	s_mov_b32 m0, s43
	ds_read_b128 v[190:193], v142 offset:16384
	ds_read_b128 v[194:197], v142 offset:17408
	ds_read_b128 v[198:201], v142 offset:18432
	ds_read_b128 v[202:205], v142 offset:19456
	ds_read_b128 v[206:209], v142 offset:20480
	ds_read_b128 v[210:213], v142 offset:21504
	ds_read_b128 v[214:217], v142 offset:22528
	ds_read_b128 v[218:221], v142 offset:23552
	global_load_lds_dwordx4 v[138:139], off
	s_add_i32 m0, s43, 0x2000
	s_add_u32 s44, s24, 0x40000
	v_lshl_add_u64 v[162:163], s[24:25], 0, v[128:129]
	s_addc_u32 s45, s25, 0
	s_add_i32 s43, s46, s28
	global_load_lds_dwordx4 v[162:163], off
	v_lshl_add_u64 v[222:223], s[44:45], 0, v[164:165]
	s_mov_b32 m0, s43
	v_lshl_add_u64 v[234:235], s[26:27], 0, v[130:131]
	global_load_lds_dwordx4 v[222:223], off
	v_lshl_add_u64 v[222:223], s[44:45], 0, v[128:129]
	s_add_i32 m0, s43, 0x2000
	s_nop 0
	global_load_lds_dwordx4 v[222:223], off
	v_lshl_add_u64 v[222:223], s[26:27], 0, v[132:133]
	s_mov_b32 m0, s29
	s_nop 0
	global_load_lds_dwordx4 v[222:223], off
	s_mov_b32 m0, s30
	s_nop 0
	global_load_lds_dwordx4 v[234:235], off
	s_waitcnt vmcnt(8)
	s_waitcnt lgkmcnt(0)
	s_barrier
; #define PG8_STAGE(bufoff, gbase, voff) do { _Pragma("unroll") for (int _i = 0; _i < 2; ++_i) \
;         __builtin_amdgcn_global_load_lds((const unsigned*)((const char*)(gbase) + (voff)[_i]), (PG8_LAS unsigned*)(lds + (bufoff) + ldsw + _i * 8192), 16, 0, 0); } while (0)
; #define PG8_LDA(dst, b, h) do { _Pragma("unroll") for (int m = 0; m < 4; ++m) _Pragma("unroll") for (int k = 0; k < 2; ++k) dst[m][k] = *(const PG8_LAS bf16x8*)(lds + PG8_SA(b, h) + aoff + m * 2048 + k * 1024); } while (0)
; #define PG8_LDB(dst, b, h) do { _Pragma("unroll") for (int n = 0; n < 2; ++n) _Pragma("unroll") for (int k = 0; k < 2; ++k) dst[n][k] = *(const PG8_LAS bf16x8*)(lds + PG8_SB(b, h) + boff + n * 2048 + k * 1024); } while (0)
; #define PG8_MMA(ai, bj, At, Bt) do { __builtin_amdgcn_s_setprio(1); _Pragma("unroll") for (int m = 0; m < 4; ++m) _Pragma("unroll") for (int n = 0; n < 2; ++n) _Pragma("unroll") for (int k = 0; k < 2; ++k) \
;         acc[ai][bj][m][n] = __builtin_amdgcn_mfma_f32_16x16x32_bf16(Bt[n][k], At[m][k], acc[ai][bj][m][n], 0, 0, 0); __builtin_amdgcn_s_setprio(0); } while (0)
; #define PG8_WAIT_V(n) asm volatile("s_waitcnt vmcnt(" #n ")" ::: "memory")
; #define PG8_WAIT_L(n) asm volatile("s_waitcnt lgkmcnt(" #n ")" ::: "memory")
; #define PG8_BAR __builtin_amdgcn_s_barrier()
; #define PG8_SCHED __builtin_amdgcn_sched_barrier(0)
; template <class Epi, class Sched, bool ALIGN_EPI, bool SP2, int KC>
; __device__ __forceinline__ void gemm_phase(PG8_LAS unsigned char* lds, const Gemm g, const Sched& S, const Epi& E, const int tid) {
;     ...
;             PG8_WAIT_V(8); PG8_WAIT_L(0); PG8_BAR; PG8_MMA(1, 0, At, B0); PG8_MMA(1, 1, At, B1); PG8_BAR; PG8_SCHED;
;             PG8_LDB(B0, 1, 0); PG8_LDB(B1, 1, 1); PG8_SCHED; PG8_LDA(At, 1, 0); PG8_STAGE(PG8_SA(0, 1), a2 + hstep, voffA);
;             PG8_WAIT_V(8); PG8_WAIT_L(0); PG8_BAR; PG8_MMA(0, 0, At, B0); PG8_MMA(0, 1, At, B1); PG8_BAR; PG8_SCHED;
	s_setprio 1
	s_waitcnt lgkmcnt(0)
	v_mfma_f32_16x16x32_bf16 v[60:63], v[146:149], v[190:193], v[60:63]
	v_mfma_f32_16x16x32_bf16 v[56:59], v[154:157], v[190:193], v[56:59]
	v_mfma_f32_16x16x32_bf16 v[52:55], v[146:149], v[198:201], v[52:55]
	v_mfma_f32_16x16x32_bf16 v[44:47], v[154:157], v[198:201], v[44:47]
	v_mfma_f32_16x16x32_bf16 v[36:39], v[146:149], v[206:209], v[36:39]
	v_mfma_f32_16x16x32_bf16 v[28:31], v[154:157], v[206:209], v[28:31]
	v_mfma_f32_16x16x32_bf16 v[20:23], v[146:149], v[214:217], v[20:23]
	v_mfma_f32_16x16x32_bf16 v[12:15], v[154:157], v[214:217], v[12:15]
	v_mfma_f32_16x16x32_bf16 v[60:63], v[150:153], v[194:197], v[60:63]
	v_mfma_f32_16x16x32_bf16 v[56:59], v[158:161], v[194:197], v[56:59]
	v_mfma_f32_16x16x32_bf16 v[52:55], v[150:153], v[202:205], v[52:55]
	v_mfma_f32_16x16x32_bf16 v[44:47], v[158:161], v[202:205], v[44:47]
	v_mfma_f32_16x16x32_bf16 v[36:39], v[150:153], v[210:213], v[36:39]
	v_mfma_f32_16x16x32_bf16 v[28:31], v[158:161], v[210:213], v[28:31]
	v_mfma_f32_16x16x32_bf16 v[20:23], v[150:153], v[218:221], v[20:23]
	v_mfma_f32_16x16x32_bf16 v[12:15], v[158:161], v[218:221], v[12:15]
	v_mfma_f32_16x16x32_bf16 v[48:51], v[174:177], v[190:193], v[48:51]
	v_mfma_f32_16x16x32_bf16 v[40:43], v[182:185], v[190:193], v[40:43]
	v_mfma_f32_16x16x32_bf16 v[32:35], v[174:177], v[198:201], v[32:35]
	v_mfma_f32_16x16x32_bf16 v[24:27], v[182:185], v[198:201], v[24:27]
	v_mfma_f32_16x16x32_bf16 v[16:19], v[174:177], v[206:209], v[16:19]
	v_mfma_f32_16x16x32_bf16 v[8:11], v[182:185], v[206:209], v[8:11]
	v_mfma_f32_16x16x32_bf16 v[4:7], v[174:177], v[214:217], v[4:7]
	v_mfma_f32_16x16x32_bf16 v[0:3], v[182:185], v[214:217], v[0:3]
	v_mfma_f32_16x16x32_bf16 v[48:51], v[178:181], v[194:197], v[48:51]
	v_mfma_f32_16x16x32_bf16 v[40:43], v[186:189], v[194:197], v[40:43]
	v_mfma_f32_16x16x32_bf16 v[32:35], v[178:181], v[202:205], v[32:35]
	v_mfma_f32_16x16x32_bf16 v[24:27], v[186:189], v[202:205], v[24:27]
	v_mfma_f32_16x16x32_bf16 v[16:19], v[178:181], v[210:213], v[16:19]
	v_mfma_f32_16x16x32_bf16 v[8:11], v[186:189], v[210:213], v[8:11]
	v_mfma_f32_16x16x32_bf16 v[4:7], v[178:181], v[218:221], v[4:7]
	v_mfma_f32_16x16x32_bf16 v[0:3], v[186:189], v[218:221], v[0:3]
	s_setprio 0
	s_barrier
	s_add_i32 s43, 0, 0x18000
	v_add_u32_e32 v143, s43, v141
	s_add_i32 s44, 0, 0x1c000
	ds_read_b128 v[146:149], v143
	ds_read_b128 v[150:153], v143 offset:1024
	ds_read_b128 v[154:157], v143 offset:2048
	ds_read_b128 v[158:161], v143 offset:3072
	v_add_u32_e32 v143, s44, v141
	ds_read_b128 v[174:177], v143
	ds_read_b128 v[178:181], v143 offset:1024
	ds_read_b128 v[182:185], v143 offset:2048
	ds_read_b128 v[186:189], v143 offset:3072
	s_add_u32 s26, s26, 0x40000
	s_addc_u32 s27, s27, 0
	s_mov_b32 m0, s31
	v_lshl_add_u64 v[236:237], s[26:27], 0, v[132:133]
	ds_read_b128 v[190:193], v142 offset:32768
	ds_read_b128 v[194:197], v142 offset:33792
	ds_read_b128 v[198:201], v142 offset:34816
	ds_read_b128 v[202:205], v142 offset:35840
	ds_read_b128 v[206:209], v142 offset:36864
	ds_read_b128 v[210:213], v142 offset:37888
	ds_read_b128 v[214:217], v142 offset:38912
	ds_read_b128 v[218:221], v142 offset:39936
	global_load_lds_dwordx4 v[236:237], off
	v_lshl_add_u64 v[236:237], s[26:27], 0, v[130:131]
	s_mov_b32 m0, s34
	s_nop 0
	global_load_lds_dwordx4 v[236:237], off
	s_waitcnt vmcnt(8)
	s_waitcnt lgkmcnt(0)
	s_barrier
	s_setprio 1
	s_waitcnt lgkmcnt(0)
	v_mfma_f32_16x16x32_bf16 v[124:127], v[146:149], v[190:193], v[124:127]
	v_mfma_f32_16x16x32_bf16 v[120:123], v[154:157], v[190:193], v[120:123]
	v_mfma_f32_16x16x32_bf16 v[116:119], v[146:149], v[198:201], v[116:119]
	v_mfma_f32_16x16x32_bf16 v[108:111], v[154:157], v[198:201], v[108:111]
	v_mfma_f32_16x16x32_bf16 v[100:103], v[146:149], v[206:209], v[100:103]
	v_mfma_f32_16x16x32_bf16 v[92:95], v[154:157], v[206:209], v[92:95]
	v_mfma_f32_16x16x32_bf16 v[80:83], v[146:149], v[214:217], v[80:83]
	v_mfma_f32_16x16x32_bf16 v[72:75], v[154:157], v[214:217], v[72:75]
	v_mfma_f32_16x16x32_bf16 v[124:127], v[150:153], v[194:197], v[124:127]
	v_mfma_f32_16x16x32_bf16 v[120:123], v[158:161], v[194:197], v[120:123]
	v_mfma_f32_16x16x32_bf16 v[116:119], v[150:153], v[202:205], v[116:119]
	v_mfma_f32_16x16x32_bf16 v[108:111], v[158:161], v[202:205], v[108:111]
	v_mfma_f32_16x16x32_bf16 v[100:103], v[150:153], v[210:213], v[100:103]
	v_mfma_f32_16x16x32_bf16 v[92:95], v[158:161], v[210:213], v[92:95]
	v_mfma_f32_16x16x32_bf16 v[80:83], v[150:153], v[218:221], v[80:83]
	v_mfma_f32_16x16x32_bf16 v[72:75], v[158:161], v[218:221], v[72:75]
	v_mfma_f32_16x16x32_bf16 v[112:115], v[174:177], v[190:193], v[112:115]
	v_mfma_f32_16x16x32_bf16 v[104:107], v[182:185], v[190:193], v[104:107]
	v_mfma_f32_16x16x32_bf16 v[96:99], v[174:177], v[198:201], v[96:99]
	v_mfma_f32_16x16x32_bf16 v[88:91], v[182:185], v[198:201], v[88:91]
	v_mfma_f32_16x16x32_bf16 v[84:87], v[174:177], v[206:209], v[84:87]
	v_mfma_f32_16x16x32_bf16 v[76:79], v[182:185], v[206:209], v[76:79]
	v_mfma_f32_16x16x32_bf16 v[68:71], v[174:177], v[214:217], v[68:71]
	v_mfma_f32_16x16x32_bf16 v[64:67], v[182:185], v[214:217], v[64:67]
	v_mfma_f32_16x16x32_bf16 v[112:115], v[178:181], v[194:197], v[112:115]
	v_mfma_f32_16x16x32_bf16 v[104:107], v[186:189], v[194:197], v[104:107]
	v_mfma_f32_16x16x32_bf16 v[96:99], v[178:181], v[202:205], v[96:99]
	v_mfma_f32_16x16x32_bf16 v[88:91], v[186:189], v[202:205], v[88:91]
	v_mfma_f32_16x16x32_bf16 v[84:87], v[178:181], v[210:213], v[84:87]
	v_mfma_f32_16x16x32_bf16 v[76:79], v[186:189], v[210:213], v[76:79]
	v_mfma_f32_16x16x32_bf16 v[68:71], v[178:181], v[218:221], v[68:71]
	v_mfma_f32_16x16x32_bf16 v[64:67], v[186:189], v[218:221], v[64:67]
	s_setprio 0
	s_barrier
; #define PG8_STAGE(bufoff, gbase, voff) do { _Pragma("unroll") for (int _i = 0; _i < 2; ++_i) \
;         __builtin_amdgcn_global_load_lds((const unsigned*)((const char*)(gbase) + (voff)[_i]), (PG8_LAS unsigned*)(lds + (bufoff) + ldsw + _i * 8192), 16, 0, 0); } while (0)
; #define PG8_LDA(dst, b, h) do { _Pragma("unroll") for (int m = 0; m < 4; ++m) _Pragma("unroll") for (int k = 0; k < 2; ++k) dst[m][k] = *(const PG8_LAS bf16x8*)(lds + PG8_SA(b, h) + aoff + m * 2048 + k * 1024); } while (0)
; #define PG8_MMA(ai, bj, At, Bt) do { __builtin_amdgcn_s_setprio(1); _Pragma("unroll") for (int m = 0; m < 4; ++m) _Pragma("unroll") for (int n = 0; n < 2; ++n) _Pragma("unroll") for (int k = 0; k < 2; ++k) \
;         acc[ai][bj][m][n] = __builtin_amdgcn_mfma_f32_16x16x32_bf16(Bt[n][k], At[m][k], acc[ai][bj][m][n], 0, 0, 0); __builtin_amdgcn_s_setprio(0); } while (0)
; #define PG8_WAIT_V(n) asm volatile("s_waitcnt vmcnt(" #n ")" ::: "memory")
; #define PG8_WAIT_L(n) asm volatile("s_waitcnt lgkmcnt(" #n ")" ::: "memory")
; #define PG8_BAR __builtin_amdgcn_s_barrier()
; #define PG8_SCHED __builtin_amdgcn_sched_barrier(0)
; template <class Epi, class Sched, bool ALIGN_EPI, bool SP2, int KC>
; __device__ __forceinline__ void gemm_phase(PG8_LAS unsigned char* lds, const Gemm g, const Sched& S, const Epi& E, const int tid) {
;     ...
;             PG8_LDA(At, 1, 1); PG8_STAGE(PG8_SB(1, 0), b3, voffB); PG8_STAGE(PG8_SB(1, 1), b3 + hstep, voffB); PG8_STAGE(PG8_SA(1, 0), a3, voffA);
;             PG8_WAIT_V(8); PG8_WAIT_L(0); PG8_BAR; PG8_MMA(1, 0, At, B0); PG8_MMA(1, 1, At, B1); PG8_BAR; PG8_SCHED;
	s_add_i32 s26, s43, s28
	v_lshl_add_u64 v[138:139], v[138:139], 0, s[86:87]
	s_mov_b32 m0, s26
	ds_read_b128 v[190:193], v142 offset:49152
	ds_read_b128 v[194:197], v142 offset:50176
	ds_read_b128 v[198:201], v142 offset:51200
	ds_read_b128 v[202:205], v142 offset:52224
	ds_read_b128 v[206:209], v142 offset:53248
	ds_read_b128 v[210:213], v142 offset:54272
	ds_read_b128 v[214:217], v142 offset:55296
	ds_read_b128 v[218:221], v142 offset:56320
	global_load_lds_dwordx4 v[138:139], off
	s_add_i32 m0, s26, 0x2000
	s_add_u32 s24, s24, 0x40080
	v_lshl_add_u64 v[138:139], v[162:163], 0, s[86:87]
	s_addc_u32 s25, s25, 0
	s_add_i32 s26, s44, s28
	global_load_lds_dwordx4 v[138:139], off
	v_lshl_add_u64 v[138:139], s[24:25], 0, v[164:165]
	s_mov_b32 m0, s26
	s_nop 0
	global_load_lds_dwordx4 v[138:139], off
	v_lshl_add_u64 v[138:139], s[24:25], 0, v[128:129]
	s_add_i32 m0, s26, 0x2000
	s_nop 0
	global_load_lds_dwordx4 v[138:139], off
	v_lshl_add_u64 v[138:139], v[222:223], 0, s[86:87]
	s_mov_b32 m0, s35
	s_nop 0
	global_load_lds_dwordx4 v[138:139], off
	v_lshl_add_u64 v[138:139], v[234:235], 0, s[86:87]
	s_mov_b32 m0, s36
	s_nop 0
	global_load_lds_dwordx4 v[138:139], off
	s_waitcnt vmcnt(8)
	s_waitcnt lgkmcnt(0)
	s_barrier
	s_setprio 1
	s_waitcnt lgkmcnt(0)
	v_mfma_f32_16x16x32_bf16 v[60:63], v[146:149], v[190:193], v[60:63]
	v_mfma_f32_16x16x32_bf16 v[56:59], v[154:157], v[190:193], v[56:59]
	v_mfma_f32_16x16x32_bf16 v[52:55], v[146:149], v[198:201], v[52:55]
	v_mfma_f32_16x16x32_bf16 v[44:47], v[154:157], v[198:201], v[44:47]
	v_mfma_f32_16x16x32_bf16 v[36:39], v[146:149], v[206:209], v[36:39]
	v_mfma_f32_16x16x32_bf16 v[28:31], v[154:157], v[206:209], v[28:31]
	v_mfma_f32_16x16x32_bf16 v[20:23], v[146:149], v[214:217], v[20:23]
	v_mfma_f32_16x16x32_bf16 v[12:15], v[154:157], v[214:217], v[12:15]
	v_mfma_f32_16x16x32_bf16 v[60:63], v[150:153], v[194:197], v[60:63]
	v_mfma_f32_16x16x32_bf16 v[56:59], v[158:161], v[194:197], v[56:59]
	v_mfma_f32_16x16x32_bf16 v[52:55], v[150:153], v[202:205], v[52:55]
	v_mfma_f32_16x16x32_bf16 v[44:47], v[158:161], v[202:205], v[44:47]
	v_mfma_f32_16x16x32_bf16 v[36:39], v[150:153], v[210:213], v[36:39]
	v_mfma_f32_16x16x32_bf16 v[28:31], v[158:161], v[210:213], v[28:31]
	v_mfma_f32_16x16x32_bf16 v[20:23], v[150:153], v[218:221], v[20:23]
	v_mfma_f32_16x16x32_bf16 v[12:15], v[158:161], v[218:221], v[12:15]
	v_mfma_f32_16x16x32_bf16 v[48:51], v[174:177], v[190:193], v[48:51]
	v_mfma_f32_16x16x32_bf16 v[40:43], v[182:185], v[190:193], v[40:43]
	v_mfma_f32_16x16x32_bf16 v[32:35], v[174:177], v[198:201], v[32:35]
	v_mfma_f32_16x16x32_bf16 v[24:27], v[182:185], v[198:201], v[24:27]
	v_mfma_f32_16x16x32_bf16 v[16:19], v[174:177], v[206:209], v[16:19]
	v_mfma_f32_16x16x32_bf16 v[8:11], v[182:185], v[206:209], v[8:11]
	v_mfma_f32_16x16x32_bf16 v[4:7], v[174:177], v[214:217], v[4:7]
	v_mfma_f32_16x16x32_bf16 v[0:3], v[182:185], v[214:217], v[0:3]
	v_mfma_f32_16x16x32_bf16 v[48:51], v[178:181], v[194:197], v[48:51]
	v_mfma_f32_16x16x32_bf16 v[40:43], v[186:189], v[194:197], v[40:43]
	v_mfma_f32_16x16x32_bf16 v[32:35], v[178:181], v[202:205], v[32:35]
	v_mfma_f32_16x16x32_bf16 v[24:27], v[186:189], v[202:205], v[24:27]
	v_mfma_f32_16x16x32_bf16 v[16:19], v[178:181], v[210:213], v[16:19]
	v_mfma_f32_16x16x32_bf16 v[8:11], v[186:189], v[210:213], v[8:11]
	v_mfma_f32_16x16x32_bf16 v[4:7], v[178:181], v[218:221], v[4:7]
	v_mfma_f32_16x16x32_bf16 v[0:3], v[186:189], v[218:221], v[0:3]
	s_setprio 0
	s_barrier
	s_add_i32 s42, s42, 2
	s_add_u32 s22, s22, 0x100
	s_addc_u32 s23, s23, 0
	s_add_u32 s40, s40, 0x100
	s_addc_u32 s41, s41, 0
	s_cmp_gt_u32 s42, 13
	s_cbranch_scc0 .LBB0_66
	s_and_b64 vcc, exec, s[10:11]
	s_cbranch_vccz .LBB0_69
	s_barrier

; #define PG8_STAGE(bufoff, gbase, voff) do { _Pragma("unroll") for (int _i = 0; _i < 2; ++_i) \
;         __builtin_amdgcn_global_load_lds((const unsigned*)((const char*)(gbase) + (voff)[_i]), (PG8_LAS unsigned*)(lds + (bufoff) + ldsw + _i * 8192), 16, 0, 0); } while (0)
; #define PG8_LDA(dst, b, h) do { _Pragma("unroll") for (int m = 0; m < 4; ++m) _Pragma("unroll") for (int k = 0; k < 2; ++k) dst[m][k] = *(const PG8_LAS bf16x8*)(lds + PG8_SA(b, h) + aoff + m * 2048 + k * 1024); } while (0)
; #define PG8_LDB(dst, b, h) do { _Pragma("unroll") for (int n = 0; n < 2; ++n) _Pragma("unroll") for (int k = 0; k < 2; ++k) dst[n][k] = *(const PG8_LAS bf16x8*)(lds + PG8_SB(b, h) + boff + n * 2048 + k * 1024); } while (0)
; #define PG8_MMA(ai, bj, At, Bt) do { __builtin_amdgcn_s_setprio(1); _Pragma("unroll") for (int m = 0; m < 4; ++m) _Pragma("unroll") for (int n = 0; n < 2; ++n) _Pragma("unroll") for (int k = 0; k < 2; ++k) \
;         acc[ai][bj][m][n] = __builtin_amdgcn_mfma_f32_16x16x32_bf16(Bt[n][k], At[m][k], acc[ai][bj][m][n], 0, 0, 0); __builtin_amdgcn_s_setprio(0); } while (0)
; #define PG8_WAIT_V(n) asm volatile("s_waitcnt vmcnt(" #n ")" ::: "memory")
; #define PG8_WAIT_L(n) asm volatile("s_waitcnt lgkmcnt(" #n ")" ::: "memory")
; #define PG8_BAR __builtin_amdgcn_s_barrier()
; #define PG8_SCHED __builtin_amdgcn_sched_barrier(0)
; template <class Epi, class Sched, bool ALIGN_EPI, bool SP2, int KC>
; __device__ __forceinline__ void gemm_phase(PG8_LAS unsigned char* lds, const Gemm g, const Sched& S, const Epi& E, const int tid) {
;     ...
;             const bool last = (t == nt - 2);
;             const char* a1 = cA + (size_t)(t + 1) * kstep;
;             const char* a2 = last ? nA : cA + (size_t)(t + 2) * kstep; const char* b2 = last ? nB : cB + (size_t)(t + 2) * kstep;
;             const char* a3 = a2 + kstep; const char* b3 = b2 + kstep;
;             if (last && has_next) S.a_ready(nxt);
;             if constexpr (SP2) {
;             PG8_LDB(B0, 0, 0); PG8_LDB(B1, 0, 1); PG8_SCHED; PG8_LDA(At, 0, 0); PG8_STAGE(PG8_SA(1, 1), a1 + hstep, voffA);
;             PG8_WAIT_V(8); PG8_WAIT_L(0); PG8_BAR; PG8_MMA(0, 0, At, B0); PG8_MMA(0, 1, At, B1); PG8_BAR; PG8_SCHED;
;             PG8_LDA(At, 0, 1); PG8_STAGE(PG8_SB(0, 0), b2, voffB); PG8_STAGE(PG8_SB(0, 1), b2 + hstep, voffB); PG8_STAGE(PG8_SA(0, 0), a2, voffA);
.LBB0_92:
	s_add_u32 s26, s4, 0xfffc0080
	s_addc_u32 s27, s5, -1
	s_add_i32 s45, 0, 0x10000
	s_cmp_eq_u32 s44, 12
	s_cselect_b32 s29, s19, s27
	s_cselect_b32 s28, s40, s26
	s_cselect_b32 s27, s17, s43
	s_cselect_b32 s26, s41, s42
	s_add_i32 s48, 0, 0x14000
	v_add_u32_e32 v76, s45, v222
	v_add_u32_e32 v156, s48, v222
	ds_read_b128 v[64:67], v76
	ds_read_b128 v[68:71], v76 offset:1024
	ds_read_b128 v[72:75], v76 offset:2048
	ds_read_b128 v[76:79], v76 offset:3072
	ds_read_b128 v[144:147], v156
	ds_read_b128 v[148:151], v156 offset:1024
	ds_read_b128 v[152:155], v156 offset:2048
	ds_read_b128 v[156:159], v156 offset:3072
	v_lshl_add_u64 v[212:213], s[4:5], 0, v[176:177]
	s_add_i32 m0, s7, 0xc000
	ds_read_b128 v[180:183], v233
	ds_read_b128 v[184:187], v233 offset:1024
	ds_read_b128 v[188:191], v233 offset:2048
	ds_read_b128 v[192:195], v233 offset:3072
	ds_read_b128 v[196:199], v233 offset:4096
	ds_read_b128 v[200:203], v233 offset:5120
	ds_read_b128 v[204:207], v233 offset:6144
	ds_read_b128 v[208:211], v233 offset:7168
	global_load_lds_dwordx4 v[212:213], off
	v_lshl_add_u64 v[212:213], s[4:5], 0, v[178:179]
	s_add_i32 m0, s7, 0xe000
	s_nop 0
	global_load_lds_dwordx4 v[212:213], off
	s_waitcnt vmcnt(8)
	s_waitcnt lgkmcnt(0)
	s_barrier
	s_setprio 1
	s_waitcnt lgkmcnt(0)
	v_mfma_f32_16x16x32_bf16 v[140:143], v[64:67], v[180:183], v[140:143]
	v_mfma_f32_16x16x32_bf16 v[132:135], v[72:75], v[180:183], v[132:135]
	v_mfma_f32_16x16x32_bf16 v[124:127], v[64:67], v[188:191], v[124:127]
	v_mfma_f32_16x16x32_bf16 v[116:119], v[72:75], v[188:191], v[116:119]
	v_mfma_f32_16x16x32_bf16 v[108:111], v[64:67], v[196:199], v[108:111]
	v_mfma_f32_16x16x32_bf16 v[100:103], v[72:75], v[196:199], v[100:103]
	v_mfma_f32_16x16x32_bf16 v[92:95], v[64:67], v[204:207], v[92:95]
	v_mfma_f32_16x16x32_bf16 v[84:87], v[72:75], v[204:207], v[84:87]
	v_mfma_f32_16x16x32_bf16 v[140:143], v[68:71], v[184:187], v[140:143]
	v_mfma_f32_16x16x32_bf16 v[132:135], v[76:79], v[184:187], v[132:135]
	v_mfma_f32_16x16x32_bf16 v[124:127], v[68:71], v[192:195], v[124:127]
	v_mfma_f32_16x16x32_bf16 v[116:119], v[76:79], v[192:195], v[116:119]
	v_mfma_f32_16x16x32_bf16 v[108:111], v[68:71], v[200:203], v[108:111]
	v_mfma_f32_16x16x32_bf16 v[100:103], v[76:79], v[200:203], v[100:103]
	v_mfma_f32_16x16x32_bf16 v[92:95], v[68:71], v[208:211], v[92:95]
	v_mfma_f32_16x16x32_bf16 v[84:87], v[76:79], v[208:211], v[84:87]
	v_mfma_f32_16x16x32_bf16 v[136:139], v[144:147], v[180:183], v[136:139]
	v_mfma_f32_16x16x32_bf16 v[128:131], v[152:155], v[180:183], v[128:131]
	v_mfma_f32_16x16x32_bf16 v[120:123], v[144:147], v[188:191], v[120:123]
	v_mfma_f32_16x16x32_bf16 v[112:115], v[152:155], v[188:191], v[112:115]
	v_mfma_f32_16x16x32_bf16 v[104:107], v[144:147], v[196:199], v[104:107]
	v_mfma_f32_16x16x32_bf16 v[96:99], v[152:155], v[196:199], v[96:99]
	v_mfma_f32_16x16x32_bf16 v[88:91], v[144:147], v[204:207], v[88:91]
	v_mfma_f32_16x16x32_bf16 v[80:83], v[152:155], v[204:207], v[80:83]
	v_mfma_f32_16x16x32_bf16 v[136:139], v[148:151], v[184:187], v[136:139]
	v_mfma_f32_16x16x32_bf16 v[128:131], v[156:159], v[184:187], v[128:131]
	v_mfma_f32_16x16x32_bf16 v[120:123], v[148:151], v[192:195], v[120:123]
	v_mfma_f32_16x16x32_bf16 v[112:115], v[156:159], v[192:195], v[112:115]
	v_mfma_f32_16x16x32_bf16 v[104:107], v[148:151], v[200:203], v[104:107]
	v_mfma_f32_16x16x32_bf16 v[96:99], v[156:159], v[200:203], v[96:99]
	v_mfma_f32_16x16x32_bf16 v[88:91], v[148:151], v[208:211], v[88:91]
	v_mfma_f32_16x16x32_bf16 v[80:83], v[156:159], v[208:211], v[80:83]
	s_setprio 0
	s_barrier
	s_add_i32 s45, s45, s6
	v_lshl_add_u64 v[212:213], s[26:27], 0, v[164:165]
	s_mov_b32 m0, s45
	ds_read_b128 v[180:183], v233 offset:16384
	ds_read_b128 v[184:187], v233 offset:17408
	ds_read_b128 v[188:191], v233 offset:18432
	ds_read_b128 v[192:195], v233 offset:19456
	ds_read_b128 v[196:199], v233 offset:20480
	ds_read_b128 v[200:203], v233 offset:21504
	ds_read_b128 v[204:207], v233 offset:22528
	ds_read_b128 v[208:211], v233 offset:23552
	global_load_lds_dwordx4 v[212:213], off
	s_add_i32 m0, s45, 0x2000
	s_add_u32 s46, s26, 0x40000
	v_lshl_add_u64 v[214:215], s[26:27], 0, v[160:161]
	s_addc_u32 s47, s27, 0
	s_add_i32 s45, s48, s6
	global_load_lds_dwordx4 v[214:215], off
	v_lshl_add_u64 v[216:217], s[46:47], 0, v[164:165]
	s_mov_b32 m0, s45
	v_lshl_add_u64 v[218:219], s[28:29], 0, v[162:163]
	global_load_lds_dwordx4 v[216:217], off
	v_lshl_add_u64 v[216:217], s[46:47], 0, v[160:161]
	s_add_i32 m0, s45, 0x2000
	s_nop 0
	global_load_lds_dwordx4 v[216:217], off
	v_lshl_add_u64 v[216:217], s[28:29], 0, v[174:175]
	s_mov_b32 m0, s7
	s_nop 0
	global_load_lds_dwordx4 v[216:217], off
	s_mov_b32 m0, s30
	s_nop 0
	global_load_lds_dwordx4 v[218:219], off
	s_waitcnt vmcnt(8)
	s_waitcnt lgkmcnt(0)
	s_barrier
; #define PG8_STAGE(bufoff, gbase, voff) do { _Pragma("unroll") for (int _i = 0; _i < 2; ++_i) \
;         __builtin_amdgcn_global_load_lds((const unsigned*)((const char*)(gbase) + (voff)[_i]), (PG8_LAS unsigned*)(lds + (bufoff) + ldsw + _i * 8192), 16, 0, 0); } while (0)
; #define PG8_LDA(dst, b, h) do { _Pragma("unroll") for (int m = 0; m < 4; ++m) _Pragma("unroll") for (int k = 0; k < 2; ++k) dst[m][k] = *(const PG8_LAS bf16x8*)(lds + PG8_SA(b, h) + aoff + m * 2048 + k * 1024); } while (0)
; #define PG8_LDB(dst, b, h) do { _Pragma("unroll") for (int n = 0; n < 2; ++n) _Pragma("unroll") for (int k = 0; k < 2; ++k) dst[n][k] = *(const PG8_LAS bf16x8*)(lds + PG8_SB(b, h) + boff + n * 2048 + k * 1024); } while (0)
; #define PG8_MMA(ai, bj, At, Bt) do { __builtin_amdgcn_s_setprio(1); _Pragma("unroll") for (int m = 0; m < 4; ++m) _Pragma("unroll") for (int n = 0; n < 2; ++n) _Pragma("unroll") for (int k = 0; k < 2; ++k) \
;         acc[ai][bj][m][n] = __builtin_amdgcn_mfma_f32_16x16x32_bf16(Bt[n][k], At[m][k], acc[ai][bj][m][n], 0, 0, 0); __builtin_amdgcn_s_setprio(0); } while (0)
; #define PG8_WAIT_V(n) asm volatile("s_waitcnt vmcnt(" #n ")" ::: "memory")
; #define PG8_WAIT_L(n) asm volatile("s_waitcnt lgkmcnt(" #n ")" ::: "memory")
; #define PG8_BAR __builtin_amdgcn_s_barrier()
; #define PG8_SCHED __builtin_amdgcn_sched_barrier(0)
; template <class Epi, class Sched, bool ALIGN_EPI, bool SP2, int KC>
; __device__ __forceinline__ void gemm_phase(PG8_LAS unsigned char* lds, const Gemm g, const Sched& S, const Epi& E, const int tid) {
;     ...
;             PG8_WAIT_V(8); PG8_WAIT_L(0); PG8_BAR; PG8_MMA(1, 0, At, B0); PG8_MMA(1, 1, At, B1); PG8_BAR; PG8_SCHED;
;             PG8_LDB(B0, 1, 0); PG8_LDB(B1, 1, 1); PG8_SCHED; PG8_LDA(At, 1, 0); PG8_STAGE(PG8_SA(0, 1), a2 + hstep, voffA);
;             PG8_WAIT_V(8); PG8_WAIT_L(0); PG8_BAR; PG8_MMA(0, 0, At, B0); PG8_MMA(0, 1, At, B1); PG8_BAR; PG8_SCHED;
	s_setprio 1
	s_waitcnt lgkmcnt(0)
	v_mfma_f32_16x16x32_bf16 v[60:63], v[64:67], v[180:183], v[60:63]
	v_mfma_f32_16x16x32_bf16 v[52:55], v[72:75], v[180:183], v[52:55]
	v_mfma_f32_16x16x32_bf16 v[44:47], v[64:67], v[188:191], v[44:47]
	v_mfma_f32_16x16x32_bf16 v[36:39], v[72:75], v[188:191], v[36:39]
	v_mfma_f32_16x16x32_bf16 v[28:31], v[64:67], v[196:199], v[28:31]
	v_mfma_f32_16x16x32_bf16 v[20:23], v[72:75], v[196:199], v[20:23]
	v_mfma_f32_16x16x32_bf16 v[12:15], v[64:67], v[204:207], v[12:15]
	v_mfma_f32_16x16x32_bf16 v[4:7], v[72:75], v[204:207], v[4:7]
	v_mfma_f32_16x16x32_bf16 v[60:63], v[68:71], v[184:187], v[60:63]
	v_mfma_f32_16x16x32_bf16 v[52:55], v[76:79], v[184:187], v[52:55]
	v_mfma_f32_16x16x32_bf16 v[44:47], v[68:71], v[192:195], v[44:47]
	v_mfma_f32_16x16x32_bf16 v[36:39], v[76:79], v[192:195], v[36:39]
	v_mfma_f32_16x16x32_bf16 v[28:31], v[68:71], v[200:203], v[28:31]
	v_mfma_f32_16x16x32_bf16 v[20:23], v[76:79], v[200:203], v[20:23]
	v_mfma_f32_16x16x32_bf16 v[12:15], v[68:71], v[208:211], v[12:15]
	v_mfma_f32_16x16x32_bf16 v[4:7], v[76:79], v[208:211], v[4:7]
	v_mfma_f32_16x16x32_bf16 v[56:59], v[144:147], v[180:183], v[56:59]
	v_mfma_f32_16x16x32_bf16 v[48:51], v[152:155], v[180:183], v[48:51]
	v_mfma_f32_16x16x32_bf16 v[40:43], v[144:147], v[188:191], v[40:43]
	v_mfma_f32_16x16x32_bf16 v[32:35], v[152:155], v[188:191], v[32:35]
	v_mfma_f32_16x16x32_bf16 v[24:27], v[144:147], v[196:199], v[24:27]
	v_mfma_f32_16x16x32_bf16 v[16:19], v[152:155], v[196:199], v[16:19]
	v_mfma_f32_16x16x32_bf16 v[8:11], v[144:147], v[204:207], v[8:11]
	v_mfma_f32_16x16x32_bf16 v[0:3], v[152:155], v[204:207], v[0:3]
	v_mfma_f32_16x16x32_bf16 v[56:59], v[148:151], v[184:187], v[56:59]
	v_mfma_f32_16x16x32_bf16 v[48:51], v[156:159], v[184:187], v[48:51]
	v_mfma_f32_16x16x32_bf16 v[40:43], v[148:151], v[192:195], v[40:43]
	v_mfma_f32_16x16x32_bf16 v[32:35], v[156:159], v[192:195], v[32:35]
	v_mfma_f32_16x16x32_bf16 v[24:27], v[148:151], v[200:203], v[24:27]
	v_mfma_f32_16x16x32_bf16 v[16:19], v[156:159], v[200:203], v[16:19]
	v_mfma_f32_16x16x32_bf16 v[8:11], v[148:151], v[208:211], v[8:11]
	v_mfma_f32_16x16x32_bf16 v[0:3], v[156:159], v[208:211], v[0:3]
	s_setprio 0
	s_barrier
	s_add_i32 s45, 0, 0x18000
	s_add_i32 s46, 0, 0x1c000
	v_add_u32_e32 v76, s45, v222
	v_add_u32_e32 v156, s46, v222
	ds_read_b128 v[64:67], v76
	ds_read_b128 v[68:71], v76 offset:1024
	ds_read_b128 v[72:75], v76 offset:2048
	ds_read_b128 v[76:79], v76 offset:3072
	ds_read_b128 v[144:147], v156
	ds_read_b128 v[148:151], v156 offset:1024
	ds_read_b128 v[152:155], v156 offset:2048
	ds_read_b128 v[156:159], v156 offset:3072
	s_add_u32 s28, s28, 0x40000
	s_addc_u32 s29, s29, 0
	s_mov_b32 m0, s31
	v_lshl_add_u64 v[220:221], s[28:29], 0, v[174:175]
	ds_read_b128 v[180:183], v233 offset:32768
	ds_read_b128 v[184:187], v233 offset:33792
	ds_read_b128 v[188:191], v233 offset:34816
	ds_read_b128 v[192:195], v233 offset:35840
	ds_read_b128 v[196:199], v233 offset:36864
	ds_read_b128 v[200:203], v233 offset:37888
	ds_read_b128 v[204:207], v233 offset:38912
	ds_read_b128 v[208:211], v233 offset:39936
	global_load_lds_dwordx4 v[220:221], off
	v_lshl_add_u64 v[220:221], s[28:29], 0, v[162:163]
	s_mov_b32 m0, s34
	s_nop 0
	global_load_lds_dwordx4 v[220:221], off
	s_waitcnt vmcnt(8)
	s_waitcnt lgkmcnt(0)
	s_barrier
	s_setprio 1
	s_waitcnt lgkmcnt(0)
	v_mfma_f32_16x16x32_bf16 v[140:143], v[64:67], v[180:183], v[140:143]
	v_mfma_f32_16x16x32_bf16 v[132:135], v[72:75], v[180:183], v[132:135]
	v_mfma_f32_16x16x32_bf16 v[124:127], v[64:67], v[188:191], v[124:127]
	v_mfma_f32_16x16x32_bf16 v[116:119], v[72:75], v[188:191], v[116:119]
	v_mfma_f32_16x16x32_bf16 v[108:111], v[64:67], v[196:199], v[108:111]
	v_mfma_f32_16x16x32_bf16 v[100:103], v[72:75], v[196:199], v[100:103]
	v_mfma_f32_16x16x32_bf16 v[92:95], v[64:67], v[204:207], v[92:95]
	v_mfma_f32_16x16x32_bf16 v[84:87], v[72:75], v[204:207], v[84:87]
	v_mfma_f32_16x16x32_bf16 v[140:143], v[68:71], v[184:187], v[140:143]
	v_mfma_f32_16x16x32_bf16 v[132:135], v[76:79], v[184:187], v[132:135]
	v_mfma_f32_16x16x32_bf16 v[124:127], v[68:71], v[192:195], v[124:127]
	v_mfma_f32_16x16x32_bf16 v[116:119], v[76:79], v[192:195], v[116:119]
	v_mfma_f32_16x16x32_bf16 v[108:111], v[68:71], v[200:203], v[108:111]
	v_mfma_f32_16x16x32_bf16 v[100:103], v[76:79], v[200:203], v[100:103]
	v_mfma_f32_16x16x32_bf16 v[92:95], v[68:71], v[208:211], v[92:95]
	v_mfma_f32_16x16x32_bf16 v[84:87], v[76:79], v[208:211], v[84:87]
	v_mfma_f32_16x16x32_bf16 v[136:139], v[144:147], v[180:183], v[136:139]
	v_mfma_f32_16x16x32_bf16 v[128:131], v[152:155], v[180:183], v[128:131]
	v_mfma_f32_16x16x32_bf16 v[120:123], v[144:147], v[188:191], v[120:123]
	v_mfma_f32_16x16x32_bf16 v[112:115], v[152:155], v[188:191], v[112:115]
	v_mfma_f32_16x16x32_bf16 v[104:107], v[144:147], v[196:199], v[104:107]
	v_mfma_f32_16x16x32_bf16 v[96:99], v[152:155], v[196:199], v[96:99]
	v_mfma_f32_16x16x32_bf16 v[88:91], v[144:147], v[204:207], v[88:91]
	v_mfma_f32_16x16x32_bf16 v[80:83], v[152:155], v[204:207], v[80:83]
	v_mfma_f32_16x16x32_bf16 v[136:139], v[148:151], v[184:187], v[136:139]
	v_mfma_f32_16x16x32_bf16 v[128:131], v[156:159], v[184:187], v[128:131]
	v_mfma_f32_16x16x32_bf16 v[120:123], v[148:151], v[192:195], v[120:123]
	v_mfma_f32_16x16x32_bf16 v[112:115], v[156:159], v[192:195], v[112:115]
	v_mfma_f32_16x16x32_bf16 v[104:107], v[148:151], v[200:203], v[104:107]
	v_mfma_f32_16x16x32_bf16 v[96:99], v[156:159], v[200:203], v[96:99]
	v_mfma_f32_16x16x32_bf16 v[88:91], v[148:151], v[208:211], v[88:91]
	v_mfma_f32_16x16x32_bf16 v[80:83], v[156:159], v[208:211], v[80:83]
	s_setprio 0
	s_barrier
; #define PG8_STAGE(bufoff, gbase, voff) do { _Pragma("unroll") for (int _i = 0; _i < 2; ++_i) \
;         __builtin_amdgcn_global_load_lds((const unsigned*)((const char*)(gbase) + (voff)[_i]), (PG8_LAS unsigned*)(lds + (bufoff) + ldsw + _i * 8192), 16, 0, 0); } while (0)
; #define PG8_LDA(dst, b, h) do { _Pragma("unroll") for (int m = 0; m < 4; ++m) _Pragma("unroll") for (int k = 0; k < 2; ++k) dst[m][k] = *(const PG8_LAS bf16x8*)(lds + PG8_SA(b, h) + aoff + m * 2048 + k * 1024); } while (0)
; #define PG8_MMA(ai, bj, At, Bt) do { __builtin_amdgcn_s_setprio(1); _Pragma("unroll") for (int m = 0; m < 4; ++m) _Pragma("unroll") for (int n = 0; n < 2; ++n) _Pragma("unroll") for (int k = 0; k < 2; ++k) \
;         acc[ai][bj][m][n] = __builtin_amdgcn_mfma_f32_16x16x32_bf16(Bt[n][k], At[m][k], acc[ai][bj][m][n], 0, 0, 0); __builtin_amdgcn_s_setprio(0); } while (0)
; #define PG8_WAIT_V(n) asm volatile("s_waitcnt vmcnt(" #n ")" ::: "memory")
; #define PG8_WAIT_L(n) asm volatile("s_waitcnt lgkmcnt(" #n ")" ::: "memory")
; #define PG8_BAR __builtin_amdgcn_s_barrier()
; #define PG8_SCHED __builtin_amdgcn_sched_barrier(0)
; template <class Epi, class Sched, bool ALIGN_EPI, bool SP2, int KC>
; __device__ __forceinline__ void gemm_phase(PG8_LAS unsigned char* lds, const Gemm g, const Sched& S, const Epi& E, const int tid) {
;     ...
;             PG8_LDA(At, 1, 1); PG8_STAGE(PG8_SB(1, 0), b3, voffB); PG8_STAGE(PG8_SB(1, 1), b3 + hstep, voffB); PG8_STAGE(PG8_SA(1, 0), a3, voffA);
;             PG8_WAIT_V(8); PG8_WAIT_L(0); PG8_BAR; PG8_MMA(1, 0, At, B0); PG8_MMA(1, 1, At, B1); PG8_BAR; PG8_SCHED;
	s_add_i32 s28, s45, s6
	v_lshl_add_u64 v[212:213], v[212:213], 0, s[86:87]
	s_mov_b32 m0, s28
	ds_read_b128 v[180:183], v233 offset:49152
	ds_read_b128 v[184:187], v233 offset:50176
	ds_read_b128 v[188:191], v233 offset:51200
	ds_read_b128 v[192:195], v233 offset:52224
	ds_read_b128 v[196:199], v233 offset:53248
	ds_read_b128 v[200:203], v233 offset:54272
	ds_read_b128 v[204:207], v233 offset:55296
	ds_read_b128 v[208:211], v233 offset:56320
	global_load_lds_dwordx4 v[212:213], off
	s_add_i32 m0, s28, 0x2000
	s_add_u32 s26, s26, 0x40080
	v_lshl_add_u64 v[212:213], v[214:215], 0, s[86:87]
	s_addc_u32 s27, s27, 0
	s_add_i32 s28, s46, s6
	global_load_lds_dwordx4 v[212:213], off
	v_lshl_add_u64 v[212:213], s[26:27], 0, v[164:165]
	s_mov_b32 m0, s28
	s_nop 0
	global_load_lds_dwordx4 v[212:213], off
	v_lshl_add_u64 v[212:213], s[26:27], 0, v[160:161]
	s_add_i32 m0, s28, 0x2000
	s_nop 0
	global_load_lds_dwordx4 v[212:213], off
	v_lshl_add_u64 v[212:213], v[216:217], 0, s[86:87]
	s_mov_b32 m0, s35
	s_nop 0
	global_load_lds_dwordx4 v[212:213], off
	v_lshl_add_u64 v[212:213], v[218:219], 0, s[86:87]
	s_mov_b32 m0, s36
	s_nop 0
	global_load_lds_dwordx4 v[212:213], off
	s_waitcnt vmcnt(8)
	s_waitcnt lgkmcnt(0)
	s_barrier
	s_setprio 1
	s_waitcnt lgkmcnt(0)
	v_mfma_f32_16x16x32_bf16 v[60:63], v[64:67], v[180:183], v[60:63]
	v_mfma_f32_16x16x32_bf16 v[52:55], v[72:75], v[180:183], v[52:55]
	v_mfma_f32_16x16x32_bf16 v[44:47], v[64:67], v[188:191], v[44:47]
	v_mfma_f32_16x16x32_bf16 v[36:39], v[72:75], v[188:191], v[36:39]
	v_mfma_f32_16x16x32_bf16 v[28:31], v[64:67], v[196:199], v[28:31]
	v_mfma_f32_16x16x32_bf16 v[20:23], v[72:75], v[196:199], v[20:23]
	v_mfma_f32_16x16x32_bf16 v[12:15], v[64:67], v[204:207], v[12:15]
	v_mfma_f32_16x16x32_bf16 v[4:7], v[72:75], v[204:207], v[4:7]
	v_mfma_f32_16x16x32_bf16 v[60:63], v[68:71], v[184:187], v[60:63]
	v_mfma_f32_16x16x32_bf16 v[52:55], v[76:79], v[184:187], v[52:55]
	v_mfma_f32_16x16x32_bf16 v[44:47], v[68:71], v[192:195], v[44:47]
	v_mfma_f32_16x16x32_bf16 v[36:39], v[76:79], v[192:195], v[36:39]
	v_mfma_f32_16x16x32_bf16 v[28:31], v[68:71], v[200:203], v[28:31]
	v_mfma_f32_16x16x32_bf16 v[20:23], v[76:79], v[200:203], v[20:23]
	v_mfma_f32_16x16x32_bf16 v[12:15], v[68:71], v[208:211], v[12:15]
	v_mfma_f32_16x16x32_bf16 v[4:7], v[76:79], v[208:211], v[4:7]
	v_mfma_f32_16x16x32_bf16 v[56:59], v[144:147], v[180:183], v[56:59]
	v_mfma_f32_16x16x32_bf16 v[48:51], v[152:155], v[180:183], v[48:51]
	v_mfma_f32_16x16x32_bf16 v[40:43], v[144:147], v[188:191], v[40:43]
	v_mfma_f32_16x16x32_bf16 v[32:35], v[152:155], v[188:191], v[32:35]
	v_mfma_f32_16x16x32_bf16 v[24:27], v[144:147], v[196:199], v[24:27]
	v_mfma_f32_16x16x32_bf16 v[16:19], v[152:155], v[196:199], v[16:19]
	v_mfma_f32_16x16x32_bf16 v[8:11], v[144:147], v[204:207], v[8:11]
	v_mfma_f32_16x16x32_bf16 v[0:3], v[152:155], v[204:207], v[0:3]
	v_mfma_f32_16x16x32_bf16 v[56:59], v[148:151], v[184:187], v[56:59]
	v_mfma_f32_16x16x32_bf16 v[48:51], v[156:159], v[184:187], v[48:51]
	v_mfma_f32_16x16x32_bf16 v[40:43], v[148:151], v[192:195], v[40:43]
	v_mfma_f32_16x16x32_bf16 v[32:35], v[156:159], v[192:195], v[32:35]
	v_mfma_f32_16x16x32_bf16 v[24:27], v[148:151], v[200:203], v[24:27]
	v_mfma_f32_16x16x32_bf16 v[16:19], v[156:159], v[200:203], v[16:19]
	v_mfma_f32_16x16x32_bf16 v[8:11], v[148:151], v[208:211], v[8:11]
	v_mfma_f32_16x16x32_bf16 v[0:3], v[156:159], v[208:211], v[0:3]
	s_setprio 0
	s_barrier
	s_add_i32 s44, s44, 2
	s_add_u32 s4, s4, 0x100
	s_addc_u32 s5, s5, 0
	s_add_u32 s42, s42, 0x100
	s_addc_u32 s43, s43, 0
	s_cmp_gt_u32 s44, 13
	s_cbranch_scc0 .LBB0_92
	s_and_b64 vcc, exec, s[14:15]
	s_cbranch_vccz .LBB0_95
	s_barrier

; #define PG8_STAGE(bufoff, gbase, voff) do { _Pragma("unroll") for (int _i = 0; _i < 2; ++_i) \
;         __builtin_amdgcn_global_load_lds((const unsigned*)((const char*)(gbase) + (voff)[_i]), (PG8_LAS unsigned*)(lds + (bufoff) + ldsw + _i * 8192), 16, 0, 0); } while (0)
; #define PG8_LDA(dst, b, h) do { _Pragma("unroll") for (int m = 0; m < 4; ++m) _Pragma("unroll") for (int k = 0; k < 2; ++k) dst[m][k] = *(const PG8_LAS bf16x8*)(lds + PG8_SA(b, h) + aoff + m * 2048 + k * 1024); } while (0)
; #define PG8_LDB(dst, b, h) do { _Pragma("unroll") for (int n = 0; n < 2; ++n) _Pragma("unroll") for (int k = 0; k < 2; ++k) dst[n][k] = *(const PG8_LAS bf16x8*)(lds + PG8_SB(b, h) + boff + n * 2048 + k * 1024); } while (0)
; #define PG8_MMA(ai, bj, At, Bt) do { __builtin_amdgcn_s_setprio(1); _Pragma("unroll") for (int m = 0; m < 4; ++m) _Pragma("unroll") for (int n = 0; n < 2; ++n) _Pragma("unroll") for (int k = 0; k < 2; ++k) \
;         acc[ai][bj][m][n] = __builtin_amdgcn_mfma_f32_16x16x32_bf16(Bt[n][k], At[m][k], acc[ai][bj][m][n], 0, 0, 0); __builtin_amdgcn_s_setprio(0); } while (0)
; #define PG8_WAIT_V(n) asm volatile("s_waitcnt vmcnt(" #n ")" ::: "memory")
; #define PG8_WAIT_L(n) asm volatile("s_waitcnt lgkmcnt(" #n ")" ::: "memory")
; #define PG8_BAR __builtin_amdgcn_s_barrier()
; #define PG8_SCHED __builtin_amdgcn_sched_barrier(0)
; template <class Epi, class Sched, bool ALIGN_EPI, bool SP2, int KC>
; __device__ __forceinline__ void gemm_phase(PG8_LAS unsigned char* lds, const Gemm g, const Sched& S, const Epi& E, const int tid) {
;     ...
;             const bool last = (t == nt - 2);
;             const char* a1 = cA + (size_t)(t + 1) * kstep;
;             const char* a2 = last ? nA : cA + (size_t)(t + 2) * kstep; const char* b2 = last ? nB : cB + (size_t)(t + 2) * kstep;
;             const char* a3 = a2 + kstep; const char* b3 = b2 + kstep;
;             if (last && has_next) S.a_ready(nxt);
;             if constexpr (SP2) {
;             PG8_LDB(B0, 0, 0); PG8_LDB(B1, 0, 1); PG8_SCHED; PG8_LDA(At, 0, 0); PG8_STAGE(PG8_SA(1, 1), a1 + hstep, voffA);
;             PG8_WAIT_V(8); PG8_WAIT_L(0); PG8_BAR; PG8_MMA(0, 0, At, B0); PG8_MMA(0, 1, At, B1); PG8_BAR; PG8_SCHED;
;             PG8_LDA(At, 0, 1); PG8_STAGE(PG8_SB(0, 0), b2, voffB); PG8_STAGE(PG8_SB(0, 1), b2 + hstep, voffB); PG8_STAGE(PG8_SA(0, 0), a2, voffA);
.LBB0_116:
	s_add_u32 s24, s22, 0xfffc0080
	s_addc_u32 s25, s23, -1
	s_add_i32 s43, 0, 0x10000
	s_cmp_eq_u32 s42, 12
	s_cselect_b32 s27, s15, s25
	s_cselect_b32 s26, s38, s24
	s_cselect_b32 s25, s13, s41
	s_cselect_b32 s24, s39, s40
	s_add_i32 s46, 0, 0x14000
	v_add_u32_e32 v140, s43, v196
	v_add_u32_e32 v162, s46, v196
	ds_read_b128 v[128:131], v140
	ds_read_b128 v[132:135], v140 offset:1024
	ds_read_b128 v[136:139], v140 offset:2048
	ds_read_b128 v[140:143], v140 offset:3072
	ds_read_b128 v[154:157], v162
	ds_read_b128 v[158:161], v162 offset:1024
	ds_read_b128 v[174:177], v162 offset:2048
	ds_read_b128 v[178:181], v162 offset:3072
	v_lshl_add_u64 v[162:163], s[22:23], 0, v[150:151]
	s_add_i32 m0, s29, 0xc000
	ds_read_b128 v[182:185], v198
	ds_read_b128 v[186:189], v198 offset:1024
	ds_read_b128 v[190:193], v198 offset:2048
	ds_read_b128 v[200:203], v198 offset:3072
	ds_read_b128 v[204:207], v198 offset:4096
	ds_read_b128 v[208:211], v198 offset:5120
	ds_read_b128 v[212:215], v198 offset:6144
	ds_read_b128 v[216:219], v198 offset:7168
	global_load_lds_dwordx4 v[162:163], off
	v_lshl_add_u64 v[162:163], s[22:23], 0, v[152:153]
	s_add_i32 m0, s29, 0xe000
	s_nop 0
	global_load_lds_dwordx4 v[162:163], off
	s_waitcnt vmcnt(8)
	s_waitcnt lgkmcnt(0)
	s_barrier
	s_setprio 1
	s_waitcnt lgkmcnt(0)
	v_mfma_f32_16x16x32_bf16 v[124:127], v[128:131], v[182:185], v[124:127]
	v_mfma_f32_16x16x32_bf16 v[120:123], v[136:139], v[182:185], v[120:123]
	v_mfma_f32_16x16x32_bf16 v[116:119], v[128:131], v[190:193], v[116:119]
	v_mfma_f32_16x16x32_bf16 v[112:115], v[136:139], v[190:193], v[112:115]
	v_mfma_f32_16x16x32_bf16 v[108:111], v[128:131], v[204:207], v[108:111]
	v_mfma_f32_16x16x32_bf16 v[104:107], v[136:139], v[204:207], v[104:107]
	v_mfma_f32_16x16x32_bf16 v[100:103], v[128:131], v[212:215], v[100:103]
	v_mfma_f32_16x16x32_bf16 v[96:99], v[136:139], v[212:215], v[96:99]
	v_mfma_f32_16x16x32_bf16 v[124:127], v[132:135], v[186:189], v[124:127]
	v_mfma_f32_16x16x32_bf16 v[120:123], v[140:143], v[186:189], v[120:123]
	v_mfma_f32_16x16x32_bf16 v[116:119], v[132:135], v[200:203], v[116:119]
	v_mfma_f32_16x16x32_bf16 v[112:115], v[140:143], v[200:203], v[112:115]
	v_mfma_f32_16x16x32_bf16 v[108:111], v[132:135], v[208:211], v[108:111]
	v_mfma_f32_16x16x32_bf16 v[104:107], v[140:143], v[208:211], v[104:107]
	v_mfma_f32_16x16x32_bf16 v[100:103], v[132:135], v[216:219], v[100:103]
	v_mfma_f32_16x16x32_bf16 v[96:99], v[140:143], v[216:219], v[96:99]
	v_mfma_f32_16x16x32_bf16 v[68:71], v[154:157], v[182:185], v[68:71]
	v_mfma_f32_16x16x32_bf16 v[64:67], v[174:177], v[182:185], v[64:67]
	v_mfma_f32_16x16x32_bf16 v[52:55], v[154:157], v[190:193], v[52:55]
	v_mfma_f32_16x16x32_bf16 v[48:51], v[174:177], v[190:193], v[48:51]
	v_mfma_f32_16x16x32_bf16 v[44:47], v[154:157], v[204:207], v[44:47]
	v_mfma_f32_16x16x32_bf16 v[40:43], v[174:177], v[204:207], v[40:43]
	v_mfma_f32_16x16x32_bf16 v[36:39], v[154:157], v[212:215], v[36:39]
	v_mfma_f32_16x16x32_bf16 v[32:35], v[174:177], v[212:215], v[32:35]
	v_mfma_f32_16x16x32_bf16 v[68:71], v[158:161], v[186:189], v[68:71]
	v_mfma_f32_16x16x32_bf16 v[64:67], v[178:181], v[186:189], v[64:67]
	v_mfma_f32_16x16x32_bf16 v[52:55], v[158:161], v[200:203], v[52:55]
	v_mfma_f32_16x16x32_bf16 v[48:51], v[178:181], v[200:203], v[48:51]
	v_mfma_f32_16x16x32_bf16 v[44:47], v[158:161], v[208:211], v[44:47]
	v_mfma_f32_16x16x32_bf16 v[40:43], v[178:181], v[208:211], v[40:43]
	v_mfma_f32_16x16x32_bf16 v[36:39], v[158:161], v[216:219], v[36:39]
	v_mfma_f32_16x16x32_bf16 v[32:35], v[178:181], v[216:219], v[32:35]
	s_setprio 0
	s_barrier
	s_add_i32 s43, s43, s28
	v_lshl_add_u64 v[162:163], s[24:25], 0, v[164:165]
	s_mov_b32 m0, s43
	ds_read_b128 v[182:185], v198 offset:16384
	ds_read_b128 v[186:189], v198 offset:17408
	ds_read_b128 v[190:193], v198 offset:18432
	ds_read_b128 v[200:203], v198 offset:19456
	ds_read_b128 v[204:207], v198 offset:20480
	ds_read_b128 v[208:211], v198 offset:21504
	ds_read_b128 v[212:215], v198 offset:22528
	ds_read_b128 v[216:219], v198 offset:23552
	global_load_lds_dwordx4 v[162:163], off
	s_add_i32 m0, s43, 0x2000
	s_add_u32 s44, s24, 0x40000
	v_lshl_add_u64 v[194:195], s[24:25], 0, v[144:145]
	s_addc_u32 s45, s25, 0
	s_add_i32 s43, s46, s28
	global_load_lds_dwordx4 v[194:195], off
	v_lshl_add_u64 v[220:221], s[44:45], 0, v[164:165]
	s_mov_b32 m0, s43
	v_lshl_add_u64 v[222:223], s[26:27], 0, v[146:147]
	global_load_lds_dwordx4 v[220:221], off
	v_lshl_add_u64 v[220:221], s[44:45], 0, v[144:145]
	s_add_i32 m0, s43, 0x2000
	s_nop 0
	global_load_lds_dwordx4 v[220:221], off
	v_lshl_add_u64 v[220:221], s[26:27], 0, v[148:149]
	s_mov_b32 m0, s29
	s_nop 0
	global_load_lds_dwordx4 v[220:221], off
	s_mov_b32 m0, s30
	s_nop 0
	global_load_lds_dwordx4 v[222:223], off
	s_waitcnt vmcnt(8)
	s_waitcnt lgkmcnt(0)
	s_barrier
; #define PG8_STAGE(bufoff, gbase, voff) do { _Pragma("unroll") for (int _i = 0; _i < 2; ++_i) \
;         __builtin_amdgcn_global_load_lds((const unsigned*)((const char*)(gbase) + (voff)[_i]), (PG8_LAS unsigned*)(lds + (bufoff) + ldsw + _i * 8192), 16, 0, 0); } while (0)
; #define PG8_LDA(dst, b, h) do { _Pragma("unroll") for (int m = 0; m < 4; ++m) _Pragma("unroll") for (int k = 0; k < 2; ++k) dst[m][k] = *(const PG8_LAS bf16x8*)(lds + PG8_SA(b, h) + aoff + m * 2048 + k * 1024); } while (0)
; #define PG8_LDB(dst, b, h) do { _Pragma("unroll") for (int n = 0; n < 2; ++n) _Pragma("unroll") for (int k = 0; k < 2; ++k) dst[n][k] = *(const PG8_LAS bf16x8*)(lds + PG8_SB(b, h) + boff + n * 2048 + k * 1024); } while (0)
; #define PG8_MMA(ai, bj, At, Bt) do { __builtin_amdgcn_s_setprio(1); _Pragma("unroll") for (int m = 0; m < 4; ++m) _Pragma("unroll") for (int n = 0; n < 2; ++n) _Pragma("unroll") for (int k = 0; k < 2; ++k) \
;         acc[ai][bj][m][n] = __builtin_amdgcn_mfma_f32_16x16x32_bf16(Bt[n][k], At[m][k], acc[ai][bj][m][n], 0, 0, 0); __builtin_amdgcn_s_setprio(0); } while (0)
; #define PG8_WAIT_V(n) asm volatile("s_waitcnt vmcnt(" #n ")" ::: "memory")
; #define PG8_WAIT_L(n) asm volatile("s_waitcnt lgkmcnt(" #n ")" ::: "memory")
; #define PG8_BAR __builtin_amdgcn_s_barrier()
; #define PG8_SCHED __builtin_amdgcn_sched_barrier(0)
; template <class Epi, class Sched, bool ALIGN_EPI, bool SP2, int KC>
; __device__ __forceinline__ void gemm_phase(PG8_LAS unsigned char* lds, const Gemm g, const Sched& S, const Epi& E, const int tid) {
;     ...
;             PG8_WAIT_V(8); PG8_WAIT_L(0); PG8_BAR; PG8_MMA(1, 0, At, B0); PG8_MMA(1, 1, At, B1); PG8_BAR; PG8_SCHED;
;             PG8_LDB(B0, 1, 0); PG8_LDB(B1, 1, 1); PG8_SCHED; PG8_LDA(At, 1, 0); PG8_STAGE(PG8_SA(0, 1), a2 + hstep, voffA);
;             PG8_WAIT_V(8); PG8_WAIT_L(0); PG8_BAR; PG8_MMA(0, 0, At, B0); PG8_MMA(0, 1, At, B1); PG8_BAR; PG8_SCHED;
	s_setprio 1
	s_waitcnt lgkmcnt(0)
	v_mfma_f32_16x16x32_bf16 v[92:95], v[128:131], v[182:185], v[92:95]
	v_mfma_f32_16x16x32_bf16 v[88:91], v[136:139], v[182:185], v[88:91]
	v_mfma_f32_16x16x32_bf16 v[84:87], v[128:131], v[190:193], v[84:87]
	v_mfma_f32_16x16x32_bf16 v[80:83], v[136:139], v[190:193], v[80:83]
	v_mfma_f32_16x16x32_bf16 v[76:79], v[128:131], v[204:207], v[76:79]
	v_mfma_f32_16x16x32_bf16 v[72:75], v[136:139], v[204:207], v[72:75]
	v_mfma_f32_16x16x32_bf16 v[60:63], v[128:131], v[212:215], v[60:63]
	v_mfma_f32_16x16x32_bf16 v[56:59], v[136:139], v[212:215], v[56:59]
	v_mfma_f32_16x16x32_bf16 v[92:95], v[132:135], v[186:189], v[92:95]
	v_mfma_f32_16x16x32_bf16 v[88:91], v[140:143], v[186:189], v[88:91]
	v_mfma_f32_16x16x32_bf16 v[84:87], v[132:135], v[200:203], v[84:87]
	v_mfma_f32_16x16x32_bf16 v[80:83], v[140:143], v[200:203], v[80:83]
	v_mfma_f32_16x16x32_bf16 v[76:79], v[132:135], v[208:211], v[76:79]
	v_mfma_f32_16x16x32_bf16 v[72:75], v[140:143], v[208:211], v[72:75]
	v_mfma_f32_16x16x32_bf16 v[60:63], v[132:135], v[216:219], v[60:63]
	v_mfma_f32_16x16x32_bf16 v[56:59], v[140:143], v[216:219], v[56:59]
	v_mfma_f32_16x16x32_bf16 v[28:31], v[154:157], v[182:185], v[28:31]
	v_mfma_f32_16x16x32_bf16 v[24:27], v[174:177], v[182:185], v[24:27]
	v_mfma_f32_16x16x32_bf16 v[20:23], v[154:157], v[190:193], v[20:23]
	v_mfma_f32_16x16x32_bf16 v[16:19], v[174:177], v[190:193], v[16:19]
	v_mfma_f32_16x16x32_bf16 v[12:15], v[154:157], v[204:207], v[12:15]
	v_mfma_f32_16x16x32_bf16 v[8:11], v[174:177], v[204:207], v[8:11]
	v_mfma_f32_16x16x32_bf16 v[4:7], v[154:157], v[212:215], v[4:7]
	v_mfma_f32_16x16x32_bf16 v[0:3], v[174:177], v[212:215], v[0:3]
	v_mfma_f32_16x16x32_bf16 v[28:31], v[158:161], v[186:189], v[28:31]
	v_mfma_f32_16x16x32_bf16 v[24:27], v[178:181], v[186:189], v[24:27]
	v_mfma_f32_16x16x32_bf16 v[20:23], v[158:161], v[200:203], v[20:23]
	v_mfma_f32_16x16x32_bf16 v[16:19], v[178:181], v[200:203], v[16:19]
	v_mfma_f32_16x16x32_bf16 v[12:15], v[158:161], v[208:211], v[12:15]
	v_mfma_f32_16x16x32_bf16 v[8:11], v[178:181], v[208:211], v[8:11]
	v_mfma_f32_16x16x32_bf16 v[4:7], v[158:161], v[216:219], v[4:7]
	v_mfma_f32_16x16x32_bf16 v[0:3], v[178:181], v[216:219], v[0:3]
	s_setprio 0
	s_barrier
	s_add_i32 s43, 0, 0x18000
	s_add_i32 s44, 0, 0x1c000
	v_add_u32_e32 v140, s43, v196
	v_add_u32_e32 v178, s44, v196
	ds_read_b128 v[128:131], v140
	ds_read_b128 v[132:135], v140 offset:1024
	ds_read_b128 v[136:139], v140 offset:2048
	ds_read_b128 v[140:143], v140 offset:3072
	ds_read_b128 v[154:157], v178
	ds_read_b128 v[158:161], v178 offset:1024
	ds_read_b128 v[174:177], v178 offset:2048
	ds_read_b128 v[178:181], v178 offset:3072
	s_add_u32 s26, s26, 0x40000
	s_addc_u32 s27, s27, 0
	s_mov_b32 m0, s31
	v_lshl_add_u64 v[234:235], s[26:27], 0, v[148:149]
	ds_read_b128 v[182:185], v198 offset:32768
	ds_read_b128 v[186:189], v198 offset:33792
	ds_read_b128 v[190:193], v198 offset:34816
	ds_read_b128 v[200:203], v198 offset:35840
	ds_read_b128 v[204:207], v198 offset:36864
	ds_read_b128 v[208:211], v198 offset:37888
	ds_read_b128 v[212:215], v198 offset:38912
	ds_read_b128 v[216:219], v198 offset:39936
	global_load_lds_dwordx4 v[234:235], off
	v_lshl_add_u64 v[234:235], s[26:27], 0, v[146:147]
	s_mov_b32 m0, s34
	s_nop 0
	global_load_lds_dwordx4 v[234:235], off
	s_waitcnt vmcnt(8)
	s_waitcnt lgkmcnt(0)
	s_barrier
	s_setprio 1
	s_waitcnt lgkmcnt(0)
	v_mfma_f32_16x16x32_bf16 v[124:127], v[128:131], v[182:185], v[124:127]
	v_mfma_f32_16x16x32_bf16 v[120:123], v[136:139], v[182:185], v[120:123]
	v_mfma_f32_16x16x32_bf16 v[116:119], v[128:131], v[190:193], v[116:119]
	v_mfma_f32_16x16x32_bf16 v[112:115], v[136:139], v[190:193], v[112:115]
	v_mfma_f32_16x16x32_bf16 v[108:111], v[128:131], v[204:207], v[108:111]
	v_mfma_f32_16x16x32_bf16 v[104:107], v[136:139], v[204:207], v[104:107]
	v_mfma_f32_16x16x32_bf16 v[100:103], v[128:131], v[212:215], v[100:103]
	v_mfma_f32_16x16x32_bf16 v[96:99], v[136:139], v[212:215], v[96:99]
	v_mfma_f32_16x16x32_bf16 v[124:127], v[132:135], v[186:189], v[124:127]
	v_mfma_f32_16x16x32_bf16 v[120:123], v[140:143], v[186:189], v[120:123]
	v_mfma_f32_16x16x32_bf16 v[116:119], v[132:135], v[200:203], v[116:119]
	v_mfma_f32_16x16x32_bf16 v[112:115], v[140:143], v[200:203], v[112:115]
	v_mfma_f32_16x16x32_bf16 v[108:111], v[132:135], v[208:211], v[108:111]
	v_mfma_f32_16x16x32_bf16 v[104:107], v[140:143], v[208:211], v[104:107]
	v_mfma_f32_16x16x32_bf16 v[100:103], v[132:135], v[216:219], v[100:103]
	v_mfma_f32_16x16x32_bf16 v[96:99], v[140:143], v[216:219], v[96:99]
	v_mfma_f32_16x16x32_bf16 v[68:71], v[154:157], v[182:185], v[68:71]
	v_mfma_f32_16x16x32_bf16 v[64:67], v[174:177], v[182:185], v[64:67]
	v_mfma_f32_16x16x32_bf16 v[52:55], v[154:157], v[190:193], v[52:55]
	v_mfma_f32_16x16x32_bf16 v[48:51], v[174:177], v[190:193], v[48:51]
	v_mfma_f32_16x16x32_bf16 v[44:47], v[154:157], v[204:207], v[44:47]
	v_mfma_f32_16x16x32_bf16 v[40:43], v[174:177], v[204:207], v[40:43]
	v_mfma_f32_16x16x32_bf16 v[36:39], v[154:157], v[212:215], v[36:39]
	v_mfma_f32_16x16x32_bf16 v[32:35], v[174:177], v[212:215], v[32:35]
	v_mfma_f32_16x16x32_bf16 v[68:71], v[158:161], v[186:189], v[68:71]
	v_mfma_f32_16x16x32_bf16 v[64:67], v[178:181], v[186:189], v[64:67]
	v_mfma_f32_16x16x32_bf16 v[52:55], v[158:161], v[200:203], v[52:55]
	v_mfma_f32_16x16x32_bf16 v[48:51], v[178:181], v[200:203], v[48:51]
	v_mfma_f32_16x16x32_bf16 v[44:47], v[158:161], v[208:211], v[44:47]
	v_mfma_f32_16x16x32_bf16 v[40:43], v[178:181], v[208:211], v[40:43]
	v_mfma_f32_16x16x32_bf16 v[36:39], v[158:161], v[216:219], v[36:39]
	v_mfma_f32_16x16x32_bf16 v[32:35], v[178:181], v[216:219], v[32:35]
	s_setprio 0
	s_barrier
; #define PG8_STAGE(bufoff, gbase, voff) do { _Pragma("unroll") for (int _i = 0; _i < 2; ++_i) \
;         __builtin_amdgcn_global_load_lds((const unsigned*)((const char*)(gbase) + (voff)[_i]), (PG8_LAS unsigned*)(lds + (bufoff) + ldsw + _i * 8192), 16, 0, 0); } while (0)
; #define PG8_LDA(dst, b, h) do { _Pragma("unroll") for (int m = 0; m < 4; ++m) _Pragma("unroll") for (int k = 0; k < 2; ++k) dst[m][k] = *(const PG8_LAS bf16x8*)(lds + PG8_SA(b, h) + aoff + m * 2048 + k * 1024); } while (0)
; #define PG8_MMA(ai, bj, At, Bt) do { __builtin_amdgcn_s_setprio(1); _Pragma("unroll") for (int m = 0; m < 4; ++m) _Pragma("unroll") for (int n = 0; n < 2; ++n) _Pragma("unroll") for (int k = 0; k < 2; ++k) \
;         acc[ai][bj][m][n] = __builtin_amdgcn_mfma_f32_16x16x32_bf16(Bt[n][k], At[m][k], acc[ai][bj][m][n], 0, 0, 0); __builtin_amdgcn_s_setprio(0); } while (0)
; #define PG8_WAIT_V(n) asm volatile("s_waitcnt vmcnt(" #n ")" ::: "memory")
; #define PG8_WAIT_L(n) asm volatile("s_waitcnt lgkmcnt(" #n ")" ::: "memory")
; #define PG8_BAR __builtin_amdgcn_s_barrier()
; #define PG8_SCHED __builtin_amdgcn_sched_barrier(0)
; template <class Epi, class Sched, bool ALIGN_EPI, bool SP2, int KC>
; __device__ __forceinline__ void gemm_phase(PG8_LAS unsigned char* lds, const Gemm g, const Sched& S, const Epi& E, const int tid) {
;     ...
;             PG8_LDA(At, 1, 1); PG8_STAGE(PG8_SB(1, 0), b3, voffB); PG8_STAGE(PG8_SB(1, 1), b3 + hstep, voffB); PG8_STAGE(PG8_SA(1, 0), a3, voffA);
;             PG8_WAIT_V(8); PG8_WAIT_L(0); PG8_BAR; PG8_MMA(1, 0, At, B0); PG8_MMA(1, 1, At, B1); PG8_BAR; PG8_SCHED;
	s_add_i32 s26, s43, s28
	v_lshl_add_u64 v[162:163], v[162:163], 0, s[86:87]
	s_mov_b32 m0, s26
	ds_read_b128 v[182:185], v198 offset:49152
	ds_read_b128 v[186:189], v198 offset:50176
	ds_read_b128 v[190:193], v198 offset:51200
	ds_read_b128 v[200:203], v198 offset:52224
	ds_read_b128 v[204:207], v198 offset:53248
	ds_read_b128 v[208:211], v198 offset:54272
	ds_read_b128 v[212:215], v198 offset:55296
	ds_read_b128 v[216:219], v198 offset:56320
	global_load_lds_dwordx4 v[162:163], off
	s_add_i32 m0, s26, 0x2000
	s_add_u32 s24, s24, 0x40080
	v_lshl_add_u64 v[162:163], v[194:195], 0, s[86:87]
	s_addc_u32 s25, s25, 0
	s_add_i32 s26, s44, s28
	global_load_lds_dwordx4 v[162:163], off
	v_lshl_add_u64 v[162:163], s[24:25], 0, v[164:165]
	s_mov_b32 m0, s26
	s_nop 0
	global_load_lds_dwordx4 v[162:163], off
	v_lshl_add_u64 v[162:163], s[24:25], 0, v[144:145]
	s_add_i32 m0, s26, 0x2000
	s_nop 0
	global_load_lds_dwordx4 v[162:163], off
	v_lshl_add_u64 v[162:163], v[220:221], 0, s[86:87]
	s_mov_b32 m0, s35
	s_nop 0
	global_load_lds_dwordx4 v[162:163], off
	v_lshl_add_u64 v[162:163], v[222:223], 0, s[86:87]
	s_mov_b32 m0, s36
	s_nop 0
	global_load_lds_dwordx4 v[162:163], off
	s_waitcnt vmcnt(8)
	s_waitcnt lgkmcnt(0)
	s_barrier
	s_setprio 1
	s_waitcnt lgkmcnt(0)
	v_mfma_f32_16x16x32_bf16 v[92:95], v[128:131], v[182:185], v[92:95]
	v_mfma_f32_16x16x32_bf16 v[88:91], v[136:139], v[182:185], v[88:91]
	v_mfma_f32_16x16x32_bf16 v[84:87], v[128:131], v[190:193], v[84:87]
	v_mfma_f32_16x16x32_bf16 v[80:83], v[136:139], v[190:193], v[80:83]
	v_mfma_f32_16x16x32_bf16 v[76:79], v[128:131], v[204:207], v[76:79]
	v_mfma_f32_16x16x32_bf16 v[72:75], v[136:139], v[204:207], v[72:75]
	v_mfma_f32_16x16x32_bf16 v[60:63], v[128:131], v[212:215], v[60:63]
	v_mfma_f32_16x16x32_bf16 v[56:59], v[136:139], v[212:215], v[56:59]
	v_mfma_f32_16x16x32_bf16 v[92:95], v[132:135], v[186:189], v[92:95]
	v_mfma_f32_16x16x32_bf16 v[88:91], v[140:143], v[186:189], v[88:91]
	v_mfma_f32_16x16x32_bf16 v[84:87], v[132:135], v[200:203], v[84:87]
	v_mfma_f32_16x16x32_bf16 v[80:83], v[140:143], v[200:203], v[80:83]
	v_mfma_f32_16x16x32_bf16 v[76:79], v[132:135], v[208:211], v[76:79]
	v_mfma_f32_16x16x32_bf16 v[72:75], v[140:143], v[208:211], v[72:75]
	v_mfma_f32_16x16x32_bf16 v[60:63], v[132:135], v[216:219], v[60:63]
	v_mfma_f32_16x16x32_bf16 v[56:59], v[140:143], v[216:219], v[56:59]
	v_mfma_f32_16x16x32_bf16 v[28:31], v[154:157], v[182:185], v[28:31]
	v_mfma_f32_16x16x32_bf16 v[24:27], v[174:177], v[182:185], v[24:27]
	v_mfma_f32_16x16x32_bf16 v[20:23], v[154:157], v[190:193], v[20:23]
	v_mfma_f32_16x16x32_bf16 v[16:19], v[174:177], v[190:193], v[16:19]
	v_mfma_f32_16x16x32_bf16 v[12:15], v[154:157], v[204:207], v[12:15]
	v_mfma_f32_16x16x32_bf16 v[8:11], v[174:177], v[204:207], v[8:11]
	v_mfma_f32_16x16x32_bf16 v[4:7], v[154:157], v[212:215], v[4:7]
	v_mfma_f32_16x16x32_bf16 v[0:3], v[174:177], v[212:215], v[0:3]
	v_mfma_f32_16x16x32_bf16 v[28:31], v[158:161], v[186:189], v[28:31]
	v_mfma_f32_16x16x32_bf16 v[24:27], v[178:181], v[186:189], v[24:27]
	v_mfma_f32_16x16x32_bf16 v[20:23], v[158:161], v[200:203], v[20:23]
	v_mfma_f32_16x16x32_bf16 v[16:19], v[178:181], v[200:203], v[16:19]
	v_mfma_f32_16x16x32_bf16 v[12:15], v[158:161], v[208:211], v[12:15]
	v_mfma_f32_16x16x32_bf16 v[8:11], v[178:181], v[208:211], v[8:11]
	v_mfma_f32_16x16x32_bf16 v[4:7], v[158:161], v[216:219], v[4:7]
	v_mfma_f32_16x16x32_bf16 v[0:3], v[178:181], v[216:219], v[0:3]
	s_setprio 0
	s_barrier
	s_add_i32 s42, s42, 2
	s_add_u32 s22, s22, 0x100
	s_addc_u32 s23, s23, 0
	s_add_u32 s40, s40, 0x100
	s_addc_u32 s41, s41, 0
	s_cmp_gt_u32 s42, 13
	s_cbranch_scc0 .LBB0_116
	s_and_b64 vcc, exec, s[10:11]
	s_cbranch_vccz .LBB0_119
	s_barrier

; #define PG8_STAGE(bufoff, gbase, voff) do { _Pragma("unroll") for (int _i = 0; _i < 2; ++_i) \
;         __builtin_amdgcn_global_load_lds((const unsigned*)((const char*)(gbase) + (voff)[_i]), (PG8_LAS unsigned*)(lds + (bufoff) + ldsw + _i * 8192), 16, 0, 0); } while (0)
; #define PG8_LDA(dst, b, h) do { _Pragma("unroll") for (int m = 0; m < 4; ++m) _Pragma("unroll") for (int k = 0; k < 2; ++k) dst[m][k] = *(const PG8_LAS bf16x8*)(lds + PG8_SA(b, h) + aoff + m * 2048 + k * 1024); } while (0)
; #define PG8_LDB(dst, b, h) do { _Pragma("unroll") for (int n = 0; n < 2; ++n) _Pragma("unroll") for (int k = 0; k < 2; ++k) dst[n][k] = *(const PG8_LAS bf16x8*)(lds + PG8_SB(b, h) + boff + n * 2048 + k * 1024); } while (0)
; #define PG8_MMA(ai, bj, At, Bt) do { __builtin_amdgcn_s_setprio(1); _Pragma("unroll") for (int m = 0; m < 4; ++m) _Pragma("unroll") for (int n = 0; n < 2; ++n) _Pragma("unroll") for (int k = 0; k < 2; ++k) \
;         acc[ai][bj][m][n] = __builtin_amdgcn_mfma_f32_16x16x32_bf16(Bt[n][k], At[m][k], acc[ai][bj][m][n], 0, 0, 0); __builtin_amdgcn_s_setprio(0); } while (0)
; #define PG8_WAIT_V(n) asm volatile("s_waitcnt vmcnt(" #n ")" ::: "memory")
; #define PG8_WAIT_L(n) asm volatile("s_waitcnt lgkmcnt(" #n ")" ::: "memory")
; #define PG8_BAR __builtin_amdgcn_s_barrier()
; #define PG8_SCHED __builtin_amdgcn_sched_barrier(0)
; template <class Epi, class Sched, bool ALIGN_EPI, bool SP2, int KC>
; __device__ __forceinline__ void gemm_phase(PG8_LAS unsigned char* lds, const Gemm g, const Sched& S, const Epi& E, const int tid) {
;     ...
;             const bool last = (t == nt - 2);
;             const char* a1 = cA + (size_t)(t + 1) * kstep;
;             const char* a2 = last ? nA : cA + (size_t)(t + 2) * kstep; const char* b2 = last ? nB : cB + (size_t)(t + 2) * kstep;
;             const char* a3 = a2 + kstep; const char* b3 = b2 + kstep;
;             if (last && has_next) S.a_ready(nxt);
;             if constexpr (SP2) {
;             PG8_LDB(B0, 0, 0); PG8_LDB(B1, 0, 1); PG8_SCHED; PG8_LDA(At, 0, 0); PG8_STAGE(PG8_SA(1, 1), a1 + hstep, voffA);
;             PG8_WAIT_V(8); PG8_WAIT_L(0); PG8_BAR; PG8_MMA(0, 0, At, B0); PG8_MMA(0, 1, At, B1); PG8_BAR; PG8_SCHED;
;             PG8_LDA(At, 0, 1); PG8_STAGE(PG8_SB(0, 0), b2, voffB); PG8_STAGE(PG8_SB(0, 1), b2 + hstep, voffB); PG8_STAGE(PG8_SA(0, 0), a2, voffA);
.LBB0_162:
	s_add_u32 s16, s4, 0xfffc0080
	s_addc_u32 s17, s5, -1
	s_add_i32 s71, 0, 0x10000
	s_cmp_eq_u32 s70, 12
	s_cselect_b32 s19, s41, s17
	s_cselect_b32 s18, s47, s16
	s_cselect_b32 s17, s39, s65
	s_cselect_b32 s16, s49, s64
	s_add_i32 s79, 0, 0x14000
	v_add_u32_e32 v146, s71, v245
	v_add_u32_e32 v162, s79, v245
	ds_read_b128 v[128:131], v146
	ds_read_b128 v[132:135], v146 offset:1024
	ds_read_b128 v[136:139], v146 offset:2048
	ds_read_b128 v[146:149], v146 offset:3072
	ds_read_b128 v[150:153], v162
	ds_read_b128 v[154:157], v162 offset:1024
	ds_read_b128 v[158:161], v162 offset:2048
	ds_read_b128 v[174:177], v162 offset:3072
	v_lshl_add_u64 v[162:163], s[4:5], 0, v[142:143]
	s_add_i32 m0, s7, 0xc000
	ds_read_b128 v[178:181], v249
	ds_read_b128 v[182:185], v249 offset:1024
	ds_read_b128 v[186:189], v249 offset:2048
	ds_read_b128 v[190:193], v249 offset:3072
	ds_read_b128 v[194:197], v249 offset:4096
	ds_read_b128 v[198:201], v249 offset:5120
	ds_read_b128 v[202:205], v249 offset:6144
	ds_read_b128 v[206:209], v249 offset:7168
	global_load_lds_dwordx4 v[162:163], off
	v_lshl_add_u64 v[162:163], s[4:5], 0, v[144:145]
	s_add_i32 m0, s7, 0xe000
	s_nop 0
	global_load_lds_dwordx4 v[162:163], off
	s_waitcnt vmcnt(8)
	s_waitcnt lgkmcnt(0)
	s_barrier
	s_setprio 1
	s_waitcnt lgkmcnt(0)
	v_mfma_f32_16x16x32_bf16 v[124:127], v[128:131], v[178:181], v[124:127]
	v_mfma_f32_16x16x32_bf16 v[108:111], v[136:139], v[178:181], v[108:111]
	v_mfma_f32_16x16x32_bf16 v[120:123], v[128:131], v[186:189], v[120:123]
	v_mfma_f32_16x16x32_bf16 v[104:107], v[136:139], v[186:189], v[104:107]
	v_mfma_f32_16x16x32_bf16 v[116:119], v[128:131], v[194:197], v[116:119]
	v_mfma_f32_16x16x32_bf16 v[100:103], v[136:139], v[194:197], v[100:103]
	v_mfma_f32_16x16x32_bf16 v[112:115], v[128:131], v[202:205], v[112:115]
	v_mfma_f32_16x16x32_bf16 v[96:99], v[136:139], v[202:205], v[96:99]
	v_mfma_f32_16x16x32_bf16 v[124:127], v[132:135], v[182:185], v[124:127]
	v_mfma_f32_16x16x32_bf16 v[108:111], v[146:149], v[182:185], v[108:111]
	v_mfma_f32_16x16x32_bf16 v[120:123], v[132:135], v[190:193], v[120:123]
	v_mfma_f32_16x16x32_bf16 v[104:107], v[146:149], v[190:193], v[104:107]
	v_mfma_f32_16x16x32_bf16 v[116:119], v[132:135], v[198:201], v[116:119]
	v_mfma_f32_16x16x32_bf16 v[100:103], v[146:149], v[198:201], v[100:103]
	v_mfma_f32_16x16x32_bf16 v[112:115], v[132:135], v[206:209], v[112:115]
	v_mfma_f32_16x16x32_bf16 v[96:99], v[146:149], v[206:209], v[96:99]
	v_mfma_f32_16x16x32_bf16 v[92:95], v[150:153], v[178:181], v[92:95]
	v_mfma_f32_16x16x32_bf16 v[76:79], v[158:161], v[178:181], v[76:79]
	v_mfma_f32_16x16x32_bf16 v[88:91], v[150:153], v[186:189], v[88:91]
	v_mfma_f32_16x16x32_bf16 v[72:75], v[158:161], v[186:189], v[72:75]
	v_mfma_f32_16x16x32_bf16 v[84:87], v[150:153], v[194:197], v[84:87]
	v_mfma_f32_16x16x32_bf16 v[68:71], v[158:161], v[194:197], v[68:71]
	v_mfma_f32_16x16x32_bf16 v[80:83], v[150:153], v[202:205], v[80:83]
	v_mfma_f32_16x16x32_bf16 v[64:67], v[158:161], v[202:205], v[64:67]
	v_mfma_f32_16x16x32_bf16 v[92:95], v[154:157], v[182:185], v[92:95]
	v_mfma_f32_16x16x32_bf16 v[76:79], v[174:177], v[182:185], v[76:79]
	v_mfma_f32_16x16x32_bf16 v[88:91], v[154:157], v[190:193], v[88:91]
	v_mfma_f32_16x16x32_bf16 v[72:75], v[174:177], v[190:193], v[72:75]
	v_mfma_f32_16x16x32_bf16 v[84:87], v[154:157], v[198:201], v[84:87]
	v_mfma_f32_16x16x32_bf16 v[68:71], v[174:177], v[198:201], v[68:71]
	v_mfma_f32_16x16x32_bf16 v[80:83], v[154:157], v[206:209], v[80:83]
	v_mfma_f32_16x16x32_bf16 v[64:67], v[174:177], v[206:209], v[64:67]
	s_setprio 0
	s_barrier
	s_add_i32 s71, s71, s6
	v_lshl_add_u64 v[162:163], s[16:17], 0, v[164:165]
	s_mov_b32 m0, s71
	ds_read_b128 v[178:181], v249 offset:16384
	ds_read_b128 v[182:185], v249 offset:17408
	ds_read_b128 v[186:189], v249 offset:18432
	ds_read_b128 v[190:193], v249 offset:19456
	ds_read_b128 v[194:197], v249 offset:20480
	ds_read_b128 v[198:201], v249 offset:21504
	ds_read_b128 v[202:205], v249 offset:22528
	ds_read_b128 v[206:209], v249 offset:23552
	global_load_lds_dwordx4 v[162:163], off
	s_add_i32 m0, s71, 0x2000
	s_add_u32 s92, s16, 0x40000
	v_lshl_add_u64 v[210:211], s[16:17], 0, v[140:141]
	s_addc_u32 s93, s17, 0
	s_add_i32 s71, s79, s6
	global_load_lds_dwordx4 v[210:211], off
	v_lshl_add_u64 v[212:213], s[92:93], 0, v[164:165]
	s_mov_b32 m0, s71
	v_lshl_add_u64 v[214:215], s[18:19], 0, v[140:141]
	global_load_lds_dwordx4 v[212:213], off
	v_lshl_add_u64 v[212:213], s[92:93], 0, v[140:141]
	s_add_i32 m0, s71, 0x2000
	s_nop 0
	global_load_lds_dwordx4 v[212:213], off
	v_lshl_add_u64 v[212:213], s[18:19], 0, v[164:165]
	s_mov_b32 m0, s7
	s_nop 0
	global_load_lds_dwordx4 v[212:213], off
	s_mov_b32 m0, s58
	s_nop 0
	global_load_lds_dwordx4 v[214:215], off
	s_waitcnt vmcnt(8)
	s_waitcnt lgkmcnt(0)
	s_barrier
; #define PG8_STAGE(bufoff, gbase, voff) do { _Pragma("unroll") for (int _i = 0; _i < 2; ++_i) \
;         __builtin_amdgcn_global_load_lds((const unsigned*)((const char*)(gbase) + (voff)[_i]), (PG8_LAS unsigned*)(lds + (bufoff) + ldsw + _i * 8192), 16, 0, 0); } while (0)
; #define PG8_LDA(dst, b, h) do { _Pragma("unroll") for (int m = 0; m < 4; ++m) _Pragma("unroll") for (int k = 0; k < 2; ++k) dst[m][k] = *(const PG8_LAS bf16x8*)(lds + PG8_SA(b, h) + aoff + m * 2048 + k * 1024); } while (0)
; #define PG8_LDB(dst, b, h) do { _Pragma("unroll") for (int n = 0; n < 2; ++n) _Pragma("unroll") for (int k = 0; k < 2; ++k) dst[n][k] = *(const PG8_LAS bf16x8*)(lds + PG8_SB(b, h) + boff + n * 2048 + k * 1024); } while (0)
; #define PG8_MMA(ai, bj, At, Bt) do { __builtin_amdgcn_s_setprio(1); _Pragma("unroll") for (int m = 0; m < 4; ++m) _Pragma("unroll") for (int n = 0; n < 2; ++n) _Pragma("unroll") for (int k = 0; k < 2; ++k) \
;         acc[ai][bj][m][n] = __builtin_amdgcn_mfma_f32_16x16x32_bf16(Bt[n][k], At[m][k], acc[ai][bj][m][n], 0, 0, 0); __builtin_amdgcn_s_setprio(0); } while (0)
; #define PG8_WAIT_V(n) asm volatile("s_waitcnt vmcnt(" #n ")" ::: "memory")
; #define PG8_WAIT_L(n) asm volatile("s_waitcnt lgkmcnt(" #n ")" ::: "memory")
; #define PG8_BAR __builtin_amdgcn_s_barrier()
; #define PG8_SCHED __builtin_amdgcn_sched_barrier(0)
; template <class Epi, class Sched, bool ALIGN_EPI, bool SP2, int KC>
; __device__ __forceinline__ void gemm_phase(PG8_LAS unsigned char* lds, const Gemm g, const Sched& S, const Epi& E, const int tid) {
;     ...
;             PG8_WAIT_V(8); PG8_WAIT_L(0); PG8_BAR; PG8_MMA(1, 0, At, B0); PG8_MMA(1, 1, At, B1); PG8_BAR; PG8_SCHED;
;             PG8_LDB(B0, 1, 0); PG8_LDB(B1, 1, 1); PG8_SCHED; PG8_LDA(At, 1, 0); PG8_STAGE(PG8_SA(0, 1), a2 + hstep, voffA);
;             PG8_WAIT_V(8); PG8_WAIT_L(0); PG8_BAR; PG8_MMA(0, 0, At, B0); PG8_MMA(0, 1, At, B1); PG8_BAR; PG8_SCHED;
	s_setprio 1
	s_waitcnt lgkmcnt(0)
	v_mfma_f32_16x16x32_bf16 v[60:63], v[128:131], v[178:181], v[60:63]
	v_mfma_f32_16x16x32_bf16 v[44:47], v[136:139], v[178:181], v[44:47]
	v_mfma_f32_16x16x32_bf16 v[56:59], v[128:131], v[186:189], v[56:59]
	v_mfma_f32_16x16x32_bf16 v[40:43], v[136:139], v[186:189], v[40:43]
	v_mfma_f32_16x16x32_bf16 v[52:55], v[128:131], v[194:197], v[52:55]
	v_mfma_f32_16x16x32_bf16 v[36:39], v[136:139], v[194:197], v[36:39]
	v_mfma_f32_16x16x32_bf16 v[48:51], v[128:131], v[202:205], v[48:51]
	v_mfma_f32_16x16x32_bf16 v[32:35], v[136:139], v[202:205], v[32:35]
	v_mfma_f32_16x16x32_bf16 v[60:63], v[132:135], v[182:185], v[60:63]
	v_mfma_f32_16x16x32_bf16 v[44:47], v[146:149], v[182:185], v[44:47]
	v_mfma_f32_16x16x32_bf16 v[56:59], v[132:135], v[190:193], v[56:59]
	v_mfma_f32_16x16x32_bf16 v[40:43], v[146:149], v[190:193], v[40:43]
	v_mfma_f32_16x16x32_bf16 v[52:55], v[132:135], v[198:201], v[52:55]
	v_mfma_f32_16x16x32_bf16 v[36:39], v[146:149], v[198:201], v[36:39]
	v_mfma_f32_16x16x32_bf16 v[48:51], v[132:135], v[206:209], v[48:51]
	v_mfma_f32_16x16x32_bf16 v[32:35], v[146:149], v[206:209], v[32:35]
	v_mfma_f32_16x16x32_bf16 v[28:31], v[150:153], v[178:181], v[28:31]
	v_mfma_f32_16x16x32_bf16 v[12:15], v[158:161], v[178:181], v[12:15]
	v_mfma_f32_16x16x32_bf16 v[24:27], v[150:153], v[186:189], v[24:27]
	v_mfma_f32_16x16x32_bf16 v[8:11], v[158:161], v[186:189], v[8:11]
	v_mfma_f32_16x16x32_bf16 v[20:23], v[150:153], v[194:197], v[20:23]
	v_mfma_f32_16x16x32_bf16 v[4:7], v[158:161], v[194:197], v[4:7]
	v_mfma_f32_16x16x32_bf16 v[16:19], v[150:153], v[202:205], v[16:19]
	v_mfma_f32_16x16x32_bf16 v[0:3], v[158:161], v[202:205], v[0:3]
	v_mfma_f32_16x16x32_bf16 v[28:31], v[154:157], v[182:185], v[28:31]
	v_mfma_f32_16x16x32_bf16 v[12:15], v[174:177], v[182:185], v[12:15]
	v_mfma_f32_16x16x32_bf16 v[24:27], v[154:157], v[190:193], v[24:27]
	v_mfma_f32_16x16x32_bf16 v[8:11], v[174:177], v[190:193], v[8:11]
	v_mfma_f32_16x16x32_bf16 v[20:23], v[154:157], v[198:201], v[20:23]
	v_mfma_f32_16x16x32_bf16 v[4:7], v[174:177], v[198:201], v[4:7]
	v_mfma_f32_16x16x32_bf16 v[16:19], v[154:157], v[206:209], v[16:19]
	v_mfma_f32_16x16x32_bf16 v[0:3], v[174:177], v[206:209], v[0:3]
	s_setprio 0
	s_barrier
	s_add_i32 s71, 0, 0x18000
	s_add_i32 s79, 0, 0x1c000
	v_add_u32_e32 v146, s71, v245
	v_add_u32_e32 v174, s79, v245
	ds_read_b128 v[128:131], v146
	ds_read_b128 v[132:135], v146 offset:1024
	ds_read_b128 v[136:139], v146 offset:2048
	ds_read_b128 v[146:149], v146 offset:3072
	ds_read_b128 v[150:153], v174
	ds_read_b128 v[154:157], v174 offset:1024
	ds_read_b128 v[158:161], v174 offset:2048
	ds_read_b128 v[174:177], v174 offset:3072
	s_add_u32 s18, s18, 0x40000
	s_addc_u32 s19, s19, 0
	s_mov_b32 m0, s59
	v_lshl_add_u64 v[216:217], s[18:19], 0, v[164:165]
	ds_read_b128 v[178:181], v249 offset:32768
	ds_read_b128 v[182:185], v249 offset:33792
	ds_read_b128 v[186:189], v249 offset:34816
	ds_read_b128 v[190:193], v249 offset:35840
	ds_read_b128 v[194:197], v249 offset:36864
	ds_read_b128 v[198:201], v249 offset:37888
	ds_read_b128 v[202:205], v249 offset:38912
	ds_read_b128 v[206:209], v249 offset:39936
	global_load_lds_dwordx4 v[216:217], off
	v_lshl_add_u64 v[216:217], s[18:19], 0, v[140:141]
	s_mov_b32 m0, s74
	s_nop 0
	global_load_lds_dwordx4 v[216:217], off
	s_waitcnt vmcnt(8)
	s_waitcnt lgkmcnt(0)
	s_barrier
	s_setprio 1
	s_waitcnt lgkmcnt(0)
	v_mfma_f32_16x16x32_bf16 v[124:127], v[128:131], v[178:181], v[124:127]
	v_mfma_f32_16x16x32_bf16 v[108:111], v[136:139], v[178:181], v[108:111]
	v_mfma_f32_16x16x32_bf16 v[120:123], v[128:131], v[186:189], v[120:123]
	v_mfma_f32_16x16x32_bf16 v[104:107], v[136:139], v[186:189], v[104:107]
	v_mfma_f32_16x16x32_bf16 v[116:119], v[128:131], v[194:197], v[116:119]
	v_mfma_f32_16x16x32_bf16 v[100:103], v[136:139], v[194:197], v[100:103]
	v_mfma_f32_16x16x32_bf16 v[112:115], v[128:131], v[202:205], v[112:115]
	v_mfma_f32_16x16x32_bf16 v[96:99], v[136:139], v[202:205], v[96:99]
	v_mfma_f32_16x16x32_bf16 v[124:127], v[132:135], v[182:185], v[124:127]
	v_mfma_f32_16x16x32_bf16 v[108:111], v[146:149], v[182:185], v[108:111]
	v_mfma_f32_16x16x32_bf16 v[120:123], v[132:135], v[190:193], v[120:123]
	v_mfma_f32_16x16x32_bf16 v[104:107], v[146:149], v[190:193], v[104:107]
	v_mfma_f32_16x16x32_bf16 v[116:119], v[132:135], v[198:201], v[116:119]
	v_mfma_f32_16x16x32_bf16 v[100:103], v[146:149], v[198:201], v[100:103]
	v_mfma_f32_16x16x32_bf16 v[112:115], v[132:135], v[206:209], v[112:115]
	v_mfma_f32_16x16x32_bf16 v[96:99], v[146:149], v[206:209], v[96:99]
	v_mfma_f32_16x16x32_bf16 v[92:95], v[150:153], v[178:181], v[92:95]
	v_mfma_f32_16x16x32_bf16 v[76:79], v[158:161], v[178:181], v[76:79]
	v_mfma_f32_16x16x32_bf16 v[88:91], v[150:153], v[186:189], v[88:91]
	v_mfma_f32_16x16x32_bf16 v[72:75], v[158:161], v[186:189], v[72:75]
	v_mfma_f32_16x16x32_bf16 v[84:87], v[150:153], v[194:197], v[84:87]
	v_mfma_f32_16x16x32_bf16 v[68:71], v[158:161], v[194:197], v[68:71]
	v_mfma_f32_16x16x32_bf16 v[80:83], v[150:153], v[202:205], v[80:83]
	v_mfma_f32_16x16x32_bf16 v[64:67], v[158:161], v[202:205], v[64:67]
	v_mfma_f32_16x16x32_bf16 v[92:95], v[154:157], v[182:185], v[92:95]
	v_mfma_f32_16x16x32_bf16 v[76:79], v[174:177], v[182:185], v[76:79]
	v_mfma_f32_16x16x32_bf16 v[88:91], v[154:157], v[190:193], v[88:91]
	v_mfma_f32_16x16x32_bf16 v[72:75], v[174:177], v[190:193], v[72:75]
	v_mfma_f32_16x16x32_bf16 v[84:87], v[154:157], v[198:201], v[84:87]
	v_mfma_f32_16x16x32_bf16 v[68:71], v[174:177], v[198:201], v[68:71]
	v_mfma_f32_16x16x32_bf16 v[80:83], v[154:157], v[206:209], v[80:83]
	v_mfma_f32_16x16x32_bf16 v[64:67], v[174:177], v[206:209], v[64:67]
	s_setprio 0
	s_barrier
; #define PG8_STAGE(bufoff, gbase, voff) do { _Pragma("unroll") for (int _i = 0; _i < 2; ++_i) \
;         __builtin_amdgcn_global_load_lds((const unsigned*)((const char*)(gbase) + (voff)[_i]), (PG8_LAS unsigned*)(lds + (bufoff) + ldsw + _i * 8192), 16, 0, 0); } while (0)
; #define PG8_LDA(dst, b, h) do { _Pragma("unroll") for (int m = 0; m < 4; ++m) _Pragma("unroll") for (int k = 0; k < 2; ++k) dst[m][k] = *(const PG8_LAS bf16x8*)(lds + PG8_SA(b, h) + aoff + m * 2048 + k * 1024); } while (0)
; #define PG8_MMA(ai, bj, At, Bt) do { __builtin_amdgcn_s_setprio(1); _Pragma("unroll") for (int m = 0; m < 4; ++m) _Pragma("unroll") for (int n = 0; n < 2; ++n) _Pragma("unroll") for (int k = 0; k < 2; ++k) \
;         acc[ai][bj][m][n] = __builtin_amdgcn_mfma_f32_16x16x32_bf16(Bt[n][k], At[m][k], acc[ai][bj][m][n], 0, 0, 0); __builtin_amdgcn_s_setprio(0); } while (0)
; #define PG8_WAIT_V(n) asm volatile("s_waitcnt vmcnt(" #n ")" ::: "memory")
; #define PG8_WAIT_L(n) asm volatile("s_waitcnt lgkmcnt(" #n ")" ::: "memory")
; #define PG8_BAR __builtin_amdgcn_s_barrier()
; #define PG8_SCHED __builtin_amdgcn_sched_barrier(0)
; template <class Epi, class Sched, bool ALIGN_EPI, bool SP2, int KC>
; __device__ __forceinline__ void gemm_phase(PG8_LAS unsigned char* lds, const Gemm g, const Sched& S, const Epi& E, const int tid) {
;     ...
;             PG8_LDA(At, 1, 1); PG8_STAGE(PG8_SB(1, 0), b3, voffB); PG8_STAGE(PG8_SB(1, 1), b3 + hstep, voffB); PG8_STAGE(PG8_SA(1, 0), a3, voffA);
;             PG8_WAIT_V(8); PG8_WAIT_L(0); PG8_BAR; PG8_MMA(1, 0, At, B0); PG8_MMA(1, 1, At, B1); PG8_BAR; PG8_SCHED;
	s_add_i32 s18, s71, s6
	v_lshl_add_u64 v[162:163], v[162:163], 0, s[86:87]
	s_mov_b32 m0, s18
	ds_read_b128 v[178:181], v249 offset:49152
	ds_read_b128 v[182:185], v249 offset:50176
	ds_read_b128 v[186:189], v249 offset:51200
	ds_read_b128 v[190:193], v249 offset:52224
	ds_read_b128 v[194:197], v249 offset:53248
	ds_read_b128 v[198:201], v249 offset:54272
	ds_read_b128 v[202:205], v249 offset:55296
	ds_read_b128 v[206:209], v249 offset:56320
	global_load_lds_dwordx4 v[162:163], off
	s_add_i32 m0, s18, 0x2000
	s_add_u32 s16, s16, 0x40080
	v_lshl_add_u64 v[162:163], v[210:211], 0, s[86:87]
	s_addc_u32 s17, s17, 0
	s_add_i32 s18, s79, s6
	global_load_lds_dwordx4 v[162:163], off
	v_lshl_add_u64 v[162:163], s[16:17], 0, v[164:165]
	s_mov_b32 m0, s18
	s_nop 0
	global_load_lds_dwordx4 v[162:163], off
	v_lshl_add_u64 v[162:163], s[16:17], 0, v[140:141]
	s_add_i32 m0, s18, 0x2000
	s_nop 0
	global_load_lds_dwordx4 v[162:163], off
	v_lshl_add_u64 v[162:163], v[212:213], 0, s[86:87]
	s_mov_b32 m0, s76
	s_nop 0
	global_load_lds_dwordx4 v[162:163], off
	v_lshl_add_u64 v[162:163], v[214:215], 0, s[86:87]
	s_mov_b32 m0, s77
	s_nop 0
	global_load_lds_dwordx4 v[162:163], off
	s_waitcnt vmcnt(8)
	s_waitcnt lgkmcnt(0)
	s_barrier
	s_setprio 1
	s_waitcnt lgkmcnt(0)
	v_mfma_f32_16x16x32_bf16 v[60:63], v[128:131], v[178:181], v[60:63]
	v_mfma_f32_16x16x32_bf16 v[44:47], v[136:139], v[178:181], v[44:47]
	v_mfma_f32_16x16x32_bf16 v[56:59], v[128:131], v[186:189], v[56:59]
	v_mfma_f32_16x16x32_bf16 v[40:43], v[136:139], v[186:189], v[40:43]
	v_mfma_f32_16x16x32_bf16 v[52:55], v[128:131], v[194:197], v[52:55]
	v_mfma_f32_16x16x32_bf16 v[36:39], v[136:139], v[194:197], v[36:39]
	v_mfma_f32_16x16x32_bf16 v[48:51], v[128:131], v[202:205], v[48:51]
	v_mfma_f32_16x16x32_bf16 v[32:35], v[136:139], v[202:205], v[32:35]
	v_mfma_f32_16x16x32_bf16 v[60:63], v[132:135], v[182:185], v[60:63]
	v_mfma_f32_16x16x32_bf16 v[44:47], v[146:149], v[182:185], v[44:47]
	v_mfma_f32_16x16x32_bf16 v[56:59], v[132:135], v[190:193], v[56:59]
	v_mfma_f32_16x16x32_bf16 v[40:43], v[146:149], v[190:193], v[40:43]
	v_mfma_f32_16x16x32_bf16 v[52:55], v[132:135], v[198:201], v[52:55]
	v_mfma_f32_16x16x32_bf16 v[36:39], v[146:149], v[198:201], v[36:39]
	v_mfma_f32_16x16x32_bf16 v[48:51], v[132:135], v[206:209], v[48:51]
	v_mfma_f32_16x16x32_bf16 v[32:35], v[146:149], v[206:209], v[32:35]
	v_mfma_f32_16x16x32_bf16 v[28:31], v[150:153], v[178:181], v[28:31]
	v_mfma_f32_16x16x32_bf16 v[12:15], v[158:161], v[178:181], v[12:15]
	v_mfma_f32_16x16x32_bf16 v[24:27], v[150:153], v[186:189], v[24:27]
	v_mfma_f32_16x16x32_bf16 v[8:11], v[158:161], v[186:189], v[8:11]
	v_mfma_f32_16x16x32_bf16 v[20:23], v[150:153], v[194:197], v[20:23]
	v_mfma_f32_16x16x32_bf16 v[4:7], v[158:161], v[194:197], v[4:7]
	v_mfma_f32_16x16x32_bf16 v[16:19], v[150:153], v[202:205], v[16:19]
	v_mfma_f32_16x16x32_bf16 v[0:3], v[158:161], v[202:205], v[0:3]
	v_mfma_f32_16x16x32_bf16 v[28:31], v[154:157], v[182:185], v[28:31]
	v_mfma_f32_16x16x32_bf16 v[12:15], v[174:177], v[182:185], v[12:15]
	v_mfma_f32_16x16x32_bf16 v[24:27], v[154:157], v[190:193], v[24:27]
	v_mfma_f32_16x16x32_bf16 v[8:11], v[174:177], v[190:193], v[8:11]
	v_mfma_f32_16x16x32_bf16 v[20:23], v[154:157], v[198:201], v[20:23]
	v_mfma_f32_16x16x32_bf16 v[4:7], v[174:177], v[198:201], v[4:7]
	v_mfma_f32_16x16x32_bf16 v[16:19], v[154:157], v[206:209], v[16:19]
	v_mfma_f32_16x16x32_bf16 v[0:3], v[174:177], v[206:209], v[0:3]
	s_setprio 0
	s_barrier
	s_add_i32 s70, s70, 2
	s_add_u32 s4, s4, 0x100
	s_addc_u32 s5, s5, 0
	s_add_u32 s64, s64, 0x100
	s_addc_u32 s65, s65, 0
	s_cmp_gt_u32 s70, 13
	s_cbranch_scc0 .LBB0_162
	s_and_b64 vcc, exec, s[30:31]
	s_cbranch_vccz .LBB0_165
	s_barrier

; #define PG8_STAGE(bufoff, gbase, voff) do { _Pragma("unroll") for (int _i = 0; _i < 2; ++_i) \
;         __builtin_amdgcn_global_load_lds((const unsigned*)((const char*)(gbase) + (voff)[_i]), (PG8_LAS unsigned*)(lds + (bufoff) + ldsw + _i * 8192), 16, 0, 0); } while (0)
; #define PG8_LDA(dst, b, h) do { _Pragma("unroll") for (int m = 0; m < 4; ++m) _Pragma("unroll") for (int k = 0; k < 2; ++k) dst[m][k] = *(const PG8_LAS bf16x8*)(lds + PG8_SA(b, h) + aoff + m * 2048 + k * 1024); } while (0)
; #define PG8_LDB(dst, b, h) do { _Pragma("unroll") for (int n = 0; n < 2; ++n) _Pragma("unroll") for (int k = 0; k < 2; ++k) dst[n][k] = *(const PG8_LAS bf16x8*)(lds + PG8_SB(b, h) + boff + n * 2048 + k * 1024); } while (0)
; #define PG8_MMA(ai, bj, At, Bt) do { __builtin_amdgcn_s_setprio(1); _Pragma("unroll") for (int m = 0; m < 4; ++m) _Pragma("unroll") for (int n = 0; n < 2; ++n) _Pragma("unroll") for (int k = 0; k < 2; ++k) \
;         acc[ai][bj][m][n] = __builtin_amdgcn_mfma_f32_16x16x32_bf16(Bt[n][k], At[m][k], acc[ai][bj][m][n], 0, 0, 0); __builtin_amdgcn_s_setprio(0); } while (0)
; #define PG8_WAIT_V(n) asm volatile("s_waitcnt vmcnt(" #n ")" ::: "memory")
; #define PG8_WAIT_L(n) asm volatile("s_waitcnt lgkmcnt(" #n ")" ::: "memory")
; #define PG8_BAR __builtin_amdgcn_s_barrier()
; #define PG8_SCHED __builtin_amdgcn_sched_barrier(0)
; template <class Epi, class Sched, bool ALIGN_EPI, bool SP2, int KC>
; __device__ __forceinline__ void gemm_phase(PG8_LAS unsigned char* lds, const Gemm g, const Sched& S, const Epi& E, const int tid) {
;     ...
;             const bool last = (t == nt - 2);
;             const char* a1 = cA + (size_t)(t + 1) * kstep;
;             const char* a2 = last ? nA : cA + (size_t)(t + 2) * kstep; const char* b2 = last ? nB : cB + (size_t)(t + 2) * kstep;
;             const char* a3 = a2 + kstep; const char* b3 = b2 + kstep;
;             if (last && has_next) S.a_ready(nxt);
;             if constexpr (SP2) {
;             PG8_LDB(B0, 0, 0); PG8_LDB(B1, 0, 1); PG8_SCHED; PG8_LDA(At, 0, 0); PG8_STAGE(PG8_SA(1, 1), a1 + hstep, voffA);
;             PG8_WAIT_V(8); PG8_WAIT_L(0); PG8_BAR; PG8_MMA(0, 0, At, B0); PG8_MMA(0, 1, At, B1); PG8_BAR; PG8_SCHED;
;             PG8_LDA(At, 0, 1); PG8_STAGE(PG8_SB(0, 0), b2, voffB); PG8_STAGE(PG8_SB(0, 1), b2 + hstep, voffB); PG8_STAGE(PG8_SA(0, 0), a2, voffA);
.LBB0_560:
	s_add_u32 s16, s4, 0x100
	s_addc_u32 s17, s5, 0
	s_add_i32 s49, 0, 0x10000
	s_cmp_eq_u32 s48, 40
	s_cselect_b32 s39, s27, s17
	s_cselect_b32 s38, s26, s16
	s_cselect_b32 s37, s29, s35
	s_cselect_b32 s36, s28, s31
	s_add_i32 s58, 0, 0x14000
	v_add_u32_e32 v146, s49, v212
	v_add_u32_e32 v162, s58, v212
	ds_read_b128 v[128:131], v146
	ds_read_b128 v[132:135], v146 offset:1024
	ds_read_b128 v[142:145], v146 offset:2048
	ds_read_b128 v[146:149], v146 offset:3072
	ds_read_b128 v[150:153], v162
	ds_read_b128 v[154:157], v162 offset:1024
	ds_read_b128 v[158:161], v162 offset:2048
	ds_read_b128 v[174:177], v162 offset:3072
	v_lshl_add_u64 v[162:163], s[4:5], 0, v[138:139]
	s_add_i32 m0, s7, 0xc000
	ds_read_b128 v[178:181], v216
	ds_read_b128 v[182:185], v216 offset:1024
	ds_read_b128 v[186:189], v216 offset:2048
	ds_read_b128 v[190:193], v216 offset:3072
	ds_read_b128 v[194:197], v216 offset:4096
	ds_read_b128 v[198:201], v216 offset:5120
	ds_read_b128 v[202:205], v216 offset:6144
	ds_read_b128 v[206:209], v216 offset:7168
	global_load_lds_dwordx4 v[162:163], off
	v_lshl_add_u64 v[162:163], s[4:5], 0, v[140:141]
	s_add_i32 m0, s7, 0xe000
	s_nop 0
	global_load_lds_dwordx4 v[162:163], off
	s_waitcnt vmcnt(8)
	s_waitcnt lgkmcnt(0)
	s_barrier
	s_setprio 1
	s_waitcnt lgkmcnt(0)
	v_mfma_f32_16x16x32_bf16 v[60:63], v[128:131], v[178:181], v[60:63]
	v_mfma_f32_16x16x32_bf16 v[92:95], v[142:145], v[178:181], v[92:95]
	v_mfma_f32_16x16x32_bf16 v[56:59], v[128:131], v[186:189], v[56:59]
	v_mfma_f32_16x16x32_bf16 v[84:87], v[142:145], v[186:189], v[84:87]
	v_mfma_f32_16x16x32_bf16 v[48:51], v[128:131], v[194:197], v[48:51]
	v_mfma_f32_16x16x32_bf16 v[80:83], v[142:145], v[194:197], v[80:83]
	v_mfma_f32_16x16x32_bf16 v[40:43], v[128:131], v[202:205], v[40:43]
	v_mfma_f32_16x16x32_bf16 v[72:75], v[142:145], v[202:205], v[72:75]
	v_mfma_f32_16x16x32_bf16 v[60:63], v[132:135], v[182:185], v[60:63]
	v_mfma_f32_16x16x32_bf16 v[92:95], v[146:149], v[182:185], v[92:95]
	v_mfma_f32_16x16x32_bf16 v[56:59], v[132:135], v[190:193], v[56:59]
	v_mfma_f32_16x16x32_bf16 v[84:87], v[146:149], v[190:193], v[84:87]
	v_mfma_f32_16x16x32_bf16 v[48:51], v[132:135], v[198:201], v[48:51]
	v_mfma_f32_16x16x32_bf16 v[80:83], v[146:149], v[198:201], v[80:83]
	v_mfma_f32_16x16x32_bf16 v[40:43], v[132:135], v[206:209], v[40:43]
	v_mfma_f32_16x16x32_bf16 v[72:75], v[146:149], v[206:209], v[72:75]
	v_mfma_f32_16x16x32_bf16 v[120:123], v[150:153], v[178:181], v[120:123]
	v_mfma_f32_16x16x32_bf16 v[124:127], v[158:161], v[178:181], v[124:127]
	v_mfma_f32_16x16x32_bf16 v[112:115], v[150:153], v[186:189], v[112:115]
	v_mfma_f32_16x16x32_bf16 v[116:119], v[158:161], v[186:189], v[116:119]
	v_mfma_f32_16x16x32_bf16 v[108:111], v[150:153], v[194:197], v[108:111]
	v_mfma_f32_16x16x32_bf16 v[104:107], v[158:161], v[194:197], v[104:107]
	v_mfma_f32_16x16x32_bf16 v[100:103], v[150:153], v[202:205], v[100:103]
	v_mfma_f32_16x16x32_bf16 v[96:99], v[158:161], v[202:205], v[96:99]
	v_mfma_f32_16x16x32_bf16 v[120:123], v[154:157], v[182:185], v[120:123]
	v_mfma_f32_16x16x32_bf16 v[124:127], v[174:177], v[182:185], v[124:127]
	v_mfma_f32_16x16x32_bf16 v[112:115], v[154:157], v[190:193], v[112:115]
	v_mfma_f32_16x16x32_bf16 v[116:119], v[174:177], v[190:193], v[116:119]
	v_mfma_f32_16x16x32_bf16 v[108:111], v[154:157], v[198:201], v[108:111]
	v_mfma_f32_16x16x32_bf16 v[104:107], v[174:177], v[198:201], v[104:107]
	v_mfma_f32_16x16x32_bf16 v[100:103], v[154:157], v[206:209], v[100:103]
	v_mfma_f32_16x16x32_bf16 v[96:99], v[174:177], v[206:209], v[96:99]
	s_setprio 0
	s_barrier
	s_add_i32 s4, s49, s6
	v_lshl_add_u64 v[162:163], s[36:37], 0, v[164:165]
	s_mov_b32 m0, s4
	ds_read_b128 v[178:181], v216 offset:16384
	ds_read_b128 v[182:185], v216 offset:17408
	ds_read_b128 v[186:189], v216 offset:18432
	ds_read_b128 v[190:193], v216 offset:19456
	ds_read_b128 v[194:197], v216 offset:20480
	ds_read_b128 v[198:201], v216 offset:21504
	ds_read_b128 v[202:205], v216 offset:22528
	ds_read_b128 v[206:209], v216 offset:23552
	global_load_lds_dwordx4 v[162:163], off
	s_add_i32 m0, s4, 0x2000
	s_add_u32 s4, s36, 0xb0000
	v_lshl_add_u64 v[210:211], s[36:37], 0, v[136:137]
	s_addc_u32 s5, s37, 0
	s_add_i32 s49, s58, s6
	global_load_lds_dwordx4 v[210:211], off
	v_lshl_add_u64 v[220:221], s[4:5], 0, v[164:165]
	s_mov_b32 m0, s49
	v_lshl_add_u64 v[222:223], s[38:39], 0, v[136:137]
	global_load_lds_dwordx4 v[220:221], off
	v_lshl_add_u64 v[220:221], s[4:5], 0, v[136:137]
	s_add_i32 m0, s49, 0x2000
	s_nop 0
	global_load_lds_dwordx4 v[220:221], off
	v_lshl_add_u64 v[220:221], s[38:39], 0, v[164:165]
	s_mov_b32 m0, s7
	s_nop 0
	global_load_lds_dwordx4 v[220:221], off
	s_mov_b32 m0, s40
	s_nop 0
	global_load_lds_dwordx4 v[222:223], off
	s_waitcnt vmcnt(8)
	s_waitcnt lgkmcnt(0)
	s_barrier
; #define PG8_STAGE(bufoff, gbase, voff) do { _Pragma("unroll") for (int _i = 0; _i < 2; ++_i) \
;         __builtin_amdgcn_global_load_lds((const unsigned*)((const char*)(gbase) + (voff)[_i]), (PG8_LAS unsigned*)(lds + (bufoff) + ldsw + _i * 8192), 16, 0, 0); } while (0)
; #define PG8_LDA(dst, b, h) do { _Pragma("unroll") for (int m = 0; m < 4; ++m) _Pragma("unroll") for (int k = 0; k < 2; ++k) dst[m][k] = *(const PG8_LAS bf16x8*)(lds + PG8_SA(b, h) + aoff + m * 2048 + k * 1024); } while (0)
; #define PG8_LDB(dst, b, h) do { _Pragma("unroll") for (int n = 0; n < 2; ++n) _Pragma("unroll") for (int k = 0; k < 2; ++k) dst[n][k] = *(const PG8_LAS bf16x8*)(lds + PG8_SB(b, h) + boff + n * 2048 + k * 1024); } while (0)
; #define PG8_MMA(ai, bj, At, Bt) do { __builtin_amdgcn_s_setprio(1); _Pragma("unroll") for (int m = 0; m < 4; ++m) _Pragma("unroll") for (int n = 0; n < 2; ++n) _Pragma("unroll") for (int k = 0; k < 2; ++k) \
;         acc[ai][bj][m][n] = __builtin_amdgcn_mfma_f32_16x16x32_bf16(Bt[n][k], At[m][k], acc[ai][bj][m][n], 0, 0, 0); __builtin_amdgcn_s_setprio(0); } while (0)
; #define PG8_WAIT_V(n) asm volatile("s_waitcnt vmcnt(" #n ")" ::: "memory")
; #define PG8_WAIT_L(n) asm volatile("s_waitcnt lgkmcnt(" #n ")" ::: "memory")
; #define PG8_BAR __builtin_amdgcn_s_barrier()
; #define PG8_SCHED __builtin_amdgcn_sched_barrier(0)
; template <class Epi, class Sched, bool ALIGN_EPI, bool SP2, int KC>
; __device__ __forceinline__ void gemm_phase(PG8_LAS unsigned char* lds, const Gemm g, const Sched& S, const Epi& E, const int tid) {
;     ...
;             PG8_WAIT_V(8); PG8_WAIT_L(0); PG8_BAR; PG8_MMA(1, 0, At, B0); PG8_MMA(1, 1, At, B1); PG8_BAR; PG8_SCHED;
;             PG8_LDB(B0, 1, 0); PG8_LDB(B1, 1, 1); PG8_SCHED; PG8_LDA(At, 1, 0); PG8_STAGE(PG8_SA(0, 1), a2 + hstep, voffA);
;             PG8_WAIT_V(8); PG8_WAIT_L(0); PG8_BAR; PG8_MMA(0, 0, At, B0); PG8_MMA(0, 1, At, B1); PG8_BAR; PG8_SCHED;
	s_setprio 1
	s_waitcnt lgkmcnt(0)
	v_mfma_f32_16x16x32_bf16 v[88:91], v[128:131], v[178:181], v[88:91]
	v_mfma_f32_16x16x32_bf16 v[52:55], v[142:145], v[178:181], v[52:55]
	v_mfma_f32_16x16x32_bf16 v[76:79], v[128:131], v[186:189], v[76:79]
	v_mfma_f32_16x16x32_bf16 v[44:47], v[142:145], v[186:189], v[44:47]
	v_mfma_f32_16x16x32_bf16 v[68:71], v[128:131], v[194:197], v[68:71]
	v_mfma_f32_16x16x32_bf16 v[36:39], v[142:145], v[194:197], v[36:39]
	v_mfma_f32_16x16x32_bf16 v[64:67], v[128:131], v[202:205], v[64:67]
	v_mfma_f32_16x16x32_bf16 v[32:35], v[142:145], v[202:205], v[32:35]
	v_mfma_f32_16x16x32_bf16 v[88:91], v[132:135], v[182:185], v[88:91]
	v_mfma_f32_16x16x32_bf16 v[52:55], v[146:149], v[182:185], v[52:55]
	v_mfma_f32_16x16x32_bf16 v[76:79], v[132:135], v[190:193], v[76:79]
	v_mfma_f32_16x16x32_bf16 v[44:47], v[146:149], v[190:193], v[44:47]
	v_mfma_f32_16x16x32_bf16 v[68:71], v[132:135], v[198:201], v[68:71]
	v_mfma_f32_16x16x32_bf16 v[36:39], v[146:149], v[198:201], v[36:39]
	v_mfma_f32_16x16x32_bf16 v[64:67], v[132:135], v[206:209], v[64:67]
	v_mfma_f32_16x16x32_bf16 v[32:35], v[146:149], v[206:209], v[32:35]
	v_mfma_f32_16x16x32_bf16 v[28:31], v[150:153], v[178:181], v[28:31]
	v_mfma_f32_16x16x32_bf16 v[12:15], v[158:161], v[178:181], v[12:15]
	v_mfma_f32_16x16x32_bf16 v[24:27], v[150:153], v[186:189], v[24:27]
	v_mfma_f32_16x16x32_bf16 v[8:11], v[158:161], v[186:189], v[8:11]
	v_mfma_f32_16x16x32_bf16 v[20:23], v[150:153], v[194:197], v[20:23]
	v_mfma_f32_16x16x32_bf16 v[4:7], v[158:161], v[194:197], v[4:7]
	v_mfma_f32_16x16x32_bf16 v[16:19], v[150:153], v[202:205], v[16:19]
	v_mfma_f32_16x16x32_bf16 v[0:3], v[158:161], v[202:205], v[0:3]
	v_mfma_f32_16x16x32_bf16 v[28:31], v[154:157], v[182:185], v[28:31]
	v_mfma_f32_16x16x32_bf16 v[12:15], v[174:177], v[182:185], v[12:15]
	v_mfma_f32_16x16x32_bf16 v[24:27], v[154:157], v[190:193], v[24:27]
	v_mfma_f32_16x16x32_bf16 v[8:11], v[174:177], v[190:193], v[8:11]
	v_mfma_f32_16x16x32_bf16 v[20:23], v[154:157], v[198:201], v[20:23]
	v_mfma_f32_16x16x32_bf16 v[4:7], v[174:177], v[198:201], v[4:7]
	v_mfma_f32_16x16x32_bf16 v[16:19], v[154:157], v[206:209], v[16:19]
	v_mfma_f32_16x16x32_bf16 v[0:3], v[174:177], v[206:209], v[0:3]
	s_setprio 0
	s_barrier
	s_add_i32 s49, 0, 0x18000
	s_add_i32 s58, 0, 0x1c000
	v_add_u32_e32 v146, s49, v212
	v_add_u32_e32 v174, s58, v212
	ds_read_b128 v[128:131], v146
	ds_read_b128 v[132:135], v146 offset:1024
	ds_read_b128 v[142:145], v146 offset:2048
	ds_read_b128 v[146:149], v146 offset:3072
	ds_read_b128 v[150:153], v174
	ds_read_b128 v[154:157], v174 offset:1024
	ds_read_b128 v[158:161], v174 offset:2048
	ds_read_b128 v[174:177], v174 offset:3072
	s_add_u32 s4, s38, 0xb0000
	s_addc_u32 s5, s39, 0
	s_mov_b32 m0, s41
	v_lshl_add_u64 v[234:235], s[4:5], 0, v[164:165]
	ds_read_b128 v[178:181], v216 offset:32768
	ds_read_b128 v[182:185], v216 offset:33792
	ds_read_b128 v[186:189], v216 offset:34816
	ds_read_b128 v[190:193], v216 offset:35840
	ds_read_b128 v[194:197], v216 offset:36864
	ds_read_b128 v[198:201], v216 offset:37888
	ds_read_b128 v[202:205], v216 offset:38912
	ds_read_b128 v[206:209], v216 offset:39936
	global_load_lds_dwordx4 v[234:235], off
	v_lshl_add_u64 v[234:235], s[4:5], 0, v[136:137]
	s_mov_b32 m0, s42
	s_nop 0
	global_load_lds_dwordx4 v[234:235], off
	s_waitcnt vmcnt(8)
	s_waitcnt lgkmcnt(0)
	s_barrier
	s_setprio 1
	s_waitcnt lgkmcnt(0)
	v_mfma_f32_16x16x32_bf16 v[60:63], v[128:131], v[178:181], v[60:63]
	v_mfma_f32_16x16x32_bf16 v[92:95], v[142:145], v[178:181], v[92:95]
	v_mfma_f32_16x16x32_bf16 v[56:59], v[128:131], v[186:189], v[56:59]
	v_mfma_f32_16x16x32_bf16 v[84:87], v[142:145], v[186:189], v[84:87]
	v_mfma_f32_16x16x32_bf16 v[48:51], v[128:131], v[194:197], v[48:51]
	v_mfma_f32_16x16x32_bf16 v[80:83], v[142:145], v[194:197], v[80:83]
	v_mfma_f32_16x16x32_bf16 v[40:43], v[128:131], v[202:205], v[40:43]
	v_mfma_f32_16x16x32_bf16 v[72:75], v[142:145], v[202:205], v[72:75]
	v_mfma_f32_16x16x32_bf16 v[60:63], v[132:135], v[182:185], v[60:63]
	v_mfma_f32_16x16x32_bf16 v[92:95], v[146:149], v[182:185], v[92:95]
	v_mfma_f32_16x16x32_bf16 v[56:59], v[132:135], v[190:193], v[56:59]
	v_mfma_f32_16x16x32_bf16 v[84:87], v[146:149], v[190:193], v[84:87]
	v_mfma_f32_16x16x32_bf16 v[48:51], v[132:135], v[198:201], v[48:51]
	v_mfma_f32_16x16x32_bf16 v[80:83], v[146:149], v[198:201], v[80:83]
	v_mfma_f32_16x16x32_bf16 v[40:43], v[132:135], v[206:209], v[40:43]
	v_mfma_f32_16x16x32_bf16 v[72:75], v[146:149], v[206:209], v[72:75]
	v_mfma_f32_16x16x32_bf16 v[120:123], v[150:153], v[178:181], v[120:123]
	v_mfma_f32_16x16x32_bf16 v[124:127], v[158:161], v[178:181], v[124:127]
	v_mfma_f32_16x16x32_bf16 v[112:115], v[150:153], v[186:189], v[112:115]
	v_mfma_f32_16x16x32_bf16 v[116:119], v[158:161], v[186:189], v[116:119]
	v_mfma_f32_16x16x32_bf16 v[108:111], v[150:153], v[194:197], v[108:111]
	v_mfma_f32_16x16x32_bf16 v[104:107], v[158:161], v[194:197], v[104:107]
	v_mfma_f32_16x16x32_bf16 v[100:103], v[150:153], v[202:205], v[100:103]
	v_mfma_f32_16x16x32_bf16 v[96:99], v[158:161], v[202:205], v[96:99]
	v_mfma_f32_16x16x32_bf16 v[120:123], v[154:157], v[182:185], v[120:123]
	v_mfma_f32_16x16x32_bf16 v[124:127], v[174:177], v[182:185], v[124:127]
	v_mfma_f32_16x16x32_bf16 v[112:115], v[154:157], v[190:193], v[112:115]
	v_mfma_f32_16x16x32_bf16 v[116:119], v[174:177], v[190:193], v[116:119]
	v_mfma_f32_16x16x32_bf16 v[108:111], v[154:157], v[198:201], v[108:111]
	v_mfma_f32_16x16x32_bf16 v[104:107], v[174:177], v[198:201], v[104:107]
	v_mfma_f32_16x16x32_bf16 v[100:103], v[154:157], v[206:209], v[100:103]
	v_mfma_f32_16x16x32_bf16 v[96:99], v[174:177], v[206:209], v[96:99]
	s_setprio 0
	s_barrier
; #define PG8_STAGE(bufoff, gbase, voff) do { _Pragma("unroll") for (int _i = 0; _i < 2; ++_i) \
;         __builtin_amdgcn_global_load_lds((const unsigned*)((const char*)(gbase) + (voff)[_i]), (PG8_LAS unsigned*)(lds + (bufoff) + ldsw + _i * 8192), 16, 0, 0); } while (0)
; #define PG8_LDA(dst, b, h) do { _Pragma("unroll") for (int m = 0; m < 4; ++m) _Pragma("unroll") for (int k = 0; k < 2; ++k) dst[m][k] = *(const PG8_LAS bf16x8*)(lds + PG8_SA(b, h) + aoff + m * 2048 + k * 1024); } while (0)
; #define PG8_MMA(ai, bj, At, Bt) do { __builtin_amdgcn_s_setprio(1); _Pragma("unroll") for (int m = 0; m < 4; ++m) _Pragma("unroll") for (int n = 0; n < 2; ++n) _Pragma("unroll") for (int k = 0; k < 2; ++k) \
;         acc[ai][bj][m][n] = __builtin_amdgcn_mfma_f32_16x16x32_bf16(Bt[n][k], At[m][k], acc[ai][bj][m][n], 0, 0, 0); __builtin_amdgcn_s_setprio(0); } while (0)
; #define PG8_WAIT_V(n) asm volatile("s_waitcnt vmcnt(" #n ")" ::: "memory")
; #define PG8_WAIT_L(n) asm volatile("s_waitcnt lgkmcnt(" #n ")" ::: "memory")
; #define PG8_BAR __builtin_amdgcn_s_barrier()
; #define PG8_SCHED __builtin_amdgcn_sched_barrier(0)
; template <class Epi, class Sched, bool ALIGN_EPI, bool SP2, int KC>
; __device__ __forceinline__ void gemm_phase(PG8_LAS unsigned char* lds, const Gemm g, const Sched& S, const Epi& E, const int tid) {
;     ...
;             PG8_LDA(At, 1, 1); PG8_STAGE(PG8_SB(1, 0), b3, voffB); PG8_STAGE(PG8_SB(1, 1), b3 + hstep, voffB); PG8_STAGE(PG8_SA(1, 0), a3, voffA);
;             PG8_WAIT_V(8); PG8_WAIT_L(0); PG8_BAR; PG8_MMA(1, 0, At, B0); PG8_MMA(1, 1, At, B1); PG8_BAR; PG8_SCHED;
	s_add_i32 s4, s49, s6
	v_lshl_add_u64 v[162:163], v[162:163], 0, s[86:87]
	s_mov_b32 m0, s4
	ds_read_b128 v[178:181], v216 offset:49152
	ds_read_b128 v[182:185], v216 offset:50176
	ds_read_b128 v[186:189], v216 offset:51200
	ds_read_b128 v[190:193], v216 offset:52224
	ds_read_b128 v[194:197], v216 offset:53248
	ds_read_b128 v[198:201], v216 offset:54272
	ds_read_b128 v[202:205], v216 offset:55296
	ds_read_b128 v[206:209], v216 offset:56320
	global_load_lds_dwordx4 v[162:163], off
	s_add_i32 m0, s4, 0x2000
	s_add_u32 s4, s36, 0xb0080
	v_lshl_add_u64 v[162:163], v[210:211], 0, s[86:87]
	s_addc_u32 s5, s37, 0
	s_add_i32 s36, s58, s6
	global_load_lds_dwordx4 v[162:163], off
	v_lshl_add_u64 v[162:163], s[4:5], 0, v[164:165]
	s_mov_b32 m0, s36
	s_nop 0
	global_load_lds_dwordx4 v[162:163], off
	v_lshl_add_u64 v[162:163], s[4:5], 0, v[136:137]
	s_add_i32 m0, s36, 0x2000
	s_nop 0
	global_load_lds_dwordx4 v[162:163], off
	v_lshl_add_u64 v[162:163], v[220:221], 0, s[86:87]
	s_mov_b32 m0, s43
	s_nop 0
	global_load_lds_dwordx4 v[162:163], off
	v_lshl_add_u64 v[162:163], v[222:223], 0, s[86:87]
	s_mov_b32 m0, s44
	s_nop 0
	global_load_lds_dwordx4 v[162:163], off
	s_waitcnt vmcnt(8)
	s_waitcnt lgkmcnt(0)
	s_barrier
	s_setprio 1
	s_waitcnt lgkmcnt(0)
	v_mfma_f32_16x16x32_bf16 v[88:91], v[128:131], v[178:181], v[88:91]
	v_mfma_f32_16x16x32_bf16 v[52:55], v[142:145], v[178:181], v[52:55]
	v_mfma_f32_16x16x32_bf16 v[76:79], v[128:131], v[186:189], v[76:79]
	v_mfma_f32_16x16x32_bf16 v[44:47], v[142:145], v[186:189], v[44:47]
	v_mfma_f32_16x16x32_bf16 v[68:71], v[128:131], v[194:197], v[68:71]
	v_mfma_f32_16x16x32_bf16 v[36:39], v[142:145], v[194:197], v[36:39]
	v_mfma_f32_16x16x32_bf16 v[64:67], v[128:131], v[202:205], v[64:67]
	v_mfma_f32_16x16x32_bf16 v[32:35], v[142:145], v[202:205], v[32:35]
	v_mfma_f32_16x16x32_bf16 v[88:91], v[132:135], v[182:185], v[88:91]
	v_mfma_f32_16x16x32_bf16 v[52:55], v[146:149], v[182:185], v[52:55]
	v_mfma_f32_16x16x32_bf16 v[76:79], v[132:135], v[190:193], v[76:79]
	v_mfma_f32_16x16x32_bf16 v[44:47], v[146:149], v[190:193], v[44:47]
	v_mfma_f32_16x16x32_bf16 v[68:71], v[132:135], v[198:201], v[68:71]
	v_mfma_f32_16x16x32_bf16 v[36:39], v[146:149], v[198:201], v[36:39]
	v_mfma_f32_16x16x32_bf16 v[64:67], v[132:135], v[206:209], v[64:67]
	v_mfma_f32_16x16x32_bf16 v[32:35], v[146:149], v[206:209], v[32:35]
	v_mfma_f32_16x16x32_bf16 v[28:31], v[150:153], v[178:181], v[28:31]
	v_mfma_f32_16x16x32_bf16 v[12:15], v[158:161], v[178:181], v[12:15]
	v_mfma_f32_16x16x32_bf16 v[24:27], v[150:153], v[186:189], v[24:27]
	v_mfma_f32_16x16x32_bf16 v[8:11], v[158:161], v[186:189], v[8:11]
	v_mfma_f32_16x16x32_bf16 v[20:23], v[150:153], v[194:197], v[20:23]
	v_mfma_f32_16x16x32_bf16 v[4:7], v[158:161], v[194:197], v[4:7]
	v_mfma_f32_16x16x32_bf16 v[16:19], v[150:153], v[202:205], v[16:19]
	v_mfma_f32_16x16x32_bf16 v[0:3], v[158:161], v[202:205], v[0:3]
	v_mfma_f32_16x16x32_bf16 v[28:31], v[154:157], v[182:185], v[28:31]
	v_mfma_f32_16x16x32_bf16 v[12:15], v[174:177], v[182:185], v[12:15]
	v_mfma_f32_16x16x32_bf16 v[24:27], v[154:157], v[190:193], v[24:27]
	v_mfma_f32_16x16x32_bf16 v[8:11], v[174:177], v[190:193], v[8:11]
	v_mfma_f32_16x16x32_bf16 v[20:23], v[154:157], v[198:201], v[20:23]
	v_mfma_f32_16x16x32_bf16 v[4:7], v[174:177], v[198:201], v[4:7]
	v_mfma_f32_16x16x32_bf16 v[16:19], v[154:157], v[206:209], v[16:19]
	v_mfma_f32_16x16x32_bf16 v[0:3], v[174:177], v[206:209], v[0:3]
	s_setprio 0
	s_barrier
	s_add_i32 s48, s48, 2
	s_add_u32 s31, s31, 0x100
	s_addc_u32 s35, s35, 0
	s_cmp_gt_u32 s48, 41
	s_mov_b64 s[4:5], s[16:17]
	s_cbranch_scc0 .LBB0_560
	s_and_b64 vcc, exec, s[24:25]
	s_cbranch_vccz .LBB0_563
	s_barrier

; #define PG8_STAGE(bufoff, gbase, voff) do { _Pragma("unroll") for (int _i = 0; _i < 2; ++_i) \
;         __builtin_amdgcn_global_load_lds((const unsigned*)((const char*)(gbase) + (voff)[_i]), (PG8_LAS unsigned*)(lds + (bufoff) + ldsw + _i * 8192), 16, 0, 0); } while (0)
; #define PG8_LDA(dst, b, h) do { _Pragma("unroll") for (int m = 0; m < 4; ++m) _Pragma("unroll") for (int k = 0; k < 2; ++k) dst[m][k] = *(const PG8_LAS bf16x8*)(lds + PG8_SA(b, h) + aoff + m * 2048 + k * 1024); } while (0)
; #define PG8_LDB(dst, b, h) do { _Pragma("unroll") for (int n = 0; n < 2; ++n) _Pragma("unroll") for (int k = 0; k < 2; ++k) dst[n][k] = *(const PG8_LAS bf16x8*)(lds + PG8_SB(b, h) + boff + n * 2048 + k * 1024); } while (0)
; #define PG8_MMA(ai, bj, At, Bt) do { __builtin_amdgcn_s_setprio(1); _Pragma("unroll") for (int m = 0; m < 4; ++m) _Pragma("unroll") for (int n = 0; n < 2; ++n) _Pragma("unroll") for (int k = 0; k < 2; ++k) \
;         acc[ai][bj][m][n] = __builtin_amdgcn_mfma_f32_16x16x32_bf16(Bt[n][k], At[m][k], acc[ai][bj][m][n], 0, 0, 0); __builtin_amdgcn_s_setprio(0); } while (0)
; #define PG8_WAIT_V(n) asm volatile("s_waitcnt vmcnt(" #n ")" ::: "memory")
; #define PG8_WAIT_L(n) asm volatile("s_waitcnt lgkmcnt(" #n ")" ::: "memory")
; #define PG8_BAR __builtin_amdgcn_s_barrier()
; #define PG8_SCHED __builtin_amdgcn_sched_barrier(0)
; template <class Epi, class Sched, bool ALIGN_EPI, bool SP2, int KC>
; __device__ __forceinline__ void gemm_phase(PG8_LAS unsigned char* lds, const Gemm g, const Sched& S, const Epi& E, const int tid) {
;     ...
;             const bool last = (t == nt - 2);
;             const char* a1 = cA + (size_t)(t + 1) * kstep;
;             const char* a2 = last ? nA : cA + (size_t)(t + 2) * kstep; const char* b2 = last ? nB : cB + (size_t)(t + 2) * kstep;
;             const char* a3 = a2 + kstep; const char* b3 = b2 + kstep;
;             if (last && has_next) S.a_ready(nxt);
;             if constexpr (SP2) {
;             PG8_LDB(B0, 0, 0); PG8_LDB(B1, 0, 1); PG8_SCHED; PG8_LDA(At, 0, 0); PG8_STAGE(PG8_SA(1, 1), a1 + hstep, voffA);
;             PG8_WAIT_V(8); PG8_WAIT_L(0); PG8_BAR; PG8_MMA(0, 0, At, B0); PG8_MMA(0, 1, At, B1); PG8_BAR; PG8_SCHED;
;             PG8_LDA(At, 0, 1); PG8_STAGE(PG8_SB(0, 0), b2, voffB); PG8_STAGE(PG8_SB(0, 1), b2 + hstep, voffB); PG8_STAGE(PG8_SA(0, 0), a2, voffA);
.LBB0_730:
	s_add_u32 s22, s4, 0xfffc0080
	s_addc_u32 s23, s5, -1
	s_add_i32 s41, 0, 0x10000
	s_cmp_eq_u32 s40, 12
	s_cselect_b32 s25, s17, s23
	s_cselect_b32 s24, s36, s22
	s_cselect_b32 s23, s15, s39
	s_cselect_b32 s22, s37, s38
	s_add_i32 s44, 0, 0x14000
	v_add_u32_e32 v140, s41, v223
	v_add_u32_e32 v156, s44, v223
	ds_read_b128 v[128:131], v140
	ds_read_b128 v[132:135], v140 offset:1024
	ds_read_b128 v[136:139], v140 offset:2048
	ds_read_b128 v[140:143], v140 offset:3072
	ds_read_b128 v[144:147], v156
	ds_read_b128 v[148:151], v156 offset:1024
	ds_read_b128 v[152:155], v156 offset:2048
	ds_read_b128 v[156:159], v156 offset:3072
	v_lshl_add_u64 v[214:215], s[4:5], 0, v[182:183]
	s_add_i32 m0, s7, 0xc000
	ds_read_b128 v[160:163], v234
	s_waitcnt vmcnt(0)
	ds_read_b128 v[186:189], v234 offset:1024
	ds_read_b128 v[190:193], v234 offset:2048
	ds_read_b128 v[194:197], v234 offset:3072
	ds_read_b128 v[198:201], v234 offset:4096
	ds_read_b128 v[202:205], v234 offset:5120
	ds_read_b128 v[206:209], v234 offset:6144
	ds_read_b128 v[210:213], v234 offset:7168
	global_load_lds_dwordx4 v[214:215], off
	v_lshl_add_u64 v[214:215], s[4:5], 0, v[184:185]
	s_add_i32 m0, s7, 0xe000
	s_nop 0
	global_load_lds_dwordx4 v[214:215], off
	s_waitcnt vmcnt(8)
	s_waitcnt lgkmcnt(0)
	s_barrier
	s_setprio 1
	s_waitcnt lgkmcnt(0)
	v_mfma_f32_16x16x32_bf16 v[124:127], v[128:131], v[160:163], v[124:127]
	v_mfma_f32_16x16x32_bf16 v[120:123], v[136:139], v[160:163], v[120:123]
	v_mfma_f32_16x16x32_bf16 v[116:119], v[128:131], v[190:193], v[116:119]
	v_mfma_f32_16x16x32_bf16 v[112:115], v[136:139], v[190:193], v[112:115]
	v_mfma_f32_16x16x32_bf16 v[108:111], v[128:131], v[198:201], v[108:111]
	v_mfma_f32_16x16x32_bf16 v[104:107], v[136:139], v[198:201], v[104:107]
	v_mfma_f32_16x16x32_bf16 v[100:103], v[128:131], v[206:209], v[100:103]
	v_mfma_f32_16x16x32_bf16 v[96:99], v[136:139], v[206:209], v[96:99]
	v_mfma_f32_16x16x32_bf16 v[124:127], v[132:135], v[186:189], v[124:127]
	v_mfma_f32_16x16x32_bf16 v[120:123], v[140:143], v[186:189], v[120:123]
	v_mfma_f32_16x16x32_bf16 v[116:119], v[132:135], v[194:197], v[116:119]
	v_mfma_f32_16x16x32_bf16 v[112:115], v[140:143], v[194:197], v[112:115]
	v_mfma_f32_16x16x32_bf16 v[108:111], v[132:135], v[202:205], v[108:111]
	v_mfma_f32_16x16x32_bf16 v[104:107], v[140:143], v[202:205], v[104:107]
	v_mfma_f32_16x16x32_bf16 v[100:103], v[132:135], v[210:213], v[100:103]
	v_mfma_f32_16x16x32_bf16 v[96:99], v[140:143], v[210:213], v[96:99]
	v_mfma_f32_16x16x32_bf16 v[68:71], v[144:147], v[160:163], v[68:71]
	v_mfma_f32_16x16x32_bf16 v[56:59], v[152:155], v[160:163], v[56:59]
	v_mfma_f32_16x16x32_bf16 v[52:55], v[144:147], v[190:193], v[52:55]
	v_mfma_f32_16x16x32_bf16 v[48:51], v[152:155], v[190:193], v[48:51]
	v_mfma_f32_16x16x32_bf16 v[44:47], v[144:147], v[198:201], v[44:47]
	v_mfma_f32_16x16x32_bf16 v[40:43], v[152:155], v[198:201], v[40:43]
	v_mfma_f32_16x16x32_bf16 v[36:39], v[144:147], v[206:209], v[36:39]
	v_mfma_f32_16x16x32_bf16 v[32:35], v[152:155], v[206:209], v[32:35]
	v_mfma_f32_16x16x32_bf16 v[68:71], v[148:151], v[186:189], v[68:71]
	v_mfma_f32_16x16x32_bf16 v[56:59], v[156:159], v[186:189], v[56:59]
	v_mfma_f32_16x16x32_bf16 v[52:55], v[148:151], v[194:197], v[52:55]
	v_mfma_f32_16x16x32_bf16 v[48:51], v[156:159], v[194:197], v[48:51]
	v_mfma_f32_16x16x32_bf16 v[44:47], v[148:151], v[202:205], v[44:47]
	v_mfma_f32_16x16x32_bf16 v[40:43], v[156:159], v[202:205], v[40:43]
	v_mfma_f32_16x16x32_bf16 v[36:39], v[148:151], v[210:213], v[36:39]
	v_mfma_f32_16x16x32_bf16 v[32:35], v[156:159], v[210:213], v[32:35]
	s_setprio 0
	s_barrier
	s_add_i32 s41, s41, s6
	v_lshl_add_u64 v[214:215], s[22:23], 0, v[178:179]
	s_mov_b32 m0, s41
	ds_read_b128 v[160:163], v234 offset:16384
	ds_read_b128 v[186:189], v234 offset:17408
	ds_read_b128 v[190:193], v234 offset:18432
	ds_read_b128 v[194:197], v234 offset:19456
	ds_read_b128 v[198:201], v234 offset:20480
	ds_read_b128 v[202:205], v234 offset:21504
	ds_read_b128 v[206:209], v234 offset:22528
	ds_read_b128 v[210:213], v234 offset:23552
	global_load_lds_dwordx4 v[214:215], off
	s_add_i32 m0, s41, 0x2000
	s_add_u32 s42, s22, 0x40000
	v_lshl_add_u64 v[216:217], s[22:23], 0, v[174:175]
	s_addc_u32 s43, s23, 0
	s_add_i32 s41, s44, s6
	global_load_lds_dwordx4 v[216:217], off
	v_lshl_add_u64 v[218:219], s[42:43], 0, v[178:179]
	s_mov_b32 m0, s41
	v_lshl_add_u64 v[220:221], s[24:25], 0, v[176:177]
	global_load_lds_dwordx4 v[218:219], off
	v_lshl_add_u64 v[218:219], s[42:43], 0, v[174:175]
	s_add_i32 m0, s41, 0x2000
	s_nop 0
	global_load_lds_dwordx4 v[218:219], off
	v_lshl_add_u64 v[218:219], s[24:25], 0, v[180:181]
	s_mov_b32 m0, s7
	s_nop 0
	global_load_lds_dwordx4 v[218:219], off
	s_mov_b32 m0, s26
	s_nop 0
	global_load_lds_dwordx4 v[220:221], off
	s_waitcnt vmcnt(8)
	s_waitcnt lgkmcnt(0)
	s_barrier
; #define PG8_STAGE(bufoff, gbase, voff) do { _Pragma("unroll") for (int _i = 0; _i < 2; ++_i) \
;         __builtin_amdgcn_global_load_lds((const unsigned*)((const char*)(gbase) + (voff)[_i]), (PG8_LAS unsigned*)(lds + (bufoff) + ldsw + _i * 8192), 16, 0, 0); } while (0)
; #define PG8_LDA(dst, b, h) do { _Pragma("unroll") for (int m = 0; m < 4; ++m) _Pragma("unroll") for (int k = 0; k < 2; ++k) dst[m][k] = *(const PG8_LAS bf16x8*)(lds + PG8_SA(b, h) + aoff + m * 2048 + k * 1024); } while (0)
; #define PG8_LDB(dst, b, h) do { _Pragma("unroll") for (int n = 0; n < 2; ++n) _Pragma("unroll") for (int k = 0; k < 2; ++k) dst[n][k] = *(const PG8_LAS bf16x8*)(lds + PG8_SB(b, h) + boff + n * 2048 + k * 1024); } while (0)
; #define PG8_MMA(ai, bj, At, Bt) do { __builtin_amdgcn_s_setprio(1); _Pragma("unroll") for (int m = 0; m < 4; ++m) _Pragma("unroll") for (int n = 0; n < 2; ++n) _Pragma("unroll") for (int k = 0; k < 2; ++k) \
;         acc[ai][bj][m][n] = __builtin_amdgcn_mfma_f32_16x16x32_bf16(Bt[n][k], At[m][k], acc[ai][bj][m][n], 0, 0, 0); __builtin_amdgcn_s_setprio(0); } while (0)
; #define PG8_WAIT_V(n) asm volatile("s_waitcnt vmcnt(" #n ")" ::: "memory")
; #define PG8_WAIT_L(n) asm volatile("s_waitcnt lgkmcnt(" #n ")" ::: "memory")
; #define PG8_BAR __builtin_amdgcn_s_barrier()
; #define PG8_SCHED __builtin_amdgcn_sched_barrier(0)
; template <class Epi, class Sched, bool ALIGN_EPI, bool SP2, int KC>
; __device__ __forceinline__ void gemm_phase(PG8_LAS unsigned char* lds, const Gemm g, const Sched& S, const Epi& E, const int tid) {
;     ...
;             PG8_WAIT_V(8); PG8_WAIT_L(0); PG8_BAR; PG8_MMA(1, 0, At, B0); PG8_MMA(1, 1, At, B1); PG8_BAR; PG8_SCHED;
;             PG8_LDB(B0, 1, 0); PG8_LDB(B1, 1, 1); PG8_SCHED; PG8_LDA(At, 1, 0); PG8_STAGE(PG8_SA(0, 1), a2 + hstep, voffA);
;             PG8_WAIT_V(8); PG8_WAIT_L(0); PG8_BAR; PG8_MMA(0, 0, At, B0); PG8_MMA(0, 1, At, B1); PG8_BAR; PG8_SCHED;
	s_setprio 1
	s_waitcnt lgkmcnt(0)
	v_mfma_f32_16x16x32_bf16 v[92:95], v[128:131], v[160:163], v[92:95]
	v_mfma_f32_16x16x32_bf16 v[88:91], v[136:139], v[160:163], v[88:91]
	v_mfma_f32_16x16x32_bf16 v[84:87], v[128:131], v[190:193], v[84:87]
	v_mfma_f32_16x16x32_bf16 v[80:83], v[136:139], v[190:193], v[80:83]
	v_mfma_f32_16x16x32_bf16 v[76:79], v[128:131], v[198:201], v[76:79]
	v_mfma_f32_16x16x32_bf16 v[72:75], v[136:139], v[198:201], v[72:75]
	v_mfma_f32_16x16x32_bf16 v[64:67], v[128:131], v[206:209], v[64:67]
	v_mfma_f32_16x16x32_bf16 v[60:63], v[136:139], v[206:209], v[60:63]
	v_mfma_f32_16x16x32_bf16 v[92:95], v[132:135], v[186:189], v[92:95]
	v_mfma_f32_16x16x32_bf16 v[88:91], v[140:143], v[186:189], v[88:91]
	v_mfma_f32_16x16x32_bf16 v[84:87], v[132:135], v[194:197], v[84:87]
	v_mfma_f32_16x16x32_bf16 v[80:83], v[140:143], v[194:197], v[80:83]
	v_mfma_f32_16x16x32_bf16 v[76:79], v[132:135], v[202:205], v[76:79]
	v_mfma_f32_16x16x32_bf16 v[72:75], v[140:143], v[202:205], v[72:75]
	v_mfma_f32_16x16x32_bf16 v[64:67], v[132:135], v[210:213], v[64:67]
	v_mfma_f32_16x16x32_bf16 v[60:63], v[140:143], v[210:213], v[60:63]
	v_mfma_f32_16x16x32_bf16 v[28:31], v[144:147], v[160:163], v[28:31]
	v_mfma_f32_16x16x32_bf16 v[24:27], v[152:155], v[160:163], v[24:27]
	v_mfma_f32_16x16x32_bf16 v[20:23], v[144:147], v[190:193], v[20:23]
	v_mfma_f32_16x16x32_bf16 v[16:19], v[152:155], v[190:193], v[16:19]
	v_mfma_f32_16x16x32_bf16 v[12:15], v[144:147], v[198:201], v[12:15]
	v_mfma_f32_16x16x32_bf16 v[8:11], v[152:155], v[198:201], v[8:11]
	v_mfma_f32_16x16x32_bf16 v[4:7], v[144:147], v[206:209], v[4:7]
	v_mfma_f32_16x16x32_bf16 v[0:3], v[152:155], v[206:209], v[0:3]
	v_mfma_f32_16x16x32_bf16 v[28:31], v[148:151], v[186:189], v[28:31]
	v_mfma_f32_16x16x32_bf16 v[24:27], v[156:159], v[186:189], v[24:27]
	v_mfma_f32_16x16x32_bf16 v[20:23], v[148:151], v[194:197], v[20:23]
	v_mfma_f32_16x16x32_bf16 v[16:19], v[156:159], v[194:197], v[16:19]
	v_mfma_f32_16x16x32_bf16 v[12:15], v[148:151], v[202:205], v[12:15]
	v_mfma_f32_16x16x32_bf16 v[8:11], v[156:159], v[202:205], v[8:11]
	v_mfma_f32_16x16x32_bf16 v[4:7], v[148:151], v[210:213], v[4:7]
	v_mfma_f32_16x16x32_bf16 v[0:3], v[156:159], v[210:213], v[0:3]
	s_setprio 0
	s_barrier
	s_add_i32 s41, 0, 0x18000
	s_add_i32 s42, 0, 0x1c000
	v_add_u32_e32 v140, s41, v223
	v_add_u32_e32 v156, s42, v223
	ds_read_b128 v[128:131], v140
	ds_read_b128 v[132:135], v140 offset:1024
	ds_read_b128 v[136:139], v140 offset:2048
	ds_read_b128 v[140:143], v140 offset:3072
	ds_read_b128 v[144:147], v156
	ds_read_b128 v[148:151], v156 offset:1024
	ds_read_b128 v[152:155], v156 offset:2048
	ds_read_b128 v[156:159], v156 offset:3072
	s_add_u32 s24, s24, 0x40000
	s_addc_u32 s25, s25, 0
	s_mov_b32 m0, s27
	v_lshl_add_u64 v[236:237], s[24:25], 0, v[180:181]
	ds_read_b128 v[160:163], v234 offset:32768
	ds_read_b128 v[186:189], v234 offset:33792
	ds_read_b128 v[190:193], v234 offset:34816
	ds_read_b128 v[194:197], v234 offset:35840
	ds_read_b128 v[198:201], v234 offset:36864
	ds_read_b128 v[202:205], v234 offset:37888
	ds_read_b128 v[206:209], v234 offset:38912
	ds_read_b128 v[210:213], v234 offset:39936
	global_load_lds_dwordx4 v[236:237], off
	v_lshl_add_u64 v[236:237], s[24:25], 0, v[176:177]
	s_mov_b32 m0, s28
	s_nop 0
	global_load_lds_dwordx4 v[236:237], off
	s_waitcnt vmcnt(8)
	s_waitcnt lgkmcnt(0)
	s_barrier
	s_setprio 1
	s_waitcnt lgkmcnt(0)
	v_mfma_f32_16x16x32_bf16 v[124:127], v[128:131], v[160:163], v[124:127]
	v_mfma_f32_16x16x32_bf16 v[120:123], v[136:139], v[160:163], v[120:123]
	v_mfma_f32_16x16x32_bf16 v[116:119], v[128:131], v[190:193], v[116:119]
	v_mfma_f32_16x16x32_bf16 v[112:115], v[136:139], v[190:193], v[112:115]
	v_mfma_f32_16x16x32_bf16 v[108:111], v[128:131], v[198:201], v[108:111]
	v_mfma_f32_16x16x32_bf16 v[104:107], v[136:139], v[198:201], v[104:107]
	v_mfma_f32_16x16x32_bf16 v[100:103], v[128:131], v[206:209], v[100:103]
	v_mfma_f32_16x16x32_bf16 v[96:99], v[136:139], v[206:209], v[96:99]
	v_mfma_f32_16x16x32_bf16 v[124:127], v[132:135], v[186:189], v[124:127]
	v_mfma_f32_16x16x32_bf16 v[120:123], v[140:143], v[186:189], v[120:123]
	v_mfma_f32_16x16x32_bf16 v[116:119], v[132:135], v[194:197], v[116:119]
	v_mfma_f32_16x16x32_bf16 v[112:115], v[140:143], v[194:197], v[112:115]
	v_mfma_f32_16x16x32_bf16 v[108:111], v[132:135], v[202:205], v[108:111]
	v_mfma_f32_16x16x32_bf16 v[104:107], v[140:143], v[202:205], v[104:107]
	v_mfma_f32_16x16x32_bf16 v[100:103], v[132:135], v[210:213], v[100:103]
	v_mfma_f32_16x16x32_bf16 v[96:99], v[140:143], v[210:213], v[96:99]
	v_mfma_f32_16x16x32_bf16 v[68:71], v[144:147], v[160:163], v[68:71]
	v_mfma_f32_16x16x32_bf16 v[56:59], v[152:155], v[160:163], v[56:59]
	v_mfma_f32_16x16x32_bf16 v[52:55], v[144:147], v[190:193], v[52:55]
	v_mfma_f32_16x16x32_bf16 v[48:51], v[152:155], v[190:193], v[48:51]
	v_mfma_f32_16x16x32_bf16 v[44:47], v[144:147], v[198:201], v[44:47]
	v_mfma_f32_16x16x32_bf16 v[40:43], v[152:155], v[198:201], v[40:43]
	v_mfma_f32_16x16x32_bf16 v[36:39], v[144:147], v[206:209], v[36:39]
	v_mfma_f32_16x16x32_bf16 v[32:35], v[152:155], v[206:209], v[32:35]
	v_mfma_f32_16x16x32_bf16 v[68:71], v[148:151], v[186:189], v[68:71]
	v_mfma_f32_16x16x32_bf16 v[56:59], v[156:159], v[186:189], v[56:59]
	v_mfma_f32_16x16x32_bf16 v[52:55], v[148:151], v[194:197], v[52:55]
	v_mfma_f32_16x16x32_bf16 v[48:51], v[156:159], v[194:197], v[48:51]
	v_mfma_f32_16x16x32_bf16 v[44:47], v[148:151], v[202:205], v[44:47]
	v_mfma_f32_16x16x32_bf16 v[40:43], v[156:159], v[202:205], v[40:43]
	v_mfma_f32_16x16x32_bf16 v[36:39], v[148:151], v[210:213], v[36:39]
	v_mfma_f32_16x16x32_bf16 v[32:35], v[156:159], v[210:213], v[32:35]
	s_setprio 0
	s_barrier
; #define PG8_STAGE(bufoff, gbase, voff) do { _Pragma("unroll") for (int _i = 0; _i < 2; ++_i) \
;         __builtin_amdgcn_global_load_lds((const unsigned*)((const char*)(gbase) + (voff)[_i]), (PG8_LAS unsigned*)(lds + (bufoff) + ldsw + _i * 8192), 16, 0, 0); } while (0)
; #define PG8_LDA(dst, b, h) do { _Pragma("unroll") for (int m = 0; m < 4; ++m) _Pragma("unroll") for (int k = 0; k < 2; ++k) dst[m][k] = *(const PG8_LAS bf16x8*)(lds + PG8_SA(b, h) + aoff + m * 2048 + k * 1024); } while (0)
; #define PG8_MMA(ai, bj, At, Bt) do { __builtin_amdgcn_s_setprio(1); _Pragma("unroll") for (int m = 0; m < 4; ++m) _Pragma("unroll") for (int n = 0; n < 2; ++n) _Pragma("unroll") for (int k = 0; k < 2; ++k) \
;         acc[ai][bj][m][n] = __builtin_amdgcn_mfma_f32_16x16x32_bf16(Bt[n][k], At[m][k], acc[ai][bj][m][n], 0, 0, 0); __builtin_amdgcn_s_setprio(0); } while (0)
; #define PG8_WAIT_V(n) asm volatile("s_waitcnt vmcnt(" #n ")" ::: "memory")
; #define PG8_WAIT_L(n) asm volatile("s_waitcnt lgkmcnt(" #n ")" ::: "memory")
; #define PG8_BAR __builtin_amdgcn_s_barrier()
; #define PG8_SCHED __builtin_amdgcn_sched_barrier(0)
; template <class Epi, class Sched, bool ALIGN_EPI, bool SP2, int KC>
; __device__ __forceinline__ void gemm_phase(PG8_LAS unsigned char* lds, const Gemm g, const Sched& S, const Epi& E, const int tid) {
;     ...
;             PG8_LDA(At, 1, 1); PG8_STAGE(PG8_SB(1, 0), b3, voffB); PG8_STAGE(PG8_SB(1, 1), b3 + hstep, voffB); PG8_STAGE(PG8_SA(1, 0), a3, voffA);
;             PG8_WAIT_V(8); PG8_WAIT_L(0); PG8_BAR; PG8_MMA(1, 0, At, B0); PG8_MMA(1, 1, At, B1); PG8_BAR; PG8_SCHED;
	s_add_i32 s24, s41, s6
	v_lshl_add_u64 v[214:215], v[214:215], 0, s[86:87]
	s_mov_b32 m0, s24
	ds_read_b128 v[160:163], v234 offset:49152
	ds_read_b128 v[186:189], v234 offset:50176
	ds_read_b128 v[190:193], v234 offset:51200
	ds_read_b128 v[194:197], v234 offset:52224
	ds_read_b128 v[198:201], v234 offset:53248
	ds_read_b128 v[202:205], v234 offset:54272
	ds_read_b128 v[206:209], v234 offset:55296
	ds_read_b128 v[210:213], v234 offset:56320
	global_load_lds_dwordx4 v[214:215], off
	s_add_i32 m0, s24, 0x2000
	s_add_u32 s22, s22, 0x40080
	v_lshl_add_u64 v[214:215], v[216:217], 0, s[86:87]
	s_addc_u32 s23, s23, 0
	s_add_i32 s24, s42, s6
	global_load_lds_dwordx4 v[214:215], off
	v_lshl_add_u64 v[214:215], s[22:23], 0, v[178:179]
	s_mov_b32 m0, s24
	s_nop 0
	global_load_lds_dwordx4 v[214:215], off
	v_lshl_add_u64 v[214:215], s[22:23], 0, v[174:175]
	s_add_i32 m0, s24, 0x2000
	s_nop 0
	global_load_lds_dwordx4 v[214:215], off
	v_lshl_add_u64 v[214:215], v[218:219], 0, s[86:87]
	s_mov_b32 m0, s29
	s_nop 0
	global_load_lds_dwordx4 v[214:215], off
	v_lshl_add_u64 v[214:215], v[220:221], 0, s[86:87]
	s_mov_b32 m0, s30
	s_nop 0
	global_load_lds_dwordx4 v[214:215], off
	s_waitcnt vmcnt(8)
	s_waitcnt lgkmcnt(0)
	s_barrier
	s_setprio 1
	s_waitcnt lgkmcnt(0)
	v_mfma_f32_16x16x32_bf16 v[92:95], v[128:131], v[160:163], v[92:95]
	v_mfma_f32_16x16x32_bf16 v[88:91], v[136:139], v[160:163], v[88:91]
	v_mfma_f32_16x16x32_bf16 v[84:87], v[128:131], v[190:193], v[84:87]
	v_mfma_f32_16x16x32_bf16 v[80:83], v[136:139], v[190:193], v[80:83]
	v_mfma_f32_16x16x32_bf16 v[76:79], v[128:131], v[198:201], v[76:79]
	v_mfma_f32_16x16x32_bf16 v[72:75], v[136:139], v[198:201], v[72:75]
	v_mfma_f32_16x16x32_bf16 v[64:67], v[128:131], v[206:209], v[64:67]
	v_mfma_f32_16x16x32_bf16 v[60:63], v[136:139], v[206:209], v[60:63]
	v_mfma_f32_16x16x32_bf16 v[92:95], v[132:135], v[186:189], v[92:95]
	v_mfma_f32_16x16x32_bf16 v[88:91], v[140:143], v[186:189], v[88:91]
	v_mfma_f32_16x16x32_bf16 v[84:87], v[132:135], v[194:197], v[84:87]
	v_mfma_f32_16x16x32_bf16 v[80:83], v[140:143], v[194:197], v[80:83]
	v_mfma_f32_16x16x32_bf16 v[76:79], v[132:135], v[202:205], v[76:79]
	v_mfma_f32_16x16x32_bf16 v[72:75], v[140:143], v[202:205], v[72:75]
	v_mfma_f32_16x16x32_bf16 v[64:67], v[132:135], v[210:213], v[64:67]
	v_mfma_f32_16x16x32_bf16 v[60:63], v[140:143], v[210:213], v[60:63]
	v_mfma_f32_16x16x32_bf16 v[28:31], v[144:147], v[160:163], v[28:31]
	v_mfma_f32_16x16x32_bf16 v[24:27], v[152:155], v[160:163], v[24:27]
	v_mfma_f32_16x16x32_bf16 v[20:23], v[144:147], v[190:193], v[20:23]
	v_mfma_f32_16x16x32_bf16 v[16:19], v[152:155], v[190:193], v[16:19]
	v_mfma_f32_16x16x32_bf16 v[12:15], v[144:147], v[198:201], v[12:15]
	v_mfma_f32_16x16x32_bf16 v[8:11], v[152:155], v[198:201], v[8:11]
	v_mfma_f32_16x16x32_bf16 v[4:7], v[144:147], v[206:209], v[4:7]
	v_mfma_f32_16x16x32_bf16 v[0:3], v[152:155], v[206:209], v[0:3]
	v_mfma_f32_16x16x32_bf16 v[28:31], v[148:151], v[186:189], v[28:31]
	v_mfma_f32_16x16x32_bf16 v[24:27], v[156:159], v[186:189], v[24:27]
	v_mfma_f32_16x16x32_bf16 v[20:23], v[148:151], v[194:197], v[20:23]
	v_mfma_f32_16x16x32_bf16 v[16:19], v[156:159], v[194:197], v[16:19]
	v_mfma_f32_16x16x32_bf16 v[12:15], v[148:151], v[202:205], v[12:15]
	v_mfma_f32_16x16x32_bf16 v[8:11], v[156:159], v[202:205], v[8:11]
	v_mfma_f32_16x16x32_bf16 v[4:7], v[148:151], v[210:213], v[4:7]
	v_mfma_f32_16x16x32_bf16 v[0:3], v[156:159], v[210:213], v[0:3]
	s_setprio 0
	s_barrier
	s_add_i32 s40, s40, 2
	s_add_u32 s4, s4, 0x100
	s_addc_u32 s5, s5, 0
	s_add_u32 s38, s38, 0x100
	s_addc_u32 s39, s39, 0
	s_cmp_gt_u32 s40, 13
	s_cbranch_scc0 .LBB0_730
	s_and_b64 vcc, exec, s[12:13]
	s_cbranch_vccz .LBB0_733
	s_barrier
